# RWKV scan: single-chain sum over the 16 column groups (lanes 8-15 of a row keep their row pair swapped; 5 DPP per step instead of 8), loader writes the swapped v copy into the unused row half's slot
# baseline (speedup 1.0000x reference)
.LBB0_702:
	s_or_b64 exec, exec, s[8:9]
	v_ashrrev_i32_e32 v57, 6, v56
	s_lshl_b32 s8, s2, 5
	v_lshlrev_b32_e32 v21, 3, v57
	v_lshrrev_b32_e32 v56, 3, v54
	s_and_b32 s8, s8, 32
	v_and_b32_e32 v21, 24, v21
	v_and_b32_e32 v56, 6, v56
	v_and_b32_e32 v66, 15, v54
	v_or3_b32 v54, v56, s8, v21
	v_mov_b32_e32 v56, 0
	v_mov_b32_e32 v21, v56
	v_lshl_add_u64 v[58:59], s[12:13], 0, v[20:21]
	v_lshl_add_u64 v[60:61], s[10:11], 0, v[20:21]
	v_lshl_add_u64 v[62:63], s[14:15], 0, v[20:21]
	v_lshlrev_b32_e32 v20, 1, v54
	s_mov_b32 s71, 0
	v_lshl_add_u64 v[20:21], s[46:47], 0, v[20:21]
	s_lshl_b32 s70, s20, 1
	v_lshl_add_u64 v[20:21], v[20:21], 0, s[70:71]
	s_mov_b64 s[12:13], 0xbae4800
	v_lshlrev_b32_e32 v76, 2, v66
	v_cmp_gt_i32_e64 s[8:9], 4, v57
	v_or_b32_e32 v77, s6, v66
	v_lshl_add_u64 v[64:65], v[20:21], 0, s[12:13]
	v_and_b32_e32 v72, 3, v66
	v_cmp_eq_u32_e64 s[12:13], 0, v72
	v_cmp_eq_u32_e64 s[14:15], 1, v72
	v_cmp_eq_u32_e64 s[16:17], 2, v72
	s_movk_i32 s49, 0x1e00
	s_add_i32 s55, 0, 0xc000
	v_mov_b32_e32 v66, 0
	v_mov_b32_e32 v67, v56
	v_mov_b32_e32 v20, v56
	v_mov_b32_e32 v21, v56
	v_mov_b32_e32 v68, v56
	v_mov_b32_e32 v69, v56
	v_mov_b32_e32 v70, v56
	v_mov_b32_e32 v71, v56
	s_add_u32 s18, s46, 0x3d44800
	s_addc_u32 s19, s47, 0
	s_sub_u32 s20, s18, 0x1e00
	s_subb_u32 s21, s19, 0
	s_add_u32 s22, s46, 0xda04800
	s_addc_u32 s23, s47, 0
	s_add_u32 s24, s46, 0xea84800
	s_addc_u32 s25, s47, 0
	s_bfe_u32 s26, s2, 0x30001
	s_lshl_b32 s26, s26, 7
	v_lshrrev_b32_e32 v123, 1, v75
	v_add_u32_e32 v123, s26, v123
	v_mul_u32_u24_e32 v121, 0x3c00, v55
	v_add_u32_e32 v121, v121, v123
	v_lshl_add_u32 v122, v55, 11, v123
	v_lshl_add_u32 v123, v74, 1, v75
	v_sub_f32_e32 v168, 1.0, v16
	v_sub_f32_e32 v169, 1.0, v17
	v_sub_f32_e32 v170, 1.0, v18
	v_sub_f32_e32 v171, 1.0, v19
	s_and_b32 s26, s2, 1
	s_xor_b32 s26, s26, 1
	v_bfe_u32 v176, v75, 7, 1
	v_xor_b32_e32 v176, s26, v176
	v_xor_b32_e32 v177, 0x80, v123
	s_waitcnt lgkmcnt(0)
	s_barrier
	s_cmp_lt_u32 s33, 0x100
	s_cbranch_scc1 .Lld_noprefetch
	ds_read_b128 v[178:181], v123 offset:1280
	s_waitcnt lgkmcnt(0)
	v_mov_b32_e32 v172, v179
	v_mov_b32_e32 v173, v178
	v_mov_b32_e32 v174, v181
	v_mov_b32_e32 v175, v180
	v_cmp_ne_u32_e32 vcc, 0, v176
	s_and_saveexec_b64 s[26:27], vcc
	ds_write_b128 v177, v[172:175] offset:1280
	s_mov_b64 exec, s[26:27]
	ds_read_b128 v[178:181], v123 offset:2816
	s_waitcnt lgkmcnt(0)
	v_mov_b32_e32 v172, v179
	v_mov_b32_e32 v173, v178
	v_mov_b32_e32 v174, v181
	v_mov_b32_e32 v175, v180
	v_cmp_ne_u32_e32 vcc, 0, v176
	s_and_saveexec_b64 s[26:27], vcc
	ds_write_b128 v177, v[172:175] offset:2816
	s_mov_b64 exec, s[26:27]
	s_mov_b32 s29, 1
	s_lshl_b32 s26, s29, 5
	s_add_i32 s26, s26, s6
	s_mul_i32 s98, s26, 0x1e00
	s_lshl_b32 s100, s26, 10
	s_add_u32 s26, s20, s98
	s_addc_u32 s27, s21, 0
	s_add_u32 s28, s24, s100
	s_addc_u32 s29, s25, 0
	s_add_u32 s98, s18, s98
	s_addc_u32 s99, s19, 0
	s_add_u32 s100, s22, s100
	s_addc_u32 s101, s23, 0
	global_load_dwordx2 v[124:125], v121, s[98:99]
	global_load_dwordx2 v[126:127], v121, s[98:99] offset:1024
	global_load_dwordx2 v[128:129], v121, s[98:99] offset:2048
	global_load_dwordx2 v[130:131], v121, s[26:27]
	global_load_dwordx2 v[132:133], v121, s[26:27] offset:1024
	global_load_dwordx2 v[134:135], v121, s[26:27] offset:2048
	global_load_dwordx2 v[136:137], v122, s[100:101]
	global_load_dwordx2 v[138:139], v122, s[28:29]
	s_add_u32 s98, s98, 0x1e00
	s_addc_u32 s99, s99, 0
	s_add_u32 s100, s100, 0x400
	s_addc_u32 s101, s101, 0
	s_add_u32 s28, s28, 0x400
	s_addc_u32 s29, s29, 0
	global_load_dwordx2 v[140:141], v121, s[98:99]
	global_load_dwordx2 v[142:143], v121, s[98:99] offset:1024
	global_load_dwordx2 v[144:145], v121, s[98:99] offset:2048
	global_load_dwordx2 v[152:153], v122, s[100:101]
	global_load_dwordx2 v[154:155], v122, s[28:29]

.Lld_go_even:
	v_lshlrev_b32_e32 v156, 16, v124
	v_and_b32_e32 v157, 0xffff0000, v124
	v_lshlrev_b32_e32 v158, 16, v125
	v_and_b32_e32 v159, 0xffff0000, v125
	v_lshlrev_b32_e32 v108, 16, v130
	v_and_b32_e32 v109, 0xffff0000, v130
	v_lshlrev_b32_e32 v110, 16, v131
	v_and_b32_e32 v111, 0xffff0000, v131
	v_pk_add_f32 v[108:109], v[108:109], v[156:157] neg_lo:[0,1] neg_hi:[0,1]
	v_pk_add_f32 v[110:111], v[110:111], v[158:159] neg_lo:[0,1] neg_hi:[0,1]
	v_pk_fma_f32 v[84:85], v[0:1], v[108:109], v[156:157]
	v_pk_fma_f32 v[86:87], v[2:3], v[110:111], v[158:159]
	v_lshlrev_b32_e32 v160, 16, v126
	v_and_b32_e32 v161, 0xffff0000, v126
	v_lshlrev_b32_e32 v162, 16, v127
	v_and_b32_e32 v163, 0xffff0000, v127
	v_lshlrev_b32_e32 v108, 16, v132
	v_and_b32_e32 v109, 0xffff0000, v132
	v_lshlrev_b32_e32 v110, 16, v133
	v_and_b32_e32 v111, 0xffff0000, v133
	v_pk_add_f32 v[108:109], v[108:109], v[160:161] neg_lo:[0,1] neg_hi:[0,1]
	v_pk_add_f32 v[110:111], v[110:111], v[162:163] neg_lo:[0,1] neg_hi:[0,1]
	v_pk_fma_f32 v[88:89], v[12:13], v[108:109], v[160:161]
	v_pk_fma_f32 v[90:91], v[14:15], v[110:111], v[162:163]
	v_lshlrev_b32_e32 v164, 16, v128
	v_and_b32_e32 v165, 0xffff0000, v128
	v_lshlrev_b32_e32 v166, 16, v129
	v_and_b32_e32 v167, 0xffff0000, v129
	v_lshlrev_b32_e32 v108, 16, v134
	v_and_b32_e32 v109, 0xffff0000, v134
	v_lshlrev_b32_e32 v110, 16, v135
	v_and_b32_e32 v111, 0xffff0000, v135
	v_pk_add_f32 v[108:109], v[108:109], v[164:165] neg_lo:[0,1] neg_hi:[0,1]
	v_pk_add_f32 v[110:111], v[110:111], v[166:167] neg_lo:[0,1] neg_hi:[0,1]
	v_pk_fma_f32 v[92:93], v[4:5], v[108:109], v[164:165]
	v_pk_fma_f32 v[94:95], v[6:7], v[110:111], v[166:167]
	v_lshlrev_b32_e32 v96, 16, v136
	v_and_b32_e32 v97, 0xffff0000, v136
	v_lshlrev_b32_e32 v98, 16, v137
	v_and_b32_e32 v99, 0xffff0000, v137
	v_lshlrev_b32_e32 v100, 16, v138
	v_and_b32_e32 v101, 0xffff0000, v138
	v_lshlrev_b32_e32 v102, 16, v139
	v_and_b32_e32 v103, 0xffff0000, v139
	v_pk_mul_f32 v[112:113], v[8:9], v[88:89]
	v_pk_mul_f32 v[114:115], v[10:11], v[90:91]
	v_pk_mul_f32 v[104:105], v[112:113], v[112:113]
	v_pk_fma_f32 v[104:105], v[114:115], v[114:115], v[104:105]
	v_add_f32_e32 v104, v104, v105
	v_pk_fma_f32 v[116:117], v[100:101], v[16:17], v[168:169]
	v_pk_fma_f32 v[118:119], v[102:103], v[18:19], v[170:171]
	v_add_f32_dpp v104, v104, v104 quad_perm:[1,0,3,2] row_mask:0xf bank_mask:0xf bound_ctrl:1
	v_pk_mul_f32 v[116:117], v[116:117], v[88:89]
	v_pk_mul_f32 v[118:119], v[118:119], v[90:91]
	v_add_f32_dpp v104, v104, v104 quad_perm:[2,3,0,1] row_mask:0xf bank_mask:0xf bound_ctrl:1
	ds_write_b128 v123, v[84:87] offset:49152
	ds_write_b128 v123, v[96:99] offset:49408
	v_add_f32_dpp v104, v104, v104 row_half_mirror row_mask:0xf bank_mask:0xf bound_ctrl:1
	ds_write_b128 v123, v[116:119] offset:49664
	ds_write_b128 v123, v[92:95] offset:50432
	v_add_f32_dpp v104, v104, v104 row_mirror row_mask:0xf bank_mask:0xf bound_ctrl:1
	v_rsq_f32_e32 v104, v104
	s_nop 0
	v_min_f32_e32 v104, 0x5368d4a5, v104
	v_pk_mul_f32 v[112:113], v[112:113], v[104:105] op_sel_hi:[1,0] neg_lo:[0,1] neg_hi:[0,1]
	v_pk_mul_f32 v[114:115], v[114:115], v[104:105] op_sel_hi:[1,0] neg_lo:[0,1] neg_hi:[0,1]
	ds_write_b128 v123, v[112:115] offset:49920
	v_pk_mul_f32 v[108:109], v[112:113], v[100:101] neg_lo:[1,0] neg_hi:[1,0]
	v_pk_mul_f32 v[110:111], v[114:115], v[102:103] neg_lo:[1,0] neg_hi:[1,0]
	ds_write_b128 v123, v[108:111] offset:50176
	v_mov_b32_e32 v172, v93
	v_mov_b32_e32 v173, v92
	v_mov_b32_e32 v174, v95
	v_mov_b32_e32 v175, v94
	v_cmp_ne_u32_e32 vcc, 0, v176
	s_and_saveexec_b64 s[26:27], vcc
	ds_write_b128 v177, v[172:175] offset:50432
	s_mov_b64 exec, s[26:27]
	v_lshlrev_b32_e32 v104, 16, v140
	v_and_b32_e32 v105, 0xffff0000, v140
	v_lshlrev_b32_e32 v106, 16, v141
	v_and_b32_e32 v107, 0xffff0000, v141
	v_pk_add_f32 v[108:109], v[156:157], v[104:105] neg_lo:[0,1] neg_hi:[0,1]
	v_pk_add_f32 v[110:111], v[158:159], v[106:107] neg_lo:[0,1] neg_hi:[0,1]
	v_pk_fma_f32 v[84:85], v[0:1], v[108:109], v[104:105]
	v_pk_fma_f32 v[86:87], v[2:3], v[110:111], v[106:107]
	v_lshlrev_b32_e32 v104, 16, v142
	v_and_b32_e32 v105, 0xffff0000, v142
	v_lshlrev_b32_e32 v106, 16, v143
	v_and_b32_e32 v107, 0xffff0000, v143
	v_pk_add_f32 v[108:109], v[160:161], v[104:105] neg_lo:[0,1] neg_hi:[0,1]
	v_pk_add_f32 v[110:111], v[162:163], v[106:107] neg_lo:[0,1] neg_hi:[0,1]
	v_pk_fma_f32 v[88:89], v[12:13], v[108:109], v[104:105]
	v_pk_fma_f32 v[90:91], v[14:15], v[110:111], v[106:107]
	v_lshlrev_b32_e32 v104, 16, v144
	v_and_b32_e32 v105, 0xffff0000, v144
	v_lshlrev_b32_e32 v106, 16, v145
	v_and_b32_e32 v107, 0xffff0000, v145
	v_pk_add_f32 v[108:109], v[164:165], v[104:105] neg_lo:[0,1] neg_hi:[0,1]
	v_pk_add_f32 v[110:111], v[166:167], v[106:107] neg_lo:[0,1] neg_hi:[0,1]
	v_pk_fma_f32 v[92:93], v[4:5], v[108:109], v[104:105]
	v_pk_fma_f32 v[94:95], v[6:7], v[110:111], v[106:107]
	v_lshlrev_b32_e32 v96, 16, v152
	v_and_b32_e32 v97, 0xffff0000, v152
	v_lshlrev_b32_e32 v98, 16, v153
	v_and_b32_e32 v99, 0xffff0000, v153
	v_lshlrev_b32_e32 v100, 16, v154
	v_and_b32_e32 v101, 0xffff0000, v154
	v_lshlrev_b32_e32 v102, 16, v155
	v_and_b32_e32 v103, 0xffff0000, v155
	v_pk_mul_f32 v[112:113], v[8:9], v[88:89]
	v_pk_mul_f32 v[114:115], v[10:11], v[90:91]
	v_pk_mul_f32 v[104:105], v[112:113], v[112:113]
	v_pk_fma_f32 v[104:105], v[114:115], v[114:115], v[104:105]
	v_add_f32_e32 v104, v104, v105
	v_pk_fma_f32 v[116:117], v[100:101], v[16:17], v[168:169]
	v_pk_fma_f32 v[118:119], v[102:103], v[18:19], v[170:171]
	v_add_f32_dpp v104, v104, v104 quad_perm:[1,0,3,2] row_mask:0xf bank_mask:0xf bound_ctrl:1
	v_pk_mul_f32 v[116:117], v[116:117], v[88:89]
	v_pk_mul_f32 v[118:119], v[118:119], v[90:91]
	v_add_f32_dpp v104, v104, v104 quad_perm:[2,3,0,1] row_mask:0xf bank_mask:0xf bound_ctrl:1
	ds_write_b128 v123, v[84:87] offset:50688
	ds_write_b128 v123, v[96:99] offset:50944
	v_add_f32_dpp v104, v104, v104 row_half_mirror row_mask:0xf bank_mask:0xf bound_ctrl:1
	ds_write_b128 v123, v[116:119] offset:51200
	ds_write_b128 v123, v[92:95] offset:51968
	v_add_f32_dpp v104, v104, v104 row_mirror row_mask:0xf bank_mask:0xf bound_ctrl:1
	v_rsq_f32_e32 v104, v104
	s_nop 0
	v_min_f32_e32 v104, 0x5368d4a5, v104
	v_pk_mul_f32 v[112:113], v[112:113], v[104:105] op_sel_hi:[1,0] neg_lo:[0,1] neg_hi:[0,1]
	v_pk_mul_f32 v[114:115], v[114:115], v[104:105] op_sel_hi:[1,0] neg_lo:[0,1] neg_hi:[0,1]
	ds_write_b128 v123, v[112:115] offset:51456
	v_pk_mul_f32 v[108:109], v[112:113], v[100:101] neg_lo:[1,0] neg_hi:[1,0]
	v_pk_mul_f32 v[110:111], v[114:115], v[102:103] neg_lo:[1,0] neg_hi:[1,0]
	ds_write_b128 v123, v[108:111] offset:51712
	v_mov_b32_e32 v172, v93
	v_mov_b32_e32 v173, v92
	v_mov_b32_e32 v174, v95
	v_mov_b32_e32 v175, v94
	v_cmp_ne_u32_e32 vcc, 0, v176
	s_and_saveexec_b64 s[26:27], vcc
	ds_write_b128 v177, v[172:175] offset:51968
	s_mov_b64 exec, s[26:27]
	s_branch .LBB0_704

.Lld_go_odd:
	v_lshlrev_b32_e32 v156, 16, v22
	v_and_b32_e32 v157, 0xffff0000, v22
	v_lshlrev_b32_e32 v158, 16, v23
	v_and_b32_e32 v159, 0xffff0000, v23
	v_lshlrev_b32_e32 v108, 16, v28
	v_and_b32_e32 v109, 0xffff0000, v28
	v_lshlrev_b32_e32 v110, 16, v29
	v_and_b32_e32 v111, 0xffff0000, v29
	v_pk_add_f32 v[108:109], v[108:109], v[156:157] neg_lo:[0,1] neg_hi:[0,1]
	v_pk_add_f32 v[110:111], v[110:111], v[158:159] neg_lo:[0,1] neg_hi:[0,1]
	v_pk_fma_f32 v[84:85], v[0:1], v[108:109], v[156:157]
	v_pk_fma_f32 v[86:87], v[2:3], v[110:111], v[158:159]
	v_lshlrev_b32_e32 v160, 16, v24
	v_and_b32_e32 v161, 0xffff0000, v24
	v_lshlrev_b32_e32 v162, 16, v25
	v_and_b32_e32 v163, 0xffff0000, v25
	v_lshlrev_b32_e32 v108, 16, v30
	v_and_b32_e32 v109, 0xffff0000, v30
	v_lshlrev_b32_e32 v110, 16, v31
	v_and_b32_e32 v111, 0xffff0000, v31
	v_pk_add_f32 v[108:109], v[108:109], v[160:161] neg_lo:[0,1] neg_hi:[0,1]
	v_pk_add_f32 v[110:111], v[110:111], v[162:163] neg_lo:[0,1] neg_hi:[0,1]
	v_pk_fma_f32 v[88:89], v[12:13], v[108:109], v[160:161]
	v_pk_fma_f32 v[90:91], v[14:15], v[110:111], v[162:163]
	v_lshlrev_b32_e32 v164, 16, v26
	v_and_b32_e32 v165, 0xffff0000, v26
	v_lshlrev_b32_e32 v166, 16, v27
	v_and_b32_e32 v167, 0xffff0000, v27
	v_lshlrev_b32_e32 v108, 16, v32
	v_and_b32_e32 v109, 0xffff0000, v32
	v_lshlrev_b32_e32 v110, 16, v33
	v_and_b32_e32 v111, 0xffff0000, v33
	v_pk_add_f32 v[108:109], v[108:109], v[164:165] neg_lo:[0,1] neg_hi:[0,1]
	v_pk_add_f32 v[110:111], v[110:111], v[166:167] neg_lo:[0,1] neg_hi:[0,1]
	v_pk_fma_f32 v[92:93], v[4:5], v[108:109], v[164:165]
	v_pk_fma_f32 v[94:95], v[6:7], v[110:111], v[166:167]
	v_lshlrev_b32_e32 v96, 16, v34
	v_and_b32_e32 v97, 0xffff0000, v34
	v_lshlrev_b32_e32 v98, 16, v35
	v_and_b32_e32 v99, 0xffff0000, v35
	v_lshlrev_b32_e32 v100, 16, v36
	v_and_b32_e32 v101, 0xffff0000, v36
	v_lshlrev_b32_e32 v102, 16, v37
	v_and_b32_e32 v103, 0xffff0000, v37
	v_pk_mul_f32 v[112:113], v[8:9], v[88:89]
	v_pk_mul_f32 v[114:115], v[10:11], v[90:91]
	v_pk_mul_f32 v[104:105], v[112:113], v[112:113]
	v_pk_fma_f32 v[104:105], v[114:115], v[114:115], v[104:105]
	v_add_f32_e32 v104, v104, v105
	v_pk_fma_f32 v[116:117], v[100:101], v[16:17], v[168:169]
	v_pk_fma_f32 v[118:119], v[102:103], v[18:19], v[170:171]
	v_add_f32_dpp v104, v104, v104 quad_perm:[1,0,3,2] row_mask:0xf bank_mask:0xf bound_ctrl:1
	v_pk_mul_f32 v[116:117], v[116:117], v[88:89]
	v_pk_mul_f32 v[118:119], v[118:119], v[90:91]
	v_add_f32_dpp v104, v104, v104 quad_perm:[2,3,0,1] row_mask:0xf bank_mask:0xf bound_ctrl:1
	ds_write_b128 v123, v[84:87] offset:0
	ds_write_b128 v123, v[96:99] offset:256
	v_add_f32_dpp v104, v104, v104 row_half_mirror row_mask:0xf bank_mask:0xf bound_ctrl:1
	ds_write_b128 v123, v[116:119] offset:512
	ds_write_b128 v123, v[92:95] offset:1280
	v_add_f32_dpp v104, v104, v104 row_mirror row_mask:0xf bank_mask:0xf bound_ctrl:1
	v_rsq_f32_e32 v104, v104
	s_nop 0
	v_min_f32_e32 v104, 0x5368d4a5, v104
	v_pk_mul_f32 v[112:113], v[112:113], v[104:105] op_sel_hi:[1,0] neg_lo:[0,1] neg_hi:[0,1]
	v_pk_mul_f32 v[114:115], v[114:115], v[104:105] op_sel_hi:[1,0] neg_lo:[0,1] neg_hi:[0,1]
	ds_write_b128 v123, v[112:115] offset:768
	v_pk_mul_f32 v[108:109], v[112:113], v[100:101] neg_lo:[1,0] neg_hi:[1,0]
	v_pk_mul_f32 v[110:111], v[114:115], v[102:103] neg_lo:[1,0] neg_hi:[1,0]
	ds_write_b128 v123, v[108:111] offset:1024
	v_mov_b32_e32 v172, v93
	v_mov_b32_e32 v173, v92
	v_mov_b32_e32 v174, v95
	v_mov_b32_e32 v175, v94
	v_cmp_ne_u32_e32 vcc, 0, v176
	s_and_saveexec_b64 s[26:27], vcc
	ds_write_b128 v177, v[172:175] offset:1280
	s_mov_b64 exec, s[26:27]
	v_lshlrev_b32_e32 v104, 16, v38
	v_and_b32_e32 v105, 0xffff0000, v38
	v_lshlrev_b32_e32 v106, 16, v39
	v_and_b32_e32 v107, 0xffff0000, v39
	v_pk_add_f32 v[108:109], v[156:157], v[104:105] neg_lo:[0,1] neg_hi:[0,1]
	v_pk_add_f32 v[110:111], v[158:159], v[106:107] neg_lo:[0,1] neg_hi:[0,1]
	v_pk_fma_f32 v[84:85], v[0:1], v[108:109], v[104:105]
	v_pk_fma_f32 v[86:87], v[2:3], v[110:111], v[106:107]
	v_lshlrev_b32_e32 v104, 16, v40
	v_and_b32_e32 v105, 0xffff0000, v40
	v_lshlrev_b32_e32 v106, 16, v41
	v_and_b32_e32 v107, 0xffff0000, v41
	v_pk_add_f32 v[108:109], v[160:161], v[104:105] neg_lo:[0,1] neg_hi:[0,1]
	v_pk_add_f32 v[110:111], v[162:163], v[106:107] neg_lo:[0,1] neg_hi:[0,1]
	v_pk_fma_f32 v[88:89], v[12:13], v[108:109], v[104:105]
	v_pk_fma_f32 v[90:91], v[14:15], v[110:111], v[106:107]
	v_lshlrev_b32_e32 v104, 16, v42
	v_and_b32_e32 v105, 0xffff0000, v42
	v_lshlrev_b32_e32 v106, 16, v43
	v_and_b32_e32 v107, 0xffff0000, v43
	v_pk_add_f32 v[108:109], v[164:165], v[104:105] neg_lo:[0,1] neg_hi:[0,1]
	v_pk_add_f32 v[110:111], v[166:167], v[106:107] neg_lo:[0,1] neg_hi:[0,1]
	v_pk_fma_f32 v[92:93], v[4:5], v[108:109], v[104:105]
	v_pk_fma_f32 v[94:95], v[6:7], v[110:111], v[106:107]
	v_lshlrev_b32_e32 v96, 16, v50
	v_and_b32_e32 v97, 0xffff0000, v50
	v_lshlrev_b32_e32 v98, 16, v51
	v_and_b32_e32 v99, 0xffff0000, v51
	v_lshlrev_b32_e32 v100, 16, v52
	v_and_b32_e32 v101, 0xffff0000, v52
	v_lshlrev_b32_e32 v102, 16, v53
	v_and_b32_e32 v103, 0xffff0000, v53
	v_pk_mul_f32 v[112:113], v[8:9], v[88:89]
	v_pk_mul_f32 v[114:115], v[10:11], v[90:91]
	v_pk_mul_f32 v[104:105], v[112:113], v[112:113]
	v_pk_fma_f32 v[104:105], v[114:115], v[114:115], v[104:105]
	v_add_f32_e32 v104, v104, v105
	v_pk_fma_f32 v[116:117], v[100:101], v[16:17], v[168:169]
	v_pk_fma_f32 v[118:119], v[102:103], v[18:19], v[170:171]
	v_add_f32_dpp v104, v104, v104 quad_perm:[1,0,3,2] row_mask:0xf bank_mask:0xf bound_ctrl:1
	v_pk_mul_f32 v[116:117], v[116:117], v[88:89]
	v_pk_mul_f32 v[118:119], v[118:119], v[90:91]
	v_add_f32_dpp v104, v104, v104 quad_perm:[2,3,0,1] row_mask:0xf bank_mask:0xf bound_ctrl:1
	ds_write_b128 v123, v[84:87] offset:1536
	ds_write_b128 v123, v[96:99] offset:1792
	v_add_f32_dpp v104, v104, v104 row_half_mirror row_mask:0xf bank_mask:0xf bound_ctrl:1
	ds_write_b128 v123, v[116:119] offset:2048
	ds_write_b128 v123, v[92:95] offset:2816
	v_add_f32_dpp v104, v104, v104 row_mirror row_mask:0xf bank_mask:0xf bound_ctrl:1
	v_rsq_f32_e32 v104, v104
	s_nop 0
	v_min_f32_e32 v104, 0x5368d4a5, v104
	v_pk_mul_f32 v[112:113], v[112:113], v[104:105] op_sel_hi:[1,0] neg_lo:[0,1] neg_hi:[0,1]
	v_pk_mul_f32 v[114:115], v[114:115], v[104:105] op_sel_hi:[1,0] neg_lo:[0,1] neg_hi:[0,1]
	ds_write_b128 v123, v[112:115] offset:2304
	v_pk_mul_f32 v[108:109], v[112:113], v[100:101] neg_lo:[1,0] neg_hi:[1,0]
	v_pk_mul_f32 v[110:111], v[114:115], v[102:103] neg_lo:[1,0] neg_hi:[1,0]
	ds_write_b128 v123, v[108:111] offset:2560
	v_mov_b32_e32 v172, v93
	v_mov_b32_e32 v173, v92
	v_mov_b32_e32 v174, v95
	v_mov_b32_e32 v175, v94
	v_cmp_ne_u32_e32 vcc, 0, v176
	s_and_saveexec_b64 s[26:27], vcc
	ds_write_b128 v177, v[172:175] offset:2816
	s_mov_b64 exec, s[26:27]
	s_branch .LBB0_704
; __device__ __forceinline__ unsigned cvt_pk_bf16(float lo, float hi) { const f32x2_t v = {lo, hi}; const bf16x2_t b = __builtin_convertvector(v, bf16x2_t); return __builtin_bit_cast(unsigned, b); }
; #define LAS __attribute__((address_space(3)))
; template <bool SAMPLE>
; __device__ __forceinline__ void rwkv_unit(PR P, LAS float* lds, const int b, const int h, const int half, const int wv) {
;     ...
;             for (int g = 0; g < TC / GS; ++g) {
;                 float yk0 = 0.f, yk1 = 0.f;
;                 const LAS float* q0 = cur + (g * GS) * 384;
;                 f32x4 r4 = *(const LAS f32x4*)(q0 + j0), o4 = *(const LAS f32x4*)(q0 + 64 + j0), k4 = *(const LAS f32x4*)(q0 + 128 + j0), a4 = *(const LAS f32x4*)(q0 + 192 + j0), b4 = *(const LAS f32x4*)(q0 + 256 + j0);
;                 f32x2 v2 = *(const LAS f32x2*)(q0 + 320 + row0);
;                 float py0 = 0.f, py1 = 0.f;
; #pragma unroll
;                 for (int tt = 0; tt < GS; ++tt) {
;                     const LAS float* qn = q0 + (tt + 1 < GS ? tt + 1 : tt) * 384;
;                     const f32x4 nr4 = *(const LAS f32x4*)(qn + j0), no4 = *(const LAS f32x4*)(qn + 64 + j0), nk4 = *(const LAS f32x4*)(qn + 128 + j0), na4 = *(const LAS f32x4*)(qn + 192 + j0), nb4 = *(const LAS f32x4*)(qn + 256 + j0);
;                     const f32x2 nv2 = *(const LAS f32x2*)(qn + 320 + row0);
;                     f32x2 sa = (S[0] * a4[0] + S[1] * a4[1]) + (S[2] * a4[2] + S[3] * a4[3]);
;                     float sx = sa.x, sy = sa.y; ROW16_SUM4(sx, sy, py0, py1); sa = (f32x2){sx, sy};
;                     if (tt > 0) { yk0 = cgl == tt - 1 ? py0 : yk0; yk1 = cgl == tt - 1 ? py1 : yk1; }
; #pragma unroll
;                     for (int c = 0; c < 4; ++c) { f32x2 t = S[c] - S[c] * o4[c]; t = t + sa * b4[c]; S[c] = t + v2 * k4[c]; }
;                     const f32x2 y = (S[0] * r4[0] + S[1] * r4[1]) + (S[2] * r4[2] + S[3] * r4[3]);
;                     py0 = y.x; py1 = y.y;
;                     r4 = nr4; o4 = no4; k4 = nk4; a4 = na4; b4 = nb4; v2 = nv2;
;                 }
;                 ROW16_SUM2(py0, py1); yk0 = cgl == GS - 1 ? py0 : yk0; yk1 = cgl == GS - 1 ? py1 : yk1;
;                 if (cgl < GS) *(unsigned*)(YS + (size_t)(row_base + c * TC + g * GS + cgl) * 512 + h * 64 + row0) = pg8::cvt_pk_bf16(yk0, yk1);
.Lrw_scan_chunk:
	s_add_i32 s56, s71, 1
	s_bitcmp0_b32 s71, 0
	s_cselect_b32 s57, 0, s55
	v_lshl_add_u32 v57, s71, 5, v77
	.p2alignl 3, 3212836864
	v_lshl_add_u32 v152, v76, 2, s57
	v_lshl_add_u32 v153, v54, 2, s57
	v_add_u32_e32 v153, 0x100, v153
	s_mov_b32 s98, 0xff00ff00
	s_mov_b32 s99, 0xff00ff00
	v_xor_b32_e32 v156, 0x80, v153
	v_cndmask_b32_e64 v153, v153, v156, s[98:99]
	ds_read_b128 v[172:175], v152 offset:768
	ds_read_b128 v[164:167], v152 offset:256
	ds_read2st64_b64 v[240:243], v153 offset0:2 offset1:5
	ds_read_b128 v[168:171], v152 offset:512
	ds_read_b128 v[192:195], v152 offset:2304
	ds_read_b128 v[184:187], v152 offset:1792
	ds_read_b128 v[176:179], v152 offset:1024
	ds_read_b128 v[188:191], v152 offset:2048
	ds_read_b128 v[196:199], v152 offset:2560
	ds_read_b128 v[160:163], v152 offset:0
	ds_read_b128 v[180:183], v152 offset:1536
	s_cmp_eq_u32 s71, 0
	s_cbranch_scc1 .Lrw_first_chunk
	v_add_f32_dpp v110, v111, v110 row_ror:8 row_mask:0xf bank_mask:0x3 bound_ctrl:1
	v_add_f32_dpp v112, v113, v112 row_ror:8 row_mask:0xf bank_mask:0x3 bound_ctrl:1
	v_add_f32_dpp v114, v115, v114 row_ror:8 row_mask:0xf bank_mask:0x3 bound_ctrl:1
	v_add_f32_dpp v116, v117, v116 row_ror:8 row_mask:0xf bank_mask:0x3 bound_ctrl:1
	v_add_f32_dpp v118, v119, v118 row_ror:8 row_mask:0xf bank_mask:0x3 bound_ctrl:1
	v_add_f32_dpp v120, v121, v120 row_ror:8 row_mask:0xf bank_mask:0x3 bound_ctrl:1
	v_add_f32_dpp v122, v123, v122 row_ror:8 row_mask:0xf bank_mask:0x3 bound_ctrl:1
	v_add_f32_dpp v124, v125, v124 row_ror:8 row_mask:0xf bank_mask:0x3 bound_ctrl:1
	v_add_f32_dpp v111, v110, v111 row_ror:8 row_mask:0xf bank_mask:0x3 bound_ctrl:1
	v_add_f32_dpp v113, v112, v113 row_ror:8 row_mask:0xf bank_mask:0x3 bound_ctrl:1
	v_add_f32_dpp v115, v114, v115 row_ror:8 row_mask:0xf bank_mask:0x3 bound_ctrl:1
	v_add_f32_dpp v117, v116, v117 row_ror:8 row_mask:0xf bank_mask:0x3 bound_ctrl:1
	v_add_f32_dpp v119, v118, v119 row_ror:8 row_mask:0xf bank_mask:0x3 bound_ctrl:1
	v_add_f32_dpp v121, v120, v121 row_ror:8 row_mask:0xf bank_mask:0x3 bound_ctrl:1
	v_add_f32_dpp v123, v122, v123 row_ror:8 row_mask:0xf bank_mask:0x3 bound_ctrl:1
	v_add_f32_dpp v125, v124, v125 row_ror:8 row_mask:0xf bank_mask:0x3 bound_ctrl:1
	v_add_f32_dpp v110, v127, v126 row_ror:8 row_mask:0xf bank_mask:0xc bound_ctrl:1
	v_add_f32_dpp v112, v129, v128 row_ror:8 row_mask:0xf bank_mask:0xc bound_ctrl:1
	v_add_f32_dpp v114, v131, v130 row_ror:8 row_mask:0xf bank_mask:0xc bound_ctrl:1
	v_add_f32_dpp v116, v133, v132 row_ror:8 row_mask:0xf bank_mask:0xc bound_ctrl:1
	v_add_f32_dpp v118, v135, v134 row_ror:8 row_mask:0xf bank_mask:0xc bound_ctrl:1
	v_add_f32_dpp v120, v137, v136 row_ror:8 row_mask:0xf bank_mask:0xc bound_ctrl:1
	v_add_f32_dpp v122, v139, v138 row_ror:8 row_mask:0xf bank_mask:0xc bound_ctrl:1
	v_add_f32_dpp v124, v141, v140 row_ror:8 row_mask:0xf bank_mask:0xc bound_ctrl:1
	v_add_f32_dpp v111, v126, v127 row_ror:8 row_mask:0xf bank_mask:0xc bound_ctrl:1
	v_add_f32_dpp v113, v128, v129 row_ror:8 row_mask:0xf bank_mask:0xc bound_ctrl:1
	v_add_f32_dpp v115, v130, v131 row_ror:8 row_mask:0xf bank_mask:0xc bound_ctrl:1
	v_add_f32_dpp v117, v132, v133 row_ror:8 row_mask:0xf bank_mask:0xc bound_ctrl:1
	v_add_f32_dpp v119, v134, v135 row_ror:8 row_mask:0xf bank_mask:0xc bound_ctrl:1
	v_add_f32_dpp v121, v136, v137 row_ror:8 row_mask:0xf bank_mask:0xc bound_ctrl:1
	v_add_f32_dpp v123, v138, v139 row_ror:8 row_mask:0xf bank_mask:0xc bound_ctrl:1
	v_add_f32_dpp v125, v140, v141 row_ror:8 row_mask:0xf bank_mask:0xc bound_ctrl:1
	v_add_f32_dpp v110, v110, v110 row_shl:4 row_mask:0xf bank_mask:0x5 bound_ctrl:1
	v_add_f32_dpp v110, v118, v118 row_shr:4 row_mask:0xf bank_mask:0xa bound_ctrl:1
	v_add_f32_dpp v112, v112, v112 row_shl:4 row_mask:0xf bank_mask:0x5 bound_ctrl:1
	v_add_f32_dpp v112, v120, v120 row_shr:4 row_mask:0xf bank_mask:0xa bound_ctrl:1
	v_add_f32_dpp v114, v114, v114 row_shl:4 row_mask:0xf bank_mask:0x5 bound_ctrl:1
	v_add_f32_dpp v114, v122, v122 row_shr:4 row_mask:0xf bank_mask:0xa bound_ctrl:1
	v_add_f32_dpp v116, v116, v116 row_shl:4 row_mask:0xf bank_mask:0x5 bound_ctrl:1
	v_add_f32_dpp v116, v124, v124 row_shr:4 row_mask:0xf bank_mask:0xa bound_ctrl:1
	v_add_f32_dpp v111, v111, v111 row_shl:4 row_mask:0xf bank_mask:0x5 bound_ctrl:1
	v_add_f32_dpp v111, v119, v119 row_shr:4 row_mask:0xf bank_mask:0xa bound_ctrl:1
	v_add_f32_dpp v113, v113, v113 row_shl:4 row_mask:0xf bank_mask:0x5 bound_ctrl:1
	v_add_f32_dpp v113, v121, v121 row_shr:4 row_mask:0xf bank_mask:0xa bound_ctrl:1
	v_add_f32_dpp v115, v115, v115 row_shl:4 row_mask:0xf bank_mask:0x5 bound_ctrl:1
	v_add_f32_dpp v115, v123, v123 row_shr:4 row_mask:0xf bank_mask:0xa bound_ctrl:1
	v_add_f32_dpp v117, v117, v117 row_shl:4 row_mask:0xf bank_mask:0x5 bound_ctrl:1
	v_add_f32_dpp v117, v125, v125 row_shr:4 row_mask:0xf bank_mask:0xa bound_ctrl:1
	v_add_f32_dpp v110, v110, v110 quad_perm:[1,0,3,2] row_mask:0xf bank_mask:0xf bound_ctrl:1
	v_add_f32_dpp v112, v112, v112 quad_perm:[1,0,3,2] row_mask:0xf bank_mask:0xf bound_ctrl:1
	v_add_f32_dpp v114, v114, v114 quad_perm:[1,0,3,2] row_mask:0xf bank_mask:0xf bound_ctrl:1
	v_add_f32_dpp v116, v116, v116 quad_perm:[1,0,3,2] row_mask:0xf bank_mask:0xf bound_ctrl:1
	v_add_f32_dpp v111, v111, v111 quad_perm:[1,0,3,2] row_mask:0xf bank_mask:0xf bound_ctrl:1
	v_add_f32_dpp v113, v113, v113 quad_perm:[1,0,3,2] row_mask:0xf bank_mask:0xf bound_ctrl:1
	v_add_f32_dpp v115, v115, v115 quad_perm:[1,0,3,2] row_mask:0xf bank_mask:0xf bound_ctrl:1
	v_add_f32_dpp v117, v117, v117 quad_perm:[1,0,3,2] row_mask:0xf bank_mask:0xf bound_ctrl:1
	v_add_f32_dpp v110, v110, v110 quad_perm:[2,3,0,1] row_mask:0xf bank_mask:0xf bound_ctrl:1
	v_add_f32_dpp v112, v112, v112 quad_perm:[2,3,0,1] row_mask:0xf bank_mask:0xf bound_ctrl:1
	v_add_f32_dpp v114, v114, v114 quad_perm:[2,3,0,1] row_mask:0xf bank_mask:0xf bound_ctrl:1
	v_add_f32_dpp v116, v116, v116 quad_perm:[2,3,0,1] row_mask:0xf bank_mask:0xf bound_ctrl:1
	v_add_f32_dpp v111, v111, v111 quad_perm:[2,3,0,1] row_mask:0xf bank_mask:0xf bound_ctrl:1
	v_add_f32_dpp v113, v113, v113 quad_perm:[2,3,0,1] row_mask:0xf bank_mask:0xf bound_ctrl:1
	v_add_f32_dpp v115, v115, v115 quad_perm:[2,3,0,1] row_mask:0xf bank_mask:0xf bound_ctrl:1
	v_add_f32_dpp v117, v117, v117 quad_perm:[2,3,0,1] row_mask:0xf bank_mask:0xf bound_ctrl:1
	v_subrev_u32_e32 v72, 16, v57
	v_ashrrev_i32_e32 v73, 31, v72
	v_lshlrev_b64 v[72:73], 10, v[72:73]
	v_lshl_add_u64 v[72:73], v[64:65], 0, v[72:73]
	v_cndmask_b32_e64 v154, v116, v114, s[16:17]
	v_cndmask_b32_e64 v155, v117, v115, s[16:17]
	v_cndmask_b32_e64 v154, v154, v112, s[14:15]
	v_cndmask_b32_e64 v155, v155, v113, s[14:15]
	v_cndmask_b32_e64 v154, v154, v110, s[12:13]
	v_cndmask_b32_e64 v155, v155, v111, s[12:13]
	v_cvt_pk_bf16_f32 v157, v155, v154
	v_cvt_pk_bf16_f32 v154, v154, v155
	v_cndmask_b32_e64 v154, v154, v157, s[98:99]
	global_store_dword v[72:73], v154, off
; #define LAS __attribute__((address_space(3)))
; #define ROW16_SUM4(x, y, z, w) do { DPP4(x, y, z, w, "quad_perm:[1,0,3,2]", "s_nop 1"); DPP4(x, y, z, w, "quad_perm:[2,3,0,1]", ""); DPP4(x, y, z, w, "row_half_mirror", ""); DPP4(x, y, z, w, "row_mirror", ""); } while (0)
; template <bool SAMPLE>
; __device__ __forceinline__ void rwkv_unit(PR P, LAS float* lds, const int b, const int h, const int half, const int wv) {
;     ...
;                 for (int tt = 0; tt < GS; ++tt) {
;                     const LAS float* qn = q0 + (tt + 1 < GS ? tt + 1 : tt) * 384;
;                     const f32x4 nr4 = *(const LAS f32x4*)(qn + j0), no4 = *(const LAS f32x4*)(qn + 64 + j0), nk4 = *(const LAS f32x4*)(qn + 128 + j0), na4 = *(const LAS f32x4*)(qn + 192 + j0), nb4 = *(const LAS f32x4*)(qn + 256 + j0);
;                     const f32x2 nv2 = *(const LAS f32x2*)(qn + 320 + row0);
;                     f32x2 sa = (S[0] * a4[0] + S[1] * a4[1]) + (S[2] * a4[2] + S[3] * a4[3]);
;                     float sx = sa.x, sy = sa.y; ROW16_SUM4(sx, sy, py0, py1); sa = (f32x2){sx, sy};
;                     if (tt > 0) { yk0 = cgl == tt - 1 ? py0 : yk0; yk1 = cgl == tt - 1 ? py1 : yk1; }
; #pragma unroll
;                     for (int c = 0; c < 4; ++c) { f32x2 t = S[c] - S[c] * o4[c]; t = t + sa * b4[c]; S[c] = t + v2 * k4[c]; }
;                     const f32x2 y = (S[0] * r4[0] + S[1] * r4[1]) + (S[2] * r4[2] + S[3] * r4[3]);
;                     py0 = y.x; py1 = y.y;
;                     r4 = nr4; o4 = no4; k4 = nk4; a4 = na4; b4 = nb4; v2 = nv2;
.Lrw_first_chunk:
	s_waitcnt lgkmcnt(0)
	s_nop 0
	v_pk_mul_f32 v[150:151], v[66:67], v[172:173] op_sel_hi:[1,0]
	ds_read_b128 v[212:215], v152 offset:3840
	v_pk_fma_f32 v[150:151], v[20:21], v[172:173], v[150:151] op_sel:[0,1,0]
	ds_read_b128 v[204:207], v152 offset:3328
	v_pk_fma_f32 v[150:151], v[68:69], v[174:175], v[150:151] op_sel_hi:[1,0,1]
	ds_read2st64_b64 v[244:247], v153 offset0:8 offset1:11
	v_pk_fma_f32 v[150:151], v[70:71], v[174:175], v[150:151] op_sel:[0,1,0]
	ds_read_b128 v[208:211], v152 offset:3584
	v_pk_fma_f32 v[142:143], v[66:67], v[164:165], v[66:67] op_sel_hi:[1,0,1] neg_lo:[1,0,0] neg_hi:[1,0,0]
	v_pk_fma_f32 v[144:145], v[20:21], v[164:165], v[20:21] op_sel:[0,1,0] neg_lo:[1,0,0] neg_hi:[1,0,0]
	v_add_f32_dpp v150, v151, v150 row_ror:8 row_mask:0xf bank_mask:0xf bound_ctrl:1
	v_pk_fma_f32 v[146:147], v[68:69], v[166:167], v[68:69] op_sel_hi:[1,0,1] neg_lo:[1,0,0] neg_hi:[1,0,0]
	v_pk_fma_f32 v[148:149], v[70:71], v[166:167], v[70:71] op_sel:[0,1,0] neg_lo:[1,0,0] neg_hi:[1,0,0]
	v_add_f32_dpp v150, v150, v150 quad_perm:[1,0,3,2] row_mask:0xf bank_mask:0xf bound_ctrl:1
	v_pk_fma_f32 v[142:143], v[240:241], v[168:169], v[142:143] op_sel_hi:[1,0,1]
	v_pk_fma_f32 v[144:145], v[240:241], v[168:169], v[144:145] op_sel:[0,1,0]
	v_add_f32_dpp v150, v150, v150 quad_perm:[2,3,0,1] row_mask:0xf bank_mask:0xf bound_ctrl:1
	v_pk_fma_f32 v[146:147], v[240:241], v[170:171], v[146:147] op_sel_hi:[1,0,1]
	v_pk_fma_f32 v[148:149], v[240:241], v[170:171], v[148:149] op_sel:[0,1,0]
	v_add_f32_dpp v150, v150, v150 row_half_mirror row_mask:0xf bank_mask:0xf bound_ctrl:1
	ds_read_b128 v[232:235], v152 offset:5376
	ds_read_b128 v[224:227], v152 offset:4864
	v_mov_b32_dpp v151, v150 row_ror:8 row_mask:0xf bank_mask:0xf bound_ctrl:1
	ds_read_b128 v[216:219], v152 offset:4096
	ds_read_b128 v[228:231], v152 offset:5120
	ds_read_b128 v[236:239], v152 offset:5632
	ds_read_b128 v[200:203], v152 offset:3072
	ds_read_b128 v[220:223], v152 offset:4608
	v_pk_fma_f32 v[66:67], v[150:151], v[176:177], v[142:143] op_sel_hi:[1,0,1]
	v_pk_fma_f32 v[20:21], v[150:151], v[176:177], v[144:145] op_sel:[0,1,0]
	v_pk_fma_f32 v[68:69], v[150:151], v[178:179], v[146:147] op_sel_hi:[1,0,1]
	v_pk_fma_f32 v[70:71], v[150:151], v[178:179], v[148:149] op_sel:[0,1,0]
	v_pk_mul_f32 v[78:79], v[66:67], v[160:161] op_sel_hi:[1,0]
	v_pk_mul_f32 v[150:151], v[66:67], v[192:193] op_sel_hi:[1,0]
	v_pk_fma_f32 v[78:79], v[20:21], v[160:161], v[78:79] op_sel:[0,1,0]
	v_pk_fma_f32 v[150:151], v[20:21], v[192:193], v[150:151] op_sel:[0,1,0]
	v_pk_fma_f32 v[78:79], v[68:69], v[162:163], v[78:79] op_sel_hi:[1,0,1]
	v_pk_fma_f32 v[150:151], v[68:69], v[194:195], v[150:151] op_sel_hi:[1,0,1]
	v_pk_fma_f32 v[78:79], v[70:71], v[162:163], v[78:79] op_sel:[0,1,0]
	v_pk_fma_f32 v[150:151], v[70:71], v[194:195], v[150:151] op_sel:[0,1,0]
	v_pk_fma_f32 v[142:143], v[66:67], v[184:185], v[66:67] op_sel_hi:[1,0,1] neg_lo:[1,0,0] neg_hi:[1,0,0]
	v_pk_fma_f32 v[144:145], v[20:21], v[184:185], v[20:21] op_sel:[0,1,0] neg_lo:[1,0,0] neg_hi:[1,0,0]
	v_add_f32_dpp v150, v151, v150 row_ror:8 row_mask:0xf bank_mask:0xf bound_ctrl:1
	v_pk_fma_f32 v[146:147], v[68:69], v[186:187], v[68:69] op_sel_hi:[1,0,1] neg_lo:[1,0,0] neg_hi:[1,0,0]
	v_pk_fma_f32 v[148:149], v[70:71], v[186:187], v[70:71] op_sel:[0,1,0] neg_lo:[1,0,0] neg_hi:[1,0,0]
	v_add_f32_dpp v150, v150, v150 quad_perm:[1,0,3,2] row_mask:0xf bank_mask:0xf bound_ctrl:1
	v_pk_fma_f32 v[142:143], v[242:243], v[188:189], v[142:143] op_sel_hi:[1,0,1]
	v_pk_fma_f32 v[144:145], v[242:243], v[188:189], v[144:145] op_sel:[0,1,0]
	v_add_f32_dpp v150, v150, v150 quad_perm:[2,3,0,1] row_mask:0xf bank_mask:0xf bound_ctrl:1
	v_pk_fma_f32 v[146:147], v[242:243], v[190:191], v[146:147] op_sel_hi:[1,0,1]
	v_pk_fma_f32 v[148:149], v[242:243], v[190:191], v[148:149] op_sel:[0,1,0]
	v_add_f32_dpp v150, v150, v150 row_half_mirror row_mask:0xf bank_mask:0xf bound_ctrl:1
	s_nop 0
	s_waitcnt lgkmcnt(0)
	v_mov_b32_dpp v151, v150 row_ror:8 row_mask:0xf bank_mask:0xf bound_ctrl:1
	v_pk_fma_f32 v[66:67], v[150:151], v[196:197], v[142:143] op_sel_hi:[1,0,1]
	v_pk_fma_f32 v[20:21], v[150:151], v[196:197], v[144:145] op_sel:[0,1,0]
	v_pk_fma_f32 v[68:69], v[150:151], v[198:199], v[146:147] op_sel_hi:[1,0,1]
	v_pk_fma_f32 v[70:71], v[150:151], v[198:199], v[148:149] op_sel:[0,1,0]
	v_pk_mul_f32 v[80:81], v[66:67], v[180:181] op_sel_hi:[1,0]
	v_pk_mul_f32 v[150:151], v[66:67], v[212:213] op_sel_hi:[1,0]
	ds_read_b128 v[172:175], v152 offset:6912
	v_pk_fma_f32 v[80:81], v[20:21], v[180:181], v[80:81] op_sel:[0,1,0]
	v_pk_fma_f32 v[150:151], v[20:21], v[212:213], v[150:151] op_sel:[0,1,0]
	ds_read_b128 v[164:167], v152 offset:6400
	v_pk_fma_f32 v[80:81], v[68:69], v[182:183], v[80:81] op_sel_hi:[1,0,1]
	v_pk_fma_f32 v[150:151], v[68:69], v[214:215], v[150:151] op_sel_hi:[1,0,1]
	ds_read2st64_b64 v[248:251], v153 offset0:14 offset1:17
	v_pk_fma_f32 v[80:81], v[70:71], v[182:183], v[80:81] op_sel:[0,1,0]
	v_pk_fma_f32 v[150:151], v[70:71], v[214:215], v[150:151] op_sel:[0,1,0]
	ds_read_b128 v[168:171], v152 offset:6656
	v_pk_fma_f32 v[142:143], v[66:67], v[204:205], v[66:67] op_sel_hi:[1,0,1] neg_lo:[1,0,0] neg_hi:[1,0,0]
	v_pk_fma_f32 v[144:145], v[20:21], v[204:205], v[20:21] op_sel:[0,1,0] neg_lo:[1,0,0] neg_hi:[1,0,0]
	v_add_f32_dpp v150, v151, v150 row_ror:8 row_mask:0xf bank_mask:0xf bound_ctrl:1
	v_pk_fma_f32 v[146:147], v[68:69], v[206:207], v[68:69] op_sel_hi:[1,0,1] neg_lo:[1,0,0] neg_hi:[1,0,0]
	v_pk_fma_f32 v[148:149], v[70:71], v[206:207], v[70:71] op_sel:[0,1,0] neg_lo:[1,0,0] neg_hi:[1,0,0]
	v_add_f32_dpp v150, v150, v150 quad_perm:[1,0,3,2] row_mask:0xf bank_mask:0xf bound_ctrl:1
; #define LAS __attribute__((address_space(3)))
; #define ROW16_SUM4(x, y, z, w) do { DPP4(x, y, z, w, "quad_perm:[1,0,3,2]", "s_nop 1"); DPP4(x, y, z, w, "quad_perm:[2,3,0,1]", ""); DPP4(x, y, z, w, "row_half_mirror", ""); DPP4(x, y, z, w, "row_mirror", ""); } while (0)
; template <bool SAMPLE>
; __device__ __forceinline__ void rwkv_unit(PR P, LAS float* lds, const int b, const int h, const int half, const int wv) {
;     ...
;                 for (int tt = 0; tt < GS; ++tt) {
;                     const LAS float* qn = q0 + (tt + 1 < GS ? tt + 1 : tt) * 384;
;                     const f32x4 nr4 = *(const LAS f32x4*)(qn + j0), no4 = *(const LAS f32x4*)(qn + 64 + j0), nk4 = *(const LAS f32x4*)(qn + 128 + j0), na4 = *(const LAS f32x4*)(qn + 192 + j0), nb4 = *(const LAS f32x4*)(qn + 256 + j0);
;                     const f32x2 nv2 = *(const LAS f32x2*)(qn + 320 + row0);
;                     f32x2 sa = (S[0] * a4[0] + S[1] * a4[1]) + (S[2] * a4[2] + S[3] * a4[3]);
;                     float sx = sa.x, sy = sa.y; ROW16_SUM4(sx, sy, py0, py1); sa = (f32x2){sx, sy};
;                     if (tt > 0) { yk0 = cgl == tt - 1 ? py0 : yk0; yk1 = cgl == tt - 1 ? py1 : yk1; }
; #pragma unroll
;                     for (int c = 0; c < 4; ++c) { f32x2 t = S[c] - S[c] * o4[c]; t = t + sa * b4[c]; S[c] = t + v2 * k4[c]; }
;                     const f32x2 y = (S[0] * r4[0] + S[1] * r4[1]) + (S[2] * r4[2] + S[3] * r4[3]);
;                     py0 = y.x; py1 = y.y;
;                     r4 = nr4; o4 = no4; k4 = nk4; a4 = na4; b4 = nb4; v2 = nv2;
	v_pk_fma_f32 v[142:143], v[244:245], v[208:209], v[142:143] op_sel_hi:[1,0,1]
	v_pk_fma_f32 v[144:145], v[244:245], v[208:209], v[144:145] op_sel:[0,1,0]
	v_add_f32_dpp v150, v150, v150 quad_perm:[2,3,0,1] row_mask:0xf bank_mask:0xf bound_ctrl:1
	v_pk_fma_f32 v[146:147], v[244:245], v[210:211], v[146:147] op_sel_hi:[1,0,1]
	v_pk_fma_f32 v[148:149], v[244:245], v[210:211], v[148:149] op_sel:[0,1,0]
	v_add_f32_dpp v150, v150, v150 row_half_mirror row_mask:0xf bank_mask:0xf bound_ctrl:1
	ds_read_b128 v[192:195], v152 offset:8448
	ds_read_b128 v[184:187], v152 offset:7936
	v_mov_b32_dpp v151, v150 row_ror:8 row_mask:0xf bank_mask:0xf bound_ctrl:1
	ds_read_b128 v[176:179], v152 offset:7168
	ds_read_b128 v[188:191], v152 offset:8192
	ds_read_b128 v[196:199], v152 offset:8704
	ds_read_b128 v[160:163], v152 offset:6144
	ds_read_b128 v[180:183], v152 offset:7680
	v_pk_fma_f32 v[66:67], v[150:151], v[216:217], v[142:143] op_sel_hi:[1,0,1]
	v_pk_fma_f32 v[20:21], v[150:151], v[216:217], v[144:145] op_sel:[0,1,0]
	v_pk_fma_f32 v[68:69], v[150:151], v[218:219], v[146:147] op_sel_hi:[1,0,1]
	v_pk_fma_f32 v[70:71], v[150:151], v[218:219], v[148:149] op_sel:[0,1,0]
	v_pk_mul_f32 v[82:83], v[66:67], v[200:201] op_sel_hi:[1,0]
	v_pk_mul_f32 v[150:151], v[66:67], v[232:233] op_sel_hi:[1,0]
	v_pk_fma_f32 v[82:83], v[20:21], v[200:201], v[82:83] op_sel:[0,1,0]
	v_pk_fma_f32 v[150:151], v[20:21], v[232:233], v[150:151] op_sel:[0,1,0]
	v_pk_fma_f32 v[82:83], v[68:69], v[202:203], v[82:83] op_sel_hi:[1,0,1]
	v_pk_fma_f32 v[150:151], v[68:69], v[234:235], v[150:151] op_sel_hi:[1,0,1]
	v_pk_fma_f32 v[82:83], v[70:71], v[202:203], v[82:83] op_sel:[0,1,0]
	v_pk_fma_f32 v[150:151], v[70:71], v[234:235], v[150:151] op_sel:[0,1,0]
	v_pk_fma_f32 v[142:143], v[66:67], v[224:225], v[66:67] op_sel_hi:[1,0,1] neg_lo:[1,0,0] neg_hi:[1,0,0]
	v_pk_fma_f32 v[144:145], v[20:21], v[224:225], v[20:21] op_sel:[0,1,0] neg_lo:[1,0,0] neg_hi:[1,0,0]
	v_add_f32_dpp v150, v151, v150 row_ror:8 row_mask:0xf bank_mask:0xf bound_ctrl:1
	v_pk_fma_f32 v[146:147], v[68:69], v[226:227], v[68:69] op_sel_hi:[1,0,1] neg_lo:[1,0,0] neg_hi:[1,0,0]
	v_pk_fma_f32 v[148:149], v[70:71], v[226:227], v[70:71] op_sel:[0,1,0] neg_lo:[1,0,0] neg_hi:[1,0,0]
	v_add_f32_dpp v150, v150, v150 quad_perm:[1,0,3,2] row_mask:0xf bank_mask:0xf bound_ctrl:1
	v_pk_fma_f32 v[142:143], v[246:247], v[228:229], v[142:143] op_sel_hi:[1,0,1]
	v_pk_fma_f32 v[144:145], v[246:247], v[228:229], v[144:145] op_sel:[0,1,0]
	v_add_f32_dpp v150, v150, v150 quad_perm:[2,3,0,1] row_mask:0xf bank_mask:0xf bound_ctrl:1
	v_pk_fma_f32 v[146:147], v[246:247], v[230:231], v[146:147] op_sel_hi:[1,0,1]
	v_pk_fma_f32 v[148:149], v[246:247], v[230:231], v[148:149] op_sel:[0,1,0]
	v_add_f32_dpp v150, v150, v150 row_half_mirror row_mask:0xf bank_mask:0xf bound_ctrl:1
	s_nop 0
	s_waitcnt lgkmcnt(0)
	v_mov_b32_dpp v151, v150 row_ror:8 row_mask:0xf bank_mask:0xf bound_ctrl:1
	v_pk_fma_f32 v[66:67], v[150:151], v[236:237], v[142:143] op_sel_hi:[1,0,1]
	v_pk_fma_f32 v[20:21], v[150:151], v[236:237], v[144:145] op_sel:[0,1,0]
	v_pk_fma_f32 v[68:69], v[150:151], v[238:239], v[146:147] op_sel_hi:[1,0,1]
	v_pk_fma_f32 v[70:71], v[150:151], v[238:239], v[148:149] op_sel:[0,1,0]
	v_pk_mul_f32 v[84:85], v[66:67], v[220:221] op_sel_hi:[1,0]
	v_pk_mul_f32 v[150:151], v[66:67], v[172:173] op_sel_hi:[1,0]
	ds_read_b128 v[212:215], v152 offset:9984
	v_pk_fma_f32 v[84:85], v[20:21], v[220:221], v[84:85] op_sel:[0,1,0]
	v_pk_fma_f32 v[150:151], v[20:21], v[172:173], v[150:151] op_sel:[0,1,0]
	ds_read_b128 v[204:207], v152 offset:9472
	v_pk_fma_f32 v[84:85], v[68:69], v[222:223], v[84:85] op_sel_hi:[1,0,1]
	v_pk_fma_f32 v[150:151], v[68:69], v[174:175], v[150:151] op_sel_hi:[1,0,1]
	ds_read2st64_b64 v[240:243], v153 offset0:20 offset1:23
	v_pk_fma_f32 v[84:85], v[70:71], v[222:223], v[84:85] op_sel:[0,1,0]
	v_pk_fma_f32 v[150:151], v[70:71], v[174:175], v[150:151] op_sel:[0,1,0]
	ds_read_b128 v[208:211], v152 offset:9728
	v_pk_fma_f32 v[142:143], v[66:67], v[164:165], v[66:67] op_sel_hi:[1,0,1] neg_lo:[1,0,0] neg_hi:[1,0,0]
	v_pk_fma_f32 v[144:145], v[20:21], v[164:165], v[20:21] op_sel:[0,1,0] neg_lo:[1,0,0] neg_hi:[1,0,0]
	v_add_f32_dpp v150, v151, v150 row_ror:8 row_mask:0xf bank_mask:0xf bound_ctrl:1
	v_pk_fma_f32 v[146:147], v[68:69], v[166:167], v[68:69] op_sel_hi:[1,0,1] neg_lo:[1,0,0] neg_hi:[1,0,0]
	v_pk_fma_f32 v[148:149], v[70:71], v[166:167], v[70:71] op_sel:[0,1,0] neg_lo:[1,0,0] neg_hi:[1,0,0]
	v_add_f32_dpp v150, v150, v150 quad_perm:[1,0,3,2] row_mask:0xf bank_mask:0xf bound_ctrl:1
	v_pk_fma_f32 v[142:143], v[248:249], v[168:169], v[142:143] op_sel_hi:[1,0,1]
	v_pk_fma_f32 v[144:145], v[248:249], v[168:169], v[144:145] op_sel:[0,1,0]
	v_add_f32_dpp v150, v150, v150 quad_perm:[2,3,0,1] row_mask:0xf bank_mask:0xf bound_ctrl:1
	v_pk_fma_f32 v[146:147], v[248:249], v[170:171], v[146:147] op_sel_hi:[1,0,1]
	v_pk_fma_f32 v[148:149], v[248:249], v[170:171], v[148:149] op_sel:[0,1,0]
	v_add_f32_dpp v150, v150, v150 row_half_mirror row_mask:0xf bank_mask:0xf bound_ctrl:1
	ds_read_b128 v[232:235], v152 offset:11520
	ds_read_b128 v[224:227], v152 offset:11008
	v_mov_b32_dpp v151, v150 row_ror:8 row_mask:0xf bank_mask:0xf bound_ctrl:1
	ds_read_b128 v[216:219], v152 offset:10240
	ds_read_b128 v[228:231], v152 offset:11264
	ds_read_b128 v[236:239], v152 offset:11776
	ds_read_b128 v[200:203], v152 offset:9216
	ds_read_b128 v[220:223], v152 offset:10752
	v_pk_fma_f32 v[66:67], v[150:151], v[176:177], v[142:143] op_sel_hi:[1,0,1]
	v_pk_fma_f32 v[20:21], v[150:151], v[176:177], v[144:145] op_sel:[0,1,0]
	v_pk_fma_f32 v[68:69], v[150:151], v[178:179], v[146:147] op_sel_hi:[1,0,1]
; #define LAS __attribute__((address_space(3)))
; #define ROW16_SUM4(x, y, z, w) do { DPP4(x, y, z, w, "quad_perm:[1,0,3,2]", "s_nop 1"); DPP4(x, y, z, w, "quad_perm:[2,3,0,1]", ""); DPP4(x, y, z, w, "row_half_mirror", ""); DPP4(x, y, z, w, "row_mirror", ""); } while (0)
; template <bool SAMPLE>
; __device__ __forceinline__ void rwkv_unit(PR P, LAS float* lds, const int b, const int h, const int half, const int wv) {
;     ...
;                 for (int tt = 0; tt < GS; ++tt) {
;                     const LAS float* qn = q0 + (tt + 1 < GS ? tt + 1 : tt) * 384;
;                     const f32x4 nr4 = *(const LAS f32x4*)(qn + j0), no4 = *(const LAS f32x4*)(qn + 64 + j0), nk4 = *(const LAS f32x4*)(qn + 128 + j0), na4 = *(const LAS f32x4*)(qn + 192 + j0), nb4 = *(const LAS f32x4*)(qn + 256 + j0);
;                     const f32x2 nv2 = *(const LAS f32x2*)(qn + 320 + row0);
;                     f32x2 sa = (S[0] * a4[0] + S[1] * a4[1]) + (S[2] * a4[2] + S[3] * a4[3]);
;                     float sx = sa.x, sy = sa.y; ROW16_SUM4(sx, sy, py0, py1); sa = (f32x2){sx, sy};
;                     if (tt > 0) { yk0 = cgl == tt - 1 ? py0 : yk0; yk1 = cgl == tt - 1 ? py1 : yk1; }
; #pragma unroll
;                     for (int c = 0; c < 4; ++c) { f32x2 t = S[c] - S[c] * o4[c]; t = t + sa * b4[c]; S[c] = t + v2 * k4[c]; }
;                     const f32x2 y = (S[0] * r4[0] + S[1] * r4[1]) + (S[2] * r4[2] + S[3] * r4[3]);
;                     py0 = y.x; py1 = y.y;
;                     r4 = nr4; o4 = no4; k4 = nk4; a4 = na4; b4 = nb4; v2 = nv2;
	v_pk_fma_f32 v[70:71], v[150:151], v[178:179], v[148:149] op_sel:[0,1,0]
	v_pk_mul_f32 v[86:87], v[66:67], v[160:161] op_sel_hi:[1,0]
	v_pk_mul_f32 v[150:151], v[66:67], v[192:193] op_sel_hi:[1,0]
	v_pk_fma_f32 v[86:87], v[20:21], v[160:161], v[86:87] op_sel:[0,1,0]
	v_pk_fma_f32 v[150:151], v[20:21], v[192:193], v[150:151] op_sel:[0,1,0]
	v_pk_fma_f32 v[86:87], v[68:69], v[162:163], v[86:87] op_sel_hi:[1,0,1]
	v_pk_fma_f32 v[150:151], v[68:69], v[194:195], v[150:151] op_sel_hi:[1,0,1]
	v_pk_fma_f32 v[86:87], v[70:71], v[162:163], v[86:87] op_sel:[0,1,0]
	v_pk_fma_f32 v[150:151], v[70:71], v[194:195], v[150:151] op_sel:[0,1,0]
	v_pk_fma_f32 v[142:143], v[66:67], v[184:185], v[66:67] op_sel_hi:[1,0,1] neg_lo:[1,0,0] neg_hi:[1,0,0]
	v_pk_fma_f32 v[144:145], v[20:21], v[184:185], v[20:21] op_sel:[0,1,0] neg_lo:[1,0,0] neg_hi:[1,0,0]
	v_add_f32_dpp v150, v151, v150 row_ror:8 row_mask:0xf bank_mask:0xf bound_ctrl:1
	v_pk_fma_f32 v[146:147], v[68:69], v[186:187], v[68:69] op_sel_hi:[1,0,1] neg_lo:[1,0,0] neg_hi:[1,0,0]
	v_pk_fma_f32 v[148:149], v[70:71], v[186:187], v[70:71] op_sel:[0,1,0] neg_lo:[1,0,0] neg_hi:[1,0,0]
	v_add_f32_dpp v150, v150, v150 quad_perm:[1,0,3,2] row_mask:0xf bank_mask:0xf bound_ctrl:1
	v_pk_fma_f32 v[142:143], v[250:251], v[188:189], v[142:143] op_sel_hi:[1,0,1]
	v_pk_fma_f32 v[144:145], v[250:251], v[188:189], v[144:145] op_sel:[0,1,0]
	v_add_f32_dpp v150, v150, v150 quad_perm:[2,3,0,1] row_mask:0xf bank_mask:0xf bound_ctrl:1
	v_pk_fma_f32 v[146:147], v[250:251], v[190:191], v[146:147] op_sel_hi:[1,0,1]
	v_pk_fma_f32 v[148:149], v[250:251], v[190:191], v[148:149] op_sel:[0,1,0]
	v_add_f32_dpp v150, v150, v150 row_half_mirror row_mask:0xf bank_mask:0xf bound_ctrl:1
	s_nop 0
	s_waitcnt lgkmcnt(0)
	v_mov_b32_dpp v151, v150 row_ror:8 row_mask:0xf bank_mask:0xf bound_ctrl:1
	v_pk_fma_f32 v[66:67], v[150:151], v[196:197], v[142:143] op_sel_hi:[1,0,1]
	v_pk_fma_f32 v[20:21], v[150:151], v[196:197], v[144:145] op_sel:[0,1,0]
	v_pk_fma_f32 v[68:69], v[150:151], v[198:199], v[146:147] op_sel_hi:[1,0,1]
	v_pk_fma_f32 v[70:71], v[150:151], v[198:199], v[148:149] op_sel:[0,1,0]
	v_pk_mul_f32 v[88:89], v[66:67], v[180:181] op_sel_hi:[1,0]
	v_pk_mul_f32 v[150:151], v[66:67], v[212:213] op_sel_hi:[1,0]
	ds_read_b128 v[172:175], v152 offset:13056
	v_pk_fma_f32 v[88:89], v[20:21], v[180:181], v[88:89] op_sel:[0,1,0]
	v_pk_fma_f32 v[150:151], v[20:21], v[212:213], v[150:151] op_sel:[0,1,0]
	ds_read_b128 v[164:167], v152 offset:12544
	v_pk_fma_f32 v[88:89], v[68:69], v[182:183], v[88:89] op_sel_hi:[1,0,1]
	v_pk_fma_f32 v[150:151], v[68:69], v[214:215], v[150:151] op_sel_hi:[1,0,1]
	ds_read2st64_b64 v[244:247], v153 offset0:26 offset1:29
	v_pk_fma_f32 v[88:89], v[70:71], v[182:183], v[88:89] op_sel:[0,1,0]
	v_pk_fma_f32 v[150:151], v[70:71], v[214:215], v[150:151] op_sel:[0,1,0]
	ds_read_b128 v[168:171], v152 offset:12800
	v_pk_fma_f32 v[142:143], v[66:67], v[204:205], v[66:67] op_sel_hi:[1,0,1] neg_lo:[1,0,0] neg_hi:[1,0,0]
	v_pk_fma_f32 v[144:145], v[20:21], v[204:205], v[20:21] op_sel:[0,1,0] neg_lo:[1,0,0] neg_hi:[1,0,0]
	v_add_f32_dpp v150, v151, v150 row_ror:8 row_mask:0xf bank_mask:0xf bound_ctrl:1
	v_pk_fma_f32 v[146:147], v[68:69], v[206:207], v[68:69] op_sel_hi:[1,0,1] neg_lo:[1,0,0] neg_hi:[1,0,0]
	v_pk_fma_f32 v[148:149], v[70:71], v[206:207], v[70:71] op_sel:[0,1,0] neg_lo:[1,0,0] neg_hi:[1,0,0]
	v_add_f32_dpp v150, v150, v150 quad_perm:[1,0,3,2] row_mask:0xf bank_mask:0xf bound_ctrl:1
	v_pk_fma_f32 v[142:143], v[240:241], v[208:209], v[142:143] op_sel_hi:[1,0,1]
	v_pk_fma_f32 v[144:145], v[240:241], v[208:209], v[144:145] op_sel:[0,1,0]
	v_add_f32_dpp v150, v150, v150 quad_perm:[2,3,0,1] row_mask:0xf bank_mask:0xf bound_ctrl:1
	v_pk_fma_f32 v[146:147], v[240:241], v[210:211], v[146:147] op_sel_hi:[1,0,1]
	v_pk_fma_f32 v[148:149], v[240:241], v[210:211], v[148:149] op_sel:[0,1,0]
	v_add_f32_dpp v150, v150, v150 row_half_mirror row_mask:0xf bank_mask:0xf bound_ctrl:1
	ds_read_b128 v[192:195], v152 offset:14592
	ds_read_b128 v[184:187], v152 offset:14080
	v_mov_b32_dpp v151, v150 row_ror:8 row_mask:0xf bank_mask:0xf bound_ctrl:1
	ds_read_b128 v[176:179], v152 offset:13312
	ds_read_b128 v[188:191], v152 offset:14336
	ds_read_b128 v[196:199], v152 offset:14848
	ds_read_b128 v[160:163], v152 offset:12288
	ds_read_b128 v[180:183], v152 offset:13824
	v_pk_fma_f32 v[66:67], v[150:151], v[216:217], v[142:143] op_sel_hi:[1,0,1]
	v_pk_fma_f32 v[20:21], v[150:151], v[216:217], v[144:145] op_sel:[0,1,0]
	v_pk_fma_f32 v[68:69], v[150:151], v[218:219], v[146:147] op_sel_hi:[1,0,1]
	v_pk_fma_f32 v[70:71], v[150:151], v[218:219], v[148:149] op_sel:[0,1,0]
	v_pk_mul_f32 v[90:91], v[66:67], v[200:201] op_sel_hi:[1,0]
	v_pk_mul_f32 v[150:151], v[66:67], v[232:233] op_sel_hi:[1,0]
	v_pk_fma_f32 v[90:91], v[20:21], v[200:201], v[90:91] op_sel:[0,1,0]
	v_pk_fma_f32 v[150:151], v[20:21], v[232:233], v[150:151] op_sel:[0,1,0]
	v_pk_fma_f32 v[90:91], v[68:69], v[202:203], v[90:91] op_sel_hi:[1,0,1]
	v_pk_fma_f32 v[150:151], v[68:69], v[234:235], v[150:151] op_sel_hi:[1,0,1]
	v_pk_fma_f32 v[90:91], v[70:71], v[202:203], v[90:91] op_sel:[0,1,0]
	v_pk_fma_f32 v[150:151], v[70:71], v[234:235], v[150:151] op_sel:[0,1,0]
	v_pk_fma_f32 v[142:143], v[66:67], v[224:225], v[66:67] op_sel_hi:[1,0,1] neg_lo:[1,0,0] neg_hi:[1,0,0]
	v_pk_fma_f32 v[144:145], v[20:21], v[224:225], v[20:21] op_sel:[0,1,0] neg_lo:[1,0,0] neg_hi:[1,0,0]
	v_add_f32_dpp v150, v151, v150 row_ror:8 row_mask:0xf bank_mask:0xf bound_ctrl:1
	v_pk_fma_f32 v[146:147], v[68:69], v[226:227], v[68:69] op_sel_hi:[1,0,1] neg_lo:[1,0,0] neg_hi:[1,0,0]
	v_pk_fma_f32 v[148:149], v[70:71], v[226:227], v[70:71] op_sel:[0,1,0] neg_lo:[1,0,0] neg_hi:[1,0,0]
	v_add_f32_dpp v150, v150, v150 quad_perm:[1,0,3,2] row_mask:0xf bank_mask:0xf bound_ctrl:1
	v_pk_fma_f32 v[142:143], v[242:243], v[228:229], v[142:143] op_sel_hi:[1,0,1]
	v_pk_fma_f32 v[144:145], v[242:243], v[228:229], v[144:145] op_sel:[0,1,0]
	v_add_f32_dpp v150, v150, v150 quad_perm:[2,3,0,1] row_mask:0xf bank_mask:0xf bound_ctrl:1
	v_pk_fma_f32 v[146:147], v[242:243], v[230:231], v[146:147] op_sel_hi:[1,0,1]
	v_pk_fma_f32 v[148:149], v[242:243], v[230:231], v[148:149] op_sel:[0,1,0]
	v_add_f32_dpp v150, v150, v150 row_half_mirror row_mask:0xf bank_mask:0xf bound_ctrl:1
	s_nop 0
	s_waitcnt lgkmcnt(0)
; #define LAS __attribute__((address_space(3)))
; #define ROW16_SUM4(x, y, z, w) do { DPP4(x, y, z, w, "quad_perm:[1,0,3,2]", "s_nop 1"); DPP4(x, y, z, w, "quad_perm:[2,3,0,1]", ""); DPP4(x, y, z, w, "row_half_mirror", ""); DPP4(x, y, z, w, "row_mirror", ""); } while (0)
; template <bool SAMPLE>
; __device__ __forceinline__ void rwkv_unit(PR P, LAS float* lds, const int b, const int h, const int half, const int wv) {
;     ...
;                 for (int tt = 0; tt < GS; ++tt) {
;                     const LAS float* qn = q0 + (tt + 1 < GS ? tt + 1 : tt) * 384;
;                     const f32x4 nr4 = *(const LAS f32x4*)(qn + j0), no4 = *(const LAS f32x4*)(qn + 64 + j0), nk4 = *(const LAS f32x4*)(qn + 128 + j0), na4 = *(const LAS f32x4*)(qn + 192 + j0), nb4 = *(const LAS f32x4*)(qn + 256 + j0);
;                     const f32x2 nv2 = *(const LAS f32x2*)(qn + 320 + row0);
;                     f32x2 sa = (S[0] * a4[0] + S[1] * a4[1]) + (S[2] * a4[2] + S[3] * a4[3]);
;                     float sx = sa.x, sy = sa.y; ROW16_SUM4(sx, sy, py0, py1); sa = (f32x2){sx, sy};
;                     if (tt > 0) { yk0 = cgl == tt - 1 ? py0 : yk0; yk1 = cgl == tt - 1 ? py1 : yk1; }
; #pragma unroll
;                     for (int c = 0; c < 4; ++c) { f32x2 t = S[c] - S[c] * o4[c]; t = t + sa * b4[c]; S[c] = t + v2 * k4[c]; }
;                     const f32x2 y = (S[0] * r4[0] + S[1] * r4[1]) + (S[2] * r4[2] + S[3] * r4[3]);
;                     py0 = y.x; py1 = y.y;
;                     r4 = nr4; o4 = no4; k4 = nk4; a4 = na4; b4 = nb4; v2 = nv2;
	v_mov_b32_dpp v151, v150 row_ror:8 row_mask:0xf bank_mask:0xf bound_ctrl:1
	v_pk_fma_f32 v[66:67], v[150:151], v[236:237], v[142:143] op_sel_hi:[1,0,1]
	v_pk_fma_f32 v[20:21], v[150:151], v[236:237], v[144:145] op_sel:[0,1,0]
	v_pk_fma_f32 v[68:69], v[150:151], v[238:239], v[146:147] op_sel_hi:[1,0,1]
	v_pk_fma_f32 v[70:71], v[150:151], v[238:239], v[148:149] op_sel:[0,1,0]
	v_pk_mul_f32 v[92:93], v[66:67], v[220:221] op_sel_hi:[1,0]
	v_pk_mul_f32 v[150:151], v[66:67], v[172:173] op_sel_hi:[1,0]
	ds_read_b128 v[212:215], v152 offset:16128
	v_pk_fma_f32 v[92:93], v[20:21], v[220:221], v[92:93] op_sel:[0,1,0]
	v_pk_fma_f32 v[150:151], v[20:21], v[172:173], v[150:151] op_sel:[0,1,0]
	ds_read_b128 v[204:207], v152 offset:15616
	v_pk_fma_f32 v[92:93], v[68:69], v[222:223], v[92:93] op_sel_hi:[1,0,1]
	v_pk_fma_f32 v[150:151], v[68:69], v[174:175], v[150:151] op_sel_hi:[1,0,1]
	ds_read2st64_b64 v[248:251], v153 offset0:32 offset1:35
	v_pk_fma_f32 v[92:93], v[70:71], v[222:223], v[92:93] op_sel:[0,1,0]
	v_pk_fma_f32 v[150:151], v[70:71], v[174:175], v[150:151] op_sel:[0,1,0]
	ds_read_b128 v[208:211], v152 offset:15872
	v_pk_fma_f32 v[142:143], v[66:67], v[164:165], v[66:67] op_sel_hi:[1,0,1] neg_lo:[1,0,0] neg_hi:[1,0,0]
	v_pk_fma_f32 v[144:145], v[20:21], v[164:165], v[20:21] op_sel:[0,1,0] neg_lo:[1,0,0] neg_hi:[1,0,0]
	v_add_f32_dpp v150, v151, v150 row_ror:8 row_mask:0xf bank_mask:0xf bound_ctrl:1
	v_pk_fma_f32 v[146:147], v[68:69], v[166:167], v[68:69] op_sel_hi:[1,0,1] neg_lo:[1,0,0] neg_hi:[1,0,0]
	v_pk_fma_f32 v[148:149], v[70:71], v[166:167], v[70:71] op_sel:[0,1,0] neg_lo:[1,0,0] neg_hi:[1,0,0]
	v_add_f32_dpp v150, v150, v150 quad_perm:[1,0,3,2] row_mask:0xf bank_mask:0xf bound_ctrl:1
	v_pk_fma_f32 v[142:143], v[244:245], v[168:169], v[142:143] op_sel_hi:[1,0,1]
	v_pk_fma_f32 v[144:145], v[244:245], v[168:169], v[144:145] op_sel:[0,1,0]
	v_add_f32_dpp v150, v150, v150 quad_perm:[2,3,0,1] row_mask:0xf bank_mask:0xf bound_ctrl:1
	v_pk_fma_f32 v[146:147], v[244:245], v[170:171], v[146:147] op_sel_hi:[1,0,1]
	v_pk_fma_f32 v[148:149], v[244:245], v[170:171], v[148:149] op_sel:[0,1,0]
	v_add_f32_dpp v150, v150, v150 row_half_mirror row_mask:0xf bank_mask:0xf bound_ctrl:1
	ds_read_b128 v[232:235], v152 offset:17664
	ds_read_b128 v[224:227], v152 offset:17152
	v_mov_b32_dpp v151, v150 row_ror:8 row_mask:0xf bank_mask:0xf bound_ctrl:1
	ds_read_b128 v[216:219], v152 offset:16384
	ds_read_b128 v[228:231], v152 offset:17408
	ds_read_b128 v[236:239], v152 offset:17920
	ds_read_b128 v[200:203], v152 offset:15360
	ds_read_b128 v[220:223], v152 offset:16896
	v_pk_fma_f32 v[66:67], v[150:151], v[176:177], v[142:143] op_sel_hi:[1,0,1]
	v_pk_fma_f32 v[20:21], v[150:151], v[176:177], v[144:145] op_sel:[0,1,0]
	v_pk_fma_f32 v[68:69], v[150:151], v[178:179], v[146:147] op_sel_hi:[1,0,1]
	v_pk_fma_f32 v[70:71], v[150:151], v[178:179], v[148:149] op_sel:[0,1,0]
	v_pk_mul_f32 v[94:95], v[66:67], v[160:161] op_sel_hi:[1,0]
	v_pk_mul_f32 v[150:151], v[66:67], v[192:193] op_sel_hi:[1,0]
	v_pk_fma_f32 v[94:95], v[20:21], v[160:161], v[94:95] op_sel:[0,1,0]
	v_pk_fma_f32 v[150:151], v[20:21], v[192:193], v[150:151] op_sel:[0,1,0]
	v_pk_fma_f32 v[94:95], v[68:69], v[162:163], v[94:95] op_sel_hi:[1,0,1]
	v_pk_fma_f32 v[150:151], v[68:69], v[194:195], v[150:151] op_sel_hi:[1,0,1]
	v_pk_fma_f32 v[94:95], v[70:71], v[162:163], v[94:95] op_sel:[0,1,0]
	v_pk_fma_f32 v[150:151], v[70:71], v[194:195], v[150:151] op_sel:[0,1,0]
	v_pk_fma_f32 v[142:143], v[66:67], v[184:185], v[66:67] op_sel_hi:[1,0,1] neg_lo:[1,0,0] neg_hi:[1,0,0]
	v_pk_fma_f32 v[144:145], v[20:21], v[184:185], v[20:21] op_sel:[0,1,0] neg_lo:[1,0,0] neg_hi:[1,0,0]
	v_add_f32_dpp v150, v151, v150 row_ror:8 row_mask:0xf bank_mask:0xf bound_ctrl:1
	v_pk_fma_f32 v[146:147], v[68:69], v[186:187], v[68:69] op_sel_hi:[1,0,1] neg_lo:[1,0,0] neg_hi:[1,0,0]
	v_pk_fma_f32 v[148:149], v[70:71], v[186:187], v[70:71] op_sel:[0,1,0] neg_lo:[1,0,0] neg_hi:[1,0,0]
	v_add_f32_dpp v150, v150, v150 quad_perm:[1,0,3,2] row_mask:0xf bank_mask:0xf bound_ctrl:1
	v_pk_fma_f32 v[142:143], v[246:247], v[188:189], v[142:143] op_sel_hi:[1,0,1]
	v_pk_fma_f32 v[144:145], v[246:247], v[188:189], v[144:145] op_sel:[0,1,0]
	v_add_f32_dpp v150, v150, v150 quad_perm:[2,3,0,1] row_mask:0xf bank_mask:0xf bound_ctrl:1
	v_pk_fma_f32 v[146:147], v[246:247], v[190:191], v[146:147] op_sel_hi:[1,0,1]
	v_pk_fma_f32 v[148:149], v[246:247], v[190:191], v[148:149] op_sel:[0,1,0]
	v_add_f32_dpp v150, v150, v150 row_half_mirror row_mask:0xf bank_mask:0xf bound_ctrl:1
	s_nop 0
	s_waitcnt lgkmcnt(0)
; #define LAS __attribute__((address_space(3)))
; #define ROW16_SUM4(x, y, z, w) do { DPP4(x, y, z, w, "quad_perm:[1,0,3,2]", "s_nop 1"); DPP4(x, y, z, w, "quad_perm:[2,3,0,1]", ""); DPP4(x, y, z, w, "row_half_mirror", ""); DPP4(x, y, z, w, "row_mirror", ""); } while (0)
; template <bool SAMPLE>
; __device__ __forceinline__ void rwkv_unit(PR P, LAS float* lds, const int b, const int h, const int half, const int wv) {
;     ...
;                 for (int tt = 0; tt < GS; ++tt) {
;                     const LAS float* qn = q0 + (tt + 1 < GS ? tt + 1 : tt) * 384;
;                     const f32x4 nr4 = *(const LAS f32x4*)(qn + j0), no4 = *(const LAS f32x4*)(qn + 64 + j0), nk4 = *(const LAS f32x4*)(qn + 128 + j0), na4 = *(const LAS f32x4*)(qn + 192 + j0), nb4 = *(const LAS f32x4*)(qn + 256 + j0);
;                     const f32x2 nv2 = *(const LAS f32x2*)(qn + 320 + row0);
;                     f32x2 sa = (S[0] * a4[0] + S[1] * a4[1]) + (S[2] * a4[2] + S[3] * a4[3]);
;                     float sx = sa.x, sy = sa.y; ROW16_SUM4(sx, sy, py0, py1); sa = (f32x2){sx, sy};
;                     if (tt > 0) { yk0 = cgl == tt - 1 ? py0 : yk0; yk1 = cgl == tt - 1 ? py1 : yk1; }
; #pragma unroll
;                     for (int c = 0; c < 4; ++c) { f32x2 t = S[c] - S[c] * o4[c]; t = t + sa * b4[c]; S[c] = t + v2 * k4[c]; }
;                     const f32x2 y = (S[0] * r4[0] + S[1] * r4[1]) + (S[2] * r4[2] + S[3] * r4[3]);
;                     py0 = y.x; py1 = y.y;
;                     r4 = nr4; o4 = no4; k4 = nk4; a4 = na4; b4 = nb4; v2 = nv2;
	v_mov_b32_dpp v151, v150 row_ror:8 row_mask:0xf bank_mask:0xf bound_ctrl:1
	v_pk_fma_f32 v[66:67], v[150:151], v[196:197], v[142:143] op_sel_hi:[1,0,1]
	v_pk_fma_f32 v[20:21], v[150:151], v[196:197], v[144:145] op_sel:[0,1,0]
	v_pk_fma_f32 v[68:69], v[150:151], v[198:199], v[146:147] op_sel_hi:[1,0,1]
	v_pk_fma_f32 v[70:71], v[150:151], v[198:199], v[148:149] op_sel:[0,1,0]
	v_pk_mul_f32 v[96:97], v[66:67], v[180:181] op_sel_hi:[1,0]
	v_pk_mul_f32 v[150:151], v[66:67], v[212:213] op_sel_hi:[1,0]
	ds_read_b128 v[172:175], v152 offset:19200
	v_pk_fma_f32 v[96:97], v[20:21], v[180:181], v[96:97] op_sel:[0,1,0]
	v_pk_fma_f32 v[150:151], v[20:21], v[212:213], v[150:151] op_sel:[0,1,0]
	ds_read_b128 v[164:167], v152 offset:18688
	v_pk_fma_f32 v[96:97], v[68:69], v[182:183], v[96:97] op_sel_hi:[1,0,1]
	v_pk_fma_f32 v[150:151], v[68:69], v[214:215], v[150:151] op_sel_hi:[1,0,1]
	ds_read2st64_b64 v[240:243], v153 offset0:38 offset1:41
	v_pk_fma_f32 v[96:97], v[70:71], v[182:183], v[96:97] op_sel:[0,1,0]
	v_pk_fma_f32 v[150:151], v[70:71], v[214:215], v[150:151] op_sel:[0,1,0]
	ds_read_b128 v[168:171], v152 offset:18944
	v_pk_fma_f32 v[142:143], v[66:67], v[204:205], v[66:67] op_sel_hi:[1,0,1] neg_lo:[1,0,0] neg_hi:[1,0,0]
	v_pk_fma_f32 v[144:145], v[20:21], v[204:205], v[20:21] op_sel:[0,1,0] neg_lo:[1,0,0] neg_hi:[1,0,0]
	v_add_f32_dpp v150, v151, v150 row_ror:8 row_mask:0xf bank_mask:0xf bound_ctrl:1
	v_pk_fma_f32 v[146:147], v[68:69], v[206:207], v[68:69] op_sel_hi:[1,0,1] neg_lo:[1,0,0] neg_hi:[1,0,0]
	v_pk_fma_f32 v[148:149], v[70:71], v[206:207], v[70:71] op_sel:[0,1,0] neg_lo:[1,0,0] neg_hi:[1,0,0]
	v_add_f32_dpp v150, v150, v150 quad_perm:[1,0,3,2] row_mask:0xf bank_mask:0xf bound_ctrl:1
	v_pk_fma_f32 v[142:143], v[248:249], v[208:209], v[142:143] op_sel_hi:[1,0,1]
	v_pk_fma_f32 v[144:145], v[248:249], v[208:209], v[144:145] op_sel:[0,1,0]
	v_add_f32_dpp v150, v150, v150 quad_perm:[2,3,0,1] row_mask:0xf bank_mask:0xf bound_ctrl:1
	v_pk_fma_f32 v[146:147], v[248:249], v[210:211], v[146:147] op_sel_hi:[1,0,1]
	v_pk_fma_f32 v[148:149], v[248:249], v[210:211], v[148:149] op_sel:[0,1,0]
	v_add_f32_dpp v150, v150, v150 row_half_mirror row_mask:0xf bank_mask:0xf bound_ctrl:1
	ds_read_b128 v[192:195], v152 offset:20736
	ds_read_b128 v[184:187], v152 offset:20224
	v_mov_b32_dpp v151, v150 row_ror:8 row_mask:0xf bank_mask:0xf bound_ctrl:1
	ds_read_b128 v[176:179], v152 offset:19456
	ds_read_b128 v[188:191], v152 offset:20480
	ds_read_b128 v[196:199], v152 offset:20992
	ds_read_b128 v[160:163], v152 offset:18432
	ds_read_b128 v[180:183], v152 offset:19968
	v_pk_fma_f32 v[66:67], v[150:151], v[216:217], v[142:143] op_sel_hi:[1,0,1]
	v_pk_fma_f32 v[20:21], v[150:151], v[216:217], v[144:145] op_sel:[0,1,0]
	v_pk_fma_f32 v[68:69], v[150:151], v[218:219], v[146:147] op_sel_hi:[1,0,1]
	v_pk_fma_f32 v[70:71], v[150:151], v[218:219], v[148:149] op_sel:[0,1,0]
	v_pk_mul_f32 v[98:99], v[66:67], v[200:201] op_sel_hi:[1,0]
	v_pk_mul_f32 v[150:151], v[66:67], v[232:233] op_sel_hi:[1,0]
	v_pk_fma_f32 v[98:99], v[20:21], v[200:201], v[98:99] op_sel:[0,1,0]
	v_pk_fma_f32 v[150:151], v[20:21], v[232:233], v[150:151] op_sel:[0,1,0]
	v_pk_fma_f32 v[98:99], v[68:69], v[202:203], v[98:99] op_sel_hi:[1,0,1]
	v_pk_fma_f32 v[150:151], v[68:69], v[234:235], v[150:151] op_sel_hi:[1,0,1]
	v_pk_fma_f32 v[98:99], v[70:71], v[202:203], v[98:99] op_sel:[0,1,0]
	v_pk_fma_f32 v[150:151], v[70:71], v[234:235], v[150:151] op_sel:[0,1,0]
	v_pk_fma_f32 v[142:143], v[66:67], v[224:225], v[66:67] op_sel_hi:[1,0,1] neg_lo:[1,0,0] neg_hi:[1,0,0]
	v_pk_fma_f32 v[144:145], v[20:21], v[224:225], v[20:21] op_sel:[0,1,0] neg_lo:[1,0,0] neg_hi:[1,0,0]
	v_add_f32_dpp v150, v151, v150 row_ror:8 row_mask:0xf bank_mask:0xf bound_ctrl:1
	v_pk_fma_f32 v[146:147], v[68:69], v[226:227], v[68:69] op_sel_hi:[1,0,1] neg_lo:[1,0,0] neg_hi:[1,0,0]
	v_pk_fma_f32 v[148:149], v[70:71], v[226:227], v[70:71] op_sel:[0,1,0] neg_lo:[1,0,0] neg_hi:[1,0,0]
	v_add_f32_dpp v150, v150, v150 quad_perm:[1,0,3,2] row_mask:0xf bank_mask:0xf bound_ctrl:1
	v_pk_fma_f32 v[142:143], v[250:251], v[228:229], v[142:143] op_sel_hi:[1,0,1]
	v_pk_fma_f32 v[144:145], v[250:251], v[228:229], v[144:145] op_sel:[0,1,0]
	v_add_f32_dpp v150, v150, v150 quad_perm:[2,3,0,1] row_mask:0xf bank_mask:0xf bound_ctrl:1
	v_pk_fma_f32 v[146:147], v[250:251], v[230:231], v[146:147] op_sel_hi:[1,0,1]
	v_pk_fma_f32 v[148:149], v[250:251], v[230:231], v[148:149] op_sel:[0,1,0]
	v_add_f32_dpp v150, v150, v150 row_half_mirror row_mask:0xf bank_mask:0xf bound_ctrl:1
	s_nop 0
	s_waitcnt lgkmcnt(0)
; #define LAS __attribute__((address_space(3)))
; #define ROW16_SUM4(x, y, z, w) do { DPP4(x, y, z, w, "quad_perm:[1,0,3,2]", "s_nop 1"); DPP4(x, y, z, w, "quad_perm:[2,3,0,1]", ""); DPP4(x, y, z, w, "row_half_mirror", ""); DPP4(x, y, z, w, "row_mirror", ""); } while (0)
; template <bool SAMPLE>
; __device__ __forceinline__ void rwkv_unit(PR P, LAS float* lds, const int b, const int h, const int half, const int wv) {
;     ...
;                 for (int tt = 0; tt < GS; ++tt) {
;                     const LAS float* qn = q0 + (tt + 1 < GS ? tt + 1 : tt) * 384;
;                     const f32x4 nr4 = *(const LAS f32x4*)(qn + j0), no4 = *(const LAS f32x4*)(qn + 64 + j0), nk4 = *(const LAS f32x4*)(qn + 128 + j0), na4 = *(const LAS f32x4*)(qn + 192 + j0), nb4 = *(const LAS f32x4*)(qn + 256 + j0);
;                     const f32x2 nv2 = *(const LAS f32x2*)(qn + 320 + row0);
;                     f32x2 sa = (S[0] * a4[0] + S[1] * a4[1]) + (S[2] * a4[2] + S[3] * a4[3]);
;                     float sx = sa.x, sy = sa.y; ROW16_SUM4(sx, sy, py0, py1); sa = (f32x2){sx, sy};
;                     if (tt > 0) { yk0 = cgl == tt - 1 ? py0 : yk0; yk1 = cgl == tt - 1 ? py1 : yk1; }
; #pragma unroll
;                     for (int c = 0; c < 4; ++c) { f32x2 t = S[c] - S[c] * o4[c]; t = t + sa * b4[c]; S[c] = t + v2 * k4[c]; }
;                     const f32x2 y = (S[0] * r4[0] + S[1] * r4[1]) + (S[2] * r4[2] + S[3] * r4[3]);
;                     py0 = y.x; py1 = y.y;
;                     r4 = nr4; o4 = no4; k4 = nk4; a4 = na4; b4 = nb4; v2 = nv2;
	v_mov_b32_dpp v151, v150 row_ror:8 row_mask:0xf bank_mask:0xf bound_ctrl:1
	v_pk_fma_f32 v[66:67], v[150:151], v[236:237], v[142:143] op_sel_hi:[1,0,1]
	v_pk_fma_f32 v[20:21], v[150:151], v[236:237], v[144:145] op_sel:[0,1,0]
	v_pk_fma_f32 v[68:69], v[150:151], v[238:239], v[146:147] op_sel_hi:[1,0,1]
	v_pk_fma_f32 v[70:71], v[150:151], v[238:239], v[148:149] op_sel:[0,1,0]
	v_pk_mul_f32 v[100:101], v[66:67], v[220:221] op_sel_hi:[1,0]
	v_pk_mul_f32 v[150:151], v[66:67], v[172:173] op_sel_hi:[1,0]
	ds_read_b128 v[212:215], v152 offset:22272
	v_pk_fma_f32 v[100:101], v[20:21], v[220:221], v[100:101] op_sel:[0,1,0]
	v_pk_fma_f32 v[150:151], v[20:21], v[172:173], v[150:151] op_sel:[0,1,0]
	ds_read_b128 v[204:207], v152 offset:21760
	v_pk_fma_f32 v[100:101], v[68:69], v[222:223], v[100:101] op_sel_hi:[1,0,1]
	v_pk_fma_f32 v[150:151], v[68:69], v[174:175], v[150:151] op_sel_hi:[1,0,1]
	ds_read2st64_b64 v[244:247], v153 offset0:44 offset1:47
	v_pk_fma_f32 v[100:101], v[70:71], v[222:223], v[100:101] op_sel:[0,1,0]
	v_pk_fma_f32 v[150:151], v[70:71], v[174:175], v[150:151] op_sel:[0,1,0]
	ds_read_b128 v[208:211], v152 offset:22016
	v_pk_fma_f32 v[142:143], v[66:67], v[164:165], v[66:67] op_sel_hi:[1,0,1] neg_lo:[1,0,0] neg_hi:[1,0,0]
	v_pk_fma_f32 v[144:145], v[20:21], v[164:165], v[20:21] op_sel:[0,1,0] neg_lo:[1,0,0] neg_hi:[1,0,0]
	v_add_f32_dpp v150, v151, v150 row_ror:8 row_mask:0xf bank_mask:0xf bound_ctrl:1
	v_pk_fma_f32 v[146:147], v[68:69], v[166:167], v[68:69] op_sel_hi:[1,0,1] neg_lo:[1,0,0] neg_hi:[1,0,0]
	v_pk_fma_f32 v[148:149], v[70:71], v[166:167], v[70:71] op_sel:[0,1,0] neg_lo:[1,0,0] neg_hi:[1,0,0]
	v_add_f32_dpp v150, v150, v150 quad_perm:[1,0,3,2] row_mask:0xf bank_mask:0xf bound_ctrl:1
	v_pk_fma_f32 v[142:143], v[240:241], v[168:169], v[142:143] op_sel_hi:[1,0,1]
	v_pk_fma_f32 v[144:145], v[240:241], v[168:169], v[144:145] op_sel:[0,1,0]
	v_add_f32_dpp v150, v150, v150 quad_perm:[2,3,0,1] row_mask:0xf bank_mask:0xf bound_ctrl:1
	v_pk_fma_f32 v[146:147], v[240:241], v[170:171], v[146:147] op_sel_hi:[1,0,1]
	v_pk_fma_f32 v[148:149], v[240:241], v[170:171], v[148:149] op_sel:[0,1,0]
	v_add_f32_dpp v150, v150, v150 row_half_mirror row_mask:0xf bank_mask:0xf bound_ctrl:1
	ds_read_b128 v[232:235], v152 offset:23808
	ds_read_b128 v[224:227], v152 offset:23296
	v_mov_b32_dpp v151, v150 row_ror:8 row_mask:0xf bank_mask:0xf bound_ctrl:1
	ds_read_b128 v[216:219], v152 offset:22528
	ds_read_b128 v[228:231], v152 offset:23552
	ds_read_b128 v[236:239], v152 offset:24064
	ds_read_b128 v[200:203], v152 offset:21504
	ds_read_b128 v[220:223], v152 offset:23040
	v_pk_fma_f32 v[66:67], v[150:151], v[176:177], v[142:143] op_sel_hi:[1,0,1]
	v_pk_fma_f32 v[20:21], v[150:151], v[176:177], v[144:145] op_sel:[0,1,0]
	v_pk_fma_f32 v[68:69], v[150:151], v[178:179], v[146:147] op_sel_hi:[1,0,1]
	v_pk_fma_f32 v[70:71], v[150:151], v[178:179], v[148:149] op_sel:[0,1,0]
	v_pk_mul_f32 v[102:103], v[66:67], v[160:161] op_sel_hi:[1,0]
	v_pk_mul_f32 v[150:151], v[66:67], v[192:193] op_sel_hi:[1,0]
	v_pk_fma_f32 v[102:103], v[20:21], v[160:161], v[102:103] op_sel:[0,1,0]
	v_pk_fma_f32 v[150:151], v[20:21], v[192:193], v[150:151] op_sel:[0,1,0]
	v_pk_fma_f32 v[102:103], v[68:69], v[162:163], v[102:103] op_sel_hi:[1,0,1]
	v_pk_fma_f32 v[150:151], v[68:69], v[194:195], v[150:151] op_sel_hi:[1,0,1]
	v_pk_fma_f32 v[102:103], v[70:71], v[162:163], v[102:103] op_sel:[0,1,0]
	v_pk_fma_f32 v[150:151], v[70:71], v[194:195], v[150:151] op_sel:[0,1,0]
	v_pk_fma_f32 v[142:143], v[66:67], v[184:185], v[66:67] op_sel_hi:[1,0,1] neg_lo:[1,0,0] neg_hi:[1,0,0]
	v_pk_fma_f32 v[144:145], v[20:21], v[184:185], v[20:21] op_sel:[0,1,0] neg_lo:[1,0,0] neg_hi:[1,0,0]
	v_add_f32_dpp v150, v151, v150 row_ror:8 row_mask:0xf bank_mask:0xf bound_ctrl:1
	v_pk_fma_f32 v[146:147], v[68:69], v[186:187], v[68:69] op_sel_hi:[1,0,1] neg_lo:[1,0,0] neg_hi:[1,0,0]
	v_pk_fma_f32 v[148:149], v[70:71], v[186:187], v[70:71] op_sel:[0,1,0] neg_lo:[1,0,0] neg_hi:[1,0,0]
	v_add_f32_dpp v150, v150, v150 quad_perm:[1,0,3,2] row_mask:0xf bank_mask:0xf bound_ctrl:1
	v_pk_fma_f32 v[142:143], v[242:243], v[188:189], v[142:143] op_sel_hi:[1,0,1]
	v_pk_fma_f32 v[144:145], v[242:243], v[188:189], v[144:145] op_sel:[0,1,0]
	v_add_f32_dpp v150, v150, v150 quad_perm:[2,3,0,1] row_mask:0xf bank_mask:0xf bound_ctrl:1
	v_pk_fma_f32 v[146:147], v[242:243], v[190:191], v[146:147] op_sel_hi:[1,0,1]
	v_pk_fma_f32 v[148:149], v[242:243], v[190:191], v[148:149] op_sel:[0,1,0]
	v_add_f32_dpp v150, v150, v150 row_half_mirror row_mask:0xf bank_mask:0xf bound_ctrl:1
	s_nop 0
	s_waitcnt lgkmcnt(0)
; #define LAS __attribute__((address_space(3)))
; #define ROW16_SUM4(x, y, z, w) do { DPP4(x, y, z, w, "quad_perm:[1,0,3,2]", "s_nop 1"); DPP4(x, y, z, w, "quad_perm:[2,3,0,1]", ""); DPP4(x, y, z, w, "row_half_mirror", ""); DPP4(x, y, z, w, "row_mirror", ""); } while (0)
; template <bool SAMPLE>
; __device__ __forceinline__ void rwkv_unit(PR P, LAS float* lds, const int b, const int h, const int half, const int wv) {
;     ...
;                 for (int tt = 0; tt < GS; ++tt) {
;                     const LAS float* qn = q0 + (tt + 1 < GS ? tt + 1 : tt) * 384;
;                     const f32x4 nr4 = *(const LAS f32x4*)(qn + j0), no4 = *(const LAS f32x4*)(qn + 64 + j0), nk4 = *(const LAS f32x4*)(qn + 128 + j0), na4 = *(const LAS f32x4*)(qn + 192 + j0), nb4 = *(const LAS f32x4*)(qn + 256 + j0);
;                     const f32x2 nv2 = *(const LAS f32x2*)(qn + 320 + row0);
;                     f32x2 sa = (S[0] * a4[0] + S[1] * a4[1]) + (S[2] * a4[2] + S[3] * a4[3]);
;                     float sx = sa.x, sy = sa.y; ROW16_SUM4(sx, sy, py0, py1); sa = (f32x2){sx, sy};
;                     if (tt > 0) { yk0 = cgl == tt - 1 ? py0 : yk0; yk1 = cgl == tt - 1 ? py1 : yk1; }
; #pragma unroll
;                     for (int c = 0; c < 4; ++c) { f32x2 t = S[c] - S[c] * o4[c]; t = t + sa * b4[c]; S[c] = t + v2 * k4[c]; }
;                     const f32x2 y = (S[0] * r4[0] + S[1] * r4[1]) + (S[2] * r4[2] + S[3] * r4[3]);
;                     py0 = y.x; py1 = y.y;
;                     r4 = nr4; o4 = no4; k4 = nk4; a4 = na4; b4 = nb4; v2 = nv2;
	v_mov_b32_dpp v151, v150 row_ror:8 row_mask:0xf bank_mask:0xf bound_ctrl:1
	v_pk_fma_f32 v[66:67], v[150:151], v[196:197], v[142:143] op_sel_hi:[1,0,1]
	v_pk_fma_f32 v[20:21], v[150:151], v[196:197], v[144:145] op_sel:[0,1,0]
	v_pk_fma_f32 v[68:69], v[150:151], v[198:199], v[146:147] op_sel_hi:[1,0,1]
	v_pk_fma_f32 v[70:71], v[150:151], v[198:199], v[148:149] op_sel:[0,1,0]
	v_pk_mul_f32 v[104:105], v[66:67], v[180:181] op_sel_hi:[1,0]
	v_pk_mul_f32 v[150:151], v[66:67], v[212:213] op_sel_hi:[1,0]
	ds_read_b128 v[172:175], v152 offset:25344
	v_pk_fma_f32 v[104:105], v[20:21], v[180:181], v[104:105] op_sel:[0,1,0]
	v_pk_fma_f32 v[150:151], v[20:21], v[212:213], v[150:151] op_sel:[0,1,0]
	ds_read_b128 v[164:167], v152 offset:24832
	v_pk_fma_f32 v[104:105], v[68:69], v[182:183], v[104:105] op_sel_hi:[1,0,1]
	v_pk_fma_f32 v[150:151], v[68:69], v[214:215], v[150:151] op_sel_hi:[1,0,1]
	ds_read2st64_b64 v[248:251], v153 offset0:50 offset1:53
	v_pk_fma_f32 v[104:105], v[70:71], v[182:183], v[104:105] op_sel:[0,1,0]
	v_pk_fma_f32 v[150:151], v[70:71], v[214:215], v[150:151] op_sel:[0,1,0]
	ds_read_b128 v[168:171], v152 offset:25088
	v_pk_fma_f32 v[142:143], v[66:67], v[204:205], v[66:67] op_sel_hi:[1,0,1] neg_lo:[1,0,0] neg_hi:[1,0,0]
	v_pk_fma_f32 v[144:145], v[20:21], v[204:205], v[20:21] op_sel:[0,1,0] neg_lo:[1,0,0] neg_hi:[1,0,0]
	v_add_f32_dpp v150, v151, v150 row_ror:8 row_mask:0xf bank_mask:0xf bound_ctrl:1
	v_pk_fma_f32 v[146:147], v[68:69], v[206:207], v[68:69] op_sel_hi:[1,0,1] neg_lo:[1,0,0] neg_hi:[1,0,0]
	v_pk_fma_f32 v[148:149], v[70:71], v[206:207], v[70:71] op_sel:[0,1,0] neg_lo:[1,0,0] neg_hi:[1,0,0]
	v_add_f32_dpp v150, v150, v150 quad_perm:[1,0,3,2] row_mask:0xf bank_mask:0xf bound_ctrl:1
	v_pk_fma_f32 v[142:143], v[244:245], v[208:209], v[142:143] op_sel_hi:[1,0,1]
	v_pk_fma_f32 v[144:145], v[244:245], v[208:209], v[144:145] op_sel:[0,1,0]
	v_add_f32_dpp v150, v150, v150 quad_perm:[2,3,0,1] row_mask:0xf bank_mask:0xf bound_ctrl:1
	v_pk_fma_f32 v[146:147], v[244:245], v[210:211], v[146:147] op_sel_hi:[1,0,1]
	v_pk_fma_f32 v[148:149], v[244:245], v[210:211], v[148:149] op_sel:[0,1,0]
	v_add_f32_dpp v150, v150, v150 row_half_mirror row_mask:0xf bank_mask:0xf bound_ctrl:1
	ds_read_b128 v[192:195], v152 offset:26880
	ds_read_b128 v[184:187], v152 offset:26368
	v_mov_b32_dpp v151, v150 row_ror:8 row_mask:0xf bank_mask:0xf bound_ctrl:1
	ds_read_b128 v[176:179], v152 offset:25600
	ds_read_b128 v[188:191], v152 offset:26624
	ds_read_b128 v[196:199], v152 offset:27136
	ds_read_b128 v[160:163], v152 offset:24576
	ds_read_b128 v[180:183], v152 offset:26112
	v_pk_fma_f32 v[66:67], v[150:151], v[216:217], v[142:143] op_sel_hi:[1,0,1]
	v_pk_fma_f32 v[20:21], v[150:151], v[216:217], v[144:145] op_sel:[0,1,0]
	v_pk_fma_f32 v[68:69], v[150:151], v[218:219], v[146:147] op_sel_hi:[1,0,1]
	v_pk_fma_f32 v[70:71], v[150:151], v[218:219], v[148:149] op_sel:[0,1,0]
	v_pk_mul_f32 v[106:107], v[66:67], v[200:201] op_sel_hi:[1,0]
	v_pk_mul_f32 v[150:151], v[66:67], v[232:233] op_sel_hi:[1,0]
	v_pk_fma_f32 v[106:107], v[20:21], v[200:201], v[106:107] op_sel:[0,1,0]
	v_pk_fma_f32 v[150:151], v[20:21], v[232:233], v[150:151] op_sel:[0,1,0]
	v_pk_fma_f32 v[106:107], v[68:69], v[202:203], v[106:107] op_sel_hi:[1,0,1]
	v_pk_fma_f32 v[150:151], v[68:69], v[234:235], v[150:151] op_sel_hi:[1,0,1]
	v_pk_fma_f32 v[106:107], v[70:71], v[202:203], v[106:107] op_sel:[0,1,0]
	v_pk_fma_f32 v[150:151], v[70:71], v[234:235], v[150:151] op_sel:[0,1,0]
	v_pk_fma_f32 v[142:143], v[66:67], v[224:225], v[66:67] op_sel_hi:[1,0,1] neg_lo:[1,0,0] neg_hi:[1,0,0]
	v_pk_fma_f32 v[144:145], v[20:21], v[224:225], v[20:21] op_sel:[0,1,0] neg_lo:[1,0,0] neg_hi:[1,0,0]
	v_add_f32_dpp v150, v151, v150 row_ror:8 row_mask:0xf bank_mask:0xf bound_ctrl:1
	v_pk_fma_f32 v[146:147], v[68:69], v[226:227], v[68:69] op_sel_hi:[1,0,1] neg_lo:[1,0,0] neg_hi:[1,0,0]
	v_pk_fma_f32 v[148:149], v[70:71], v[226:227], v[70:71] op_sel:[0,1,0] neg_lo:[1,0,0] neg_hi:[1,0,0]
	v_add_f32_dpp v150, v150, v150 quad_perm:[1,0,3,2] row_mask:0xf bank_mask:0xf bound_ctrl:1
	v_pk_fma_f32 v[142:143], v[246:247], v[228:229], v[142:143] op_sel_hi:[1,0,1]
	v_pk_fma_f32 v[144:145], v[246:247], v[228:229], v[144:145] op_sel:[0,1,0]
	v_add_f32_dpp v150, v150, v150 quad_perm:[2,3,0,1] row_mask:0xf bank_mask:0xf bound_ctrl:1
	v_pk_fma_f32 v[146:147], v[246:247], v[230:231], v[146:147] op_sel_hi:[1,0,1]
	v_pk_fma_f32 v[148:149], v[246:247], v[230:231], v[148:149] op_sel:[0,1,0]
	v_add_f32_dpp v150, v150, v150 row_half_mirror row_mask:0xf bank_mask:0xf bound_ctrl:1
	s_nop 0
	s_waitcnt lgkmcnt(0)
; #define LAS __attribute__((address_space(3)))
; #define ROW16_SUM4(x, y, z, w) do { DPP4(x, y, z, w, "quad_perm:[1,0,3,2]", "s_nop 1"); DPP4(x, y, z, w, "quad_perm:[2,3,0,1]", ""); DPP4(x, y, z, w, "row_half_mirror", ""); DPP4(x, y, z, w, "row_mirror", ""); } while (0)
; #define ROW16_SUM2(x, y) do { DPP2(x, y, "quad_perm:[1,0,3,2]", "s_nop 1"); DPP2(x, y, "quad_perm:[2,3,0,1]", "s_nop 0"); DPP2(x, y, "row_half_mirror", "s_nop 0"); DPP2(x, y, "row_mirror", "s_nop 0"); } while (0)
; template <bool SAMPLE>
; __device__ __forceinline__ void rwkv_unit(PR P, LAS float* lds, const int b, const int h, const int half, const int wv) {
;     ...
;                 for (int tt = 0; tt < GS; ++tt) {
;                     const LAS float* qn = q0 + (tt + 1 < GS ? tt + 1 : tt) * 384;
;                     const f32x4 nr4 = *(const LAS f32x4*)(qn + j0), no4 = *(const LAS f32x4*)(qn + 64 + j0), nk4 = *(const LAS f32x4*)(qn + 128 + j0), na4 = *(const LAS f32x4*)(qn + 192 + j0), nb4 = *(const LAS f32x4*)(qn + 256 + j0);
;                     const f32x2 nv2 = *(const LAS f32x2*)(qn + 320 + row0);
;                     f32x2 sa = (S[0] * a4[0] + S[1] * a4[1]) + (S[2] * a4[2] + S[3] * a4[3]);
;                     float sx = sa.x, sy = sa.y; ROW16_SUM4(sx, sy, py0, py1); sa = (f32x2){sx, sy};
;                     if (tt > 0) { yk0 = cgl == tt - 1 ? py0 : yk0; yk1 = cgl == tt - 1 ? py1 : yk1; }
; #pragma unroll
;                     for (int c = 0; c < 4; ++c) { f32x2 t = S[c] - S[c] * o4[c]; t = t + sa * b4[c]; S[c] = t + v2 * k4[c]; }
;                     const f32x2 y = (S[0] * r4[0] + S[1] * r4[1]) + (S[2] * r4[2] + S[3] * r4[3]);
;                     py0 = y.x; py1 = y.y;
;                     r4 = nr4; o4 = no4; k4 = nk4; a4 = na4; b4 = nb4; v2 = nv2;
;                 }
;                 ROW16_SUM2(py0, py1); yk0 = cgl == GS - 1 ? py0 : yk0; yk1 = cgl == GS - 1 ? py1 : yk1;
	v_mov_b32_dpp v151, v150 row_ror:8 row_mask:0xf bank_mask:0xf bound_ctrl:1
	v_pk_fma_f32 v[66:67], v[150:151], v[236:237], v[142:143] op_sel_hi:[1,0,1]
	v_pk_fma_f32 v[20:21], v[150:151], v[236:237], v[144:145] op_sel:[0,1,0]
	v_pk_fma_f32 v[68:69], v[150:151], v[238:239], v[146:147] op_sel_hi:[1,0,1]
	v_pk_fma_f32 v[70:71], v[150:151], v[238:239], v[148:149] op_sel:[0,1,0]
	v_pk_mul_f32 v[108:109], v[66:67], v[220:221] op_sel_hi:[1,0]
	v_pk_mul_f32 v[150:151], v[66:67], v[172:173] op_sel_hi:[1,0]
	ds_read_b128 v[212:215], v152 offset:28416
	v_pk_fma_f32 v[108:109], v[20:21], v[220:221], v[108:109] op_sel:[0,1,0]
	v_pk_fma_f32 v[150:151], v[20:21], v[172:173], v[150:151] op_sel:[0,1,0]
	ds_read_b128 v[204:207], v152 offset:27904
	v_pk_fma_f32 v[108:109], v[68:69], v[222:223], v[108:109] op_sel_hi:[1,0,1]
	v_pk_fma_f32 v[150:151], v[68:69], v[174:175], v[150:151] op_sel_hi:[1,0,1]
	ds_read2st64_b64 v[240:243], v153 offset0:56 offset1:59
	v_pk_fma_f32 v[108:109], v[70:71], v[222:223], v[108:109] op_sel:[0,1,0]
	v_pk_fma_f32 v[150:151], v[70:71], v[174:175], v[150:151] op_sel:[0,1,0]
	ds_read_b128 v[208:211], v152 offset:28160
	v_pk_fma_f32 v[142:143], v[66:67], v[164:165], v[66:67] op_sel_hi:[1,0,1] neg_lo:[1,0,0] neg_hi:[1,0,0]
	v_pk_fma_f32 v[144:145], v[20:21], v[164:165], v[20:21] op_sel:[0,1,0] neg_lo:[1,0,0] neg_hi:[1,0,0]
	v_add_f32_dpp v150, v151, v150 row_ror:8 row_mask:0xf bank_mask:0xf bound_ctrl:1
	v_pk_fma_f32 v[146:147], v[68:69], v[166:167], v[68:69] op_sel_hi:[1,0,1] neg_lo:[1,0,0] neg_hi:[1,0,0]
	v_pk_fma_f32 v[148:149], v[70:71], v[166:167], v[70:71] op_sel:[0,1,0] neg_lo:[1,0,0] neg_hi:[1,0,0]
	v_add_f32_dpp v150, v150, v150 quad_perm:[1,0,3,2] row_mask:0xf bank_mask:0xf bound_ctrl:1
	v_pk_fma_f32 v[142:143], v[248:249], v[168:169], v[142:143] op_sel_hi:[1,0,1]
	v_pk_fma_f32 v[144:145], v[248:249], v[168:169], v[144:145] op_sel:[0,1,0]
	v_add_f32_dpp v150, v150, v150 quad_perm:[2,3,0,1] row_mask:0xf bank_mask:0xf bound_ctrl:1
	v_pk_fma_f32 v[146:147], v[248:249], v[170:171], v[146:147] op_sel_hi:[1,0,1]
	v_pk_fma_f32 v[148:149], v[248:249], v[170:171], v[148:149] op_sel:[0,1,0]
	v_add_f32_dpp v150, v150, v150 row_half_mirror row_mask:0xf bank_mask:0xf bound_ctrl:1
	ds_read_b128 v[232:235], v152 offset:29952
	ds_read_b128 v[224:227], v152 offset:29440
	v_mov_b32_dpp v151, v150 row_ror:8 row_mask:0xf bank_mask:0xf bound_ctrl:1
	ds_read_b128 v[216:219], v152 offset:28672
	ds_read_b128 v[228:231], v152 offset:29696
	ds_read_b128 v[236:239], v152 offset:30208
	ds_read_b128 v[200:203], v152 offset:27648
	ds_read_b128 v[220:223], v152 offset:29184
	v_pk_fma_f32 v[66:67], v[150:151], v[176:177], v[142:143] op_sel_hi:[1,0,1]
	v_pk_fma_f32 v[20:21], v[150:151], v[176:177], v[144:145] op_sel:[0,1,0]
	v_pk_fma_f32 v[68:69], v[150:151], v[178:179], v[146:147] op_sel_hi:[1,0,1]
	v_pk_fma_f32 v[70:71], v[150:151], v[178:179], v[148:149] op_sel:[0,1,0]
	v_add_f32_dpp v78, v79, v78 row_ror:8 row_mask:0xf bank_mask:0x3 bound_ctrl:1
	v_add_f32_dpp v80, v81, v80 row_ror:8 row_mask:0xf bank_mask:0x3 bound_ctrl:1
	v_add_f32_dpp v82, v83, v82 row_ror:8 row_mask:0xf bank_mask:0x3 bound_ctrl:1
	v_add_f32_dpp v84, v85, v84 row_ror:8 row_mask:0xf bank_mask:0x3 bound_ctrl:1
	v_add_f32_dpp v86, v87, v86 row_ror:8 row_mask:0xf bank_mask:0x3 bound_ctrl:1
	v_add_f32_dpp v88, v89, v88 row_ror:8 row_mask:0xf bank_mask:0x3 bound_ctrl:1
	v_add_f32_dpp v90, v91, v90 row_ror:8 row_mask:0xf bank_mask:0x3 bound_ctrl:1
	v_add_f32_dpp v92, v93, v92 row_ror:8 row_mask:0xf bank_mask:0x3 bound_ctrl:1
	v_add_f32_dpp v79, v78, v79 row_ror:8 row_mask:0xf bank_mask:0x3 bound_ctrl:1
	v_add_f32_dpp v81, v80, v81 row_ror:8 row_mask:0xf bank_mask:0x3 bound_ctrl:1
	v_add_f32_dpp v83, v82, v83 row_ror:8 row_mask:0xf bank_mask:0x3 bound_ctrl:1
	v_add_f32_dpp v85, v84, v85 row_ror:8 row_mask:0xf bank_mask:0x3 bound_ctrl:1
	v_add_f32_dpp v87, v86, v87 row_ror:8 row_mask:0xf bank_mask:0x3 bound_ctrl:1
	v_add_f32_dpp v89, v88, v89 row_ror:8 row_mask:0xf bank_mask:0x3 bound_ctrl:1
	v_add_f32_dpp v91, v90, v91 row_ror:8 row_mask:0xf bank_mask:0x3 bound_ctrl:1
	v_add_f32_dpp v93, v92, v93 row_ror:8 row_mask:0xf bank_mask:0x3 bound_ctrl:1
	v_add_f32_dpp v78, v95, v94 row_ror:8 row_mask:0xf bank_mask:0xc bound_ctrl:1
	v_add_f32_dpp v80, v97, v96 row_ror:8 row_mask:0xf bank_mask:0xc bound_ctrl:1
	v_add_f32_dpp v82, v99, v98 row_ror:8 row_mask:0xf bank_mask:0xc bound_ctrl:1
	v_add_f32_dpp v84, v101, v100 row_ror:8 row_mask:0xf bank_mask:0xc bound_ctrl:1
	v_add_f32_dpp v86, v103, v102 row_ror:8 row_mask:0xf bank_mask:0xc bound_ctrl:1
	v_add_f32_dpp v88, v105, v104 row_ror:8 row_mask:0xf bank_mask:0xc bound_ctrl:1
	v_add_f32_dpp v90, v107, v106 row_ror:8 row_mask:0xf bank_mask:0xc bound_ctrl:1
	v_add_f32_dpp v92, v109, v108 row_ror:8 row_mask:0xf bank_mask:0xc bound_ctrl:1
	v_add_f32_dpp v79, v94, v95 row_ror:8 row_mask:0xf bank_mask:0xc bound_ctrl:1
	v_add_f32_dpp v81, v96, v97 row_ror:8 row_mask:0xf bank_mask:0xc bound_ctrl:1
	v_add_f32_dpp v83, v98, v99 row_ror:8 row_mask:0xf bank_mask:0xc bound_ctrl:1
	v_add_f32_dpp v85, v100, v101 row_ror:8 row_mask:0xf bank_mask:0xc bound_ctrl:1
	v_add_f32_dpp v87, v102, v103 row_ror:8 row_mask:0xf bank_mask:0xc bound_ctrl:1
	v_add_f32_dpp v89, v104, v105 row_ror:8 row_mask:0xf bank_mask:0xc bound_ctrl:1
	v_add_f32_dpp v91, v106, v107 row_ror:8 row_mask:0xf bank_mask:0xc bound_ctrl:1
	v_add_f32_dpp v93, v108, v109 row_ror:8 row_mask:0xf bank_mask:0xc bound_ctrl:1
	v_add_f32_dpp v78, v78, v78 row_shl:4 row_mask:0xf bank_mask:0x5 bound_ctrl:1
	v_add_f32_dpp v78, v86, v86 row_shr:4 row_mask:0xf bank_mask:0xa bound_ctrl:1
; __device__ __forceinline__ unsigned cvt_pk_bf16(float lo, float hi) { const f32x2_t v = {lo, hi}; const bf16x2_t b = __builtin_convertvector(v, bf16x2_t); return __builtin_bit_cast(unsigned, b); }
; #define ROW16_SUM4(x, y, z, w) do { DPP4(x, y, z, w, "quad_perm:[1,0,3,2]", "s_nop 1"); DPP4(x, y, z, w, "quad_perm:[2,3,0,1]", ""); DPP4(x, y, z, w, "row_half_mirror", ""); DPP4(x, y, z, w, "row_mirror", ""); } while (0)
; #define ROW16_SUM2(x, y) do { DPP2(x, y, "quad_perm:[1,0,3,2]", "s_nop 1"); DPP2(x, y, "quad_perm:[2,3,0,1]", "s_nop 0"); DPP2(x, y, "row_half_mirror", "s_nop 0"); DPP2(x, y, "row_mirror", "s_nop 0"); } while (0)
; template <bool SAMPLE>
; __device__ __forceinline__ void rwkv_unit(PR P, LAS float* lds, const int b, const int h, const int half, const int wv) {
;     ...
;                     f32x2 sa = (S[0] * a4[0] + S[1] * a4[1]) + (S[2] * a4[2] + S[3] * a4[3]);
;                     float sx = sa.x, sy = sa.y; ROW16_SUM4(sx, sy, py0, py1); sa = (f32x2){sx, sy};
;                     if (tt > 0) { yk0 = cgl == tt - 1 ? py0 : yk0; yk1 = cgl == tt - 1 ? py1 : yk1; }
; #pragma unroll
;                     for (int c = 0; c < 4; ++c) { f32x2 t = S[c] - S[c] * o4[c]; t = t + sa * b4[c]; S[c] = t + v2 * k4[c]; }
;                     const f32x2 y = (S[0] * r4[0] + S[1] * r4[1]) + (S[2] * r4[2] + S[3] * r4[3]);
;                     py0 = y.x; py1 = y.y;
;                     r4 = nr4; o4 = no4; k4 = nk4; a4 = na4; b4 = nb4; v2 = nv2;
;     ...
;                 ROW16_SUM2(py0, py1); yk0 = cgl == GS - 1 ? py0 : yk0; yk1 = cgl == GS - 1 ? py1 : yk1;
;                 if (cgl < GS) *(unsigned*)(YS + (size_t)(row_base + c * TC + g * GS + cgl) * 512 + h * 64 + row0) = pg8::cvt_pk_bf16(yk0, yk1);
	v_add_f32_dpp v80, v80, v80 row_shl:4 row_mask:0xf bank_mask:0x5 bound_ctrl:1
	v_add_f32_dpp v80, v88, v88 row_shr:4 row_mask:0xf bank_mask:0xa bound_ctrl:1
	v_add_f32_dpp v82, v82, v82 row_shl:4 row_mask:0xf bank_mask:0x5 bound_ctrl:1
	v_add_f32_dpp v82, v90, v90 row_shr:4 row_mask:0xf bank_mask:0xa bound_ctrl:1
	v_add_f32_dpp v84, v84, v84 row_shl:4 row_mask:0xf bank_mask:0x5 bound_ctrl:1
	v_add_f32_dpp v84, v92, v92 row_shr:4 row_mask:0xf bank_mask:0xa bound_ctrl:1
	v_add_f32_dpp v79, v79, v79 row_shl:4 row_mask:0xf bank_mask:0x5 bound_ctrl:1
	v_add_f32_dpp v79, v87, v87 row_shr:4 row_mask:0xf bank_mask:0xa bound_ctrl:1
	v_add_f32_dpp v81, v81, v81 row_shl:4 row_mask:0xf bank_mask:0x5 bound_ctrl:1
	v_add_f32_dpp v81, v89, v89 row_shr:4 row_mask:0xf bank_mask:0xa bound_ctrl:1
	v_add_f32_dpp v83, v83, v83 row_shl:4 row_mask:0xf bank_mask:0x5 bound_ctrl:1
	v_add_f32_dpp v83, v91, v91 row_shr:4 row_mask:0xf bank_mask:0xa bound_ctrl:1
	v_add_f32_dpp v85, v85, v85 row_shl:4 row_mask:0xf bank_mask:0x5 bound_ctrl:1
	v_add_f32_dpp v85, v93, v93 row_shr:4 row_mask:0xf bank_mask:0xa bound_ctrl:1
	v_add_f32_dpp v78, v78, v78 quad_perm:[1,0,3,2] row_mask:0xf bank_mask:0xf bound_ctrl:1
	v_add_f32_dpp v80, v80, v80 quad_perm:[1,0,3,2] row_mask:0xf bank_mask:0xf bound_ctrl:1
	v_add_f32_dpp v82, v82, v82 quad_perm:[1,0,3,2] row_mask:0xf bank_mask:0xf bound_ctrl:1
	v_add_f32_dpp v84, v84, v84 quad_perm:[1,0,3,2] row_mask:0xf bank_mask:0xf bound_ctrl:1
	v_add_f32_dpp v79, v79, v79 quad_perm:[1,0,3,2] row_mask:0xf bank_mask:0xf bound_ctrl:1
	v_add_f32_dpp v81, v81, v81 quad_perm:[1,0,3,2] row_mask:0xf bank_mask:0xf bound_ctrl:1
	v_add_f32_dpp v83, v83, v83 quad_perm:[1,0,3,2] row_mask:0xf bank_mask:0xf bound_ctrl:1
	v_add_f32_dpp v85, v85, v85 quad_perm:[1,0,3,2] row_mask:0xf bank_mask:0xf bound_ctrl:1
	v_add_f32_dpp v78, v78, v78 quad_perm:[2,3,0,1] row_mask:0xf bank_mask:0xf bound_ctrl:1
	v_add_f32_dpp v80, v80, v80 quad_perm:[2,3,0,1] row_mask:0xf bank_mask:0xf bound_ctrl:1
	v_add_f32_dpp v82, v82, v82 quad_perm:[2,3,0,1] row_mask:0xf bank_mask:0xf bound_ctrl:1
	v_add_f32_dpp v84, v84, v84 quad_perm:[2,3,0,1] row_mask:0xf bank_mask:0xf bound_ctrl:1
	v_add_f32_dpp v79, v79, v79 quad_perm:[2,3,0,1] row_mask:0xf bank_mask:0xf bound_ctrl:1
	v_add_f32_dpp v81, v81, v81 quad_perm:[2,3,0,1] row_mask:0xf bank_mask:0xf bound_ctrl:1
	v_add_f32_dpp v83, v83, v83 quad_perm:[2,3,0,1] row_mask:0xf bank_mask:0xf bound_ctrl:1
	v_add_f32_dpp v85, v85, v85 quad_perm:[2,3,0,1] row_mask:0xf bank_mask:0xf bound_ctrl:1
	v_add_u32_e32 v72, 0, v57
	v_ashrrev_i32_e32 v73, 31, v72
	v_lshlrev_b64 v[72:73], 10, v[72:73]
	v_lshl_add_u64 v[72:73], v[64:65], 0, v[72:73]
	v_cndmask_b32_e64 v154, v84, v82, s[16:17]
	v_cndmask_b32_e64 v155, v85, v83, s[16:17]
	v_cndmask_b32_e64 v154, v154, v80, s[14:15]
	v_cndmask_b32_e64 v155, v155, v81, s[14:15]
	v_cndmask_b32_e64 v154, v154, v78, s[12:13]
	v_cndmask_b32_e64 v155, v155, v79, s[12:13]
	v_cvt_pk_bf16_f32 v157, v155, v154
	v_cvt_pk_bf16_f32 v154, v154, v155
	v_cndmask_b32_e64 v154, v154, v157, s[98:99]
	global_store_dword v[72:73], v154, off
	v_pk_mul_f32 v[110:111], v[66:67], v[160:161] op_sel_hi:[1,0]
	v_pk_mul_f32 v[150:151], v[66:67], v[192:193] op_sel_hi:[1,0]
	v_pk_fma_f32 v[110:111], v[20:21], v[160:161], v[110:111] op_sel:[0,1,0]
	v_pk_fma_f32 v[150:151], v[20:21], v[192:193], v[150:151] op_sel:[0,1,0]
	v_pk_fma_f32 v[110:111], v[68:69], v[162:163], v[110:111] op_sel_hi:[1,0,1]
	v_pk_fma_f32 v[150:151], v[68:69], v[194:195], v[150:151] op_sel_hi:[1,0,1]
	v_pk_fma_f32 v[110:111], v[70:71], v[162:163], v[110:111] op_sel:[0,1,0]
	v_pk_fma_f32 v[150:151], v[70:71], v[194:195], v[150:151] op_sel:[0,1,0]
	v_pk_fma_f32 v[142:143], v[66:67], v[184:185], v[66:67] op_sel_hi:[1,0,1] neg_lo:[1,0,0] neg_hi:[1,0,0]
	v_pk_fma_f32 v[144:145], v[20:21], v[184:185], v[20:21] op_sel:[0,1,0] neg_lo:[1,0,0] neg_hi:[1,0,0]
	v_add_f32_dpp v150, v151, v150 row_ror:8 row_mask:0xf bank_mask:0xf bound_ctrl:1
	v_pk_fma_f32 v[146:147], v[68:69], v[186:187], v[68:69] op_sel_hi:[1,0,1] neg_lo:[1,0,0] neg_hi:[1,0,0]
	v_pk_fma_f32 v[148:149], v[70:71], v[186:187], v[70:71] op_sel:[0,1,0] neg_lo:[1,0,0] neg_hi:[1,0,0]
	v_add_f32_dpp v150, v150, v150 quad_perm:[1,0,3,2] row_mask:0xf bank_mask:0xf bound_ctrl:1
	v_pk_fma_f32 v[142:143], v[250:251], v[188:189], v[142:143] op_sel_hi:[1,0,1]
	v_pk_fma_f32 v[144:145], v[250:251], v[188:189], v[144:145] op_sel:[0,1,0]
	v_add_f32_dpp v150, v150, v150 quad_perm:[2,3,0,1] row_mask:0xf bank_mask:0xf bound_ctrl:1
	v_pk_fma_f32 v[146:147], v[250:251], v[190:191], v[146:147] op_sel_hi:[1,0,1]
	v_pk_fma_f32 v[148:149], v[250:251], v[190:191], v[148:149] op_sel:[0,1,0]
	v_add_f32_dpp v150, v150, v150 row_half_mirror row_mask:0xf bank_mask:0xf bound_ctrl:1
	s_nop 0
	s_waitcnt lgkmcnt(0)
; #define LAS __attribute__((address_space(3)))
; #define ROW16_SUM4(x, y, z, w) do { DPP4(x, y, z, w, "quad_perm:[1,0,3,2]", "s_nop 1"); DPP4(x, y, z, w, "quad_perm:[2,3,0,1]", ""); DPP4(x, y, z, w, "row_half_mirror", ""); DPP4(x, y, z, w, "row_mirror", ""); } while (0)
; template <bool SAMPLE>
; __device__ __forceinline__ void rwkv_unit(PR P, LAS float* lds, const int b, const int h, const int half, const int wv) {
;     ...
;                 for (int tt = 0; tt < GS; ++tt) {
;                     const LAS float* qn = q0 + (tt + 1 < GS ? tt + 1 : tt) * 384;
;                     const f32x4 nr4 = *(const LAS f32x4*)(qn + j0), no4 = *(const LAS f32x4*)(qn + 64 + j0), nk4 = *(const LAS f32x4*)(qn + 128 + j0), na4 = *(const LAS f32x4*)(qn + 192 + j0), nb4 = *(const LAS f32x4*)(qn + 256 + j0);
;                     const f32x2 nv2 = *(const LAS f32x2*)(qn + 320 + row0);
;                     f32x2 sa = (S[0] * a4[0] + S[1] * a4[1]) + (S[2] * a4[2] + S[3] * a4[3]);
;                     float sx = sa.x, sy = sa.y; ROW16_SUM4(sx, sy, py0, py1); sa = (f32x2){sx, sy};
;                     if (tt > 0) { yk0 = cgl == tt - 1 ? py0 : yk0; yk1 = cgl == tt - 1 ? py1 : yk1; }
; #pragma unroll
;                     for (int c = 0; c < 4; ++c) { f32x2 t = S[c] - S[c] * o4[c]; t = t + sa * b4[c]; S[c] = t + v2 * k4[c]; }
;                     const f32x2 y = (S[0] * r4[0] + S[1] * r4[1]) + (S[2] * r4[2] + S[3] * r4[3]);
;                     py0 = y.x; py1 = y.y;
;                     r4 = nr4; o4 = no4; k4 = nk4; a4 = na4; b4 = nb4; v2 = nv2;
	v_mov_b32_dpp v151, v150 row_ror:8 row_mask:0xf bank_mask:0xf bound_ctrl:1
	v_pk_fma_f32 v[66:67], v[150:151], v[196:197], v[142:143] op_sel_hi:[1,0,1]
	v_pk_fma_f32 v[20:21], v[150:151], v[196:197], v[144:145] op_sel:[0,1,0]
	v_pk_fma_f32 v[68:69], v[150:151], v[198:199], v[146:147] op_sel_hi:[1,0,1]
	v_pk_fma_f32 v[70:71], v[150:151], v[198:199], v[148:149] op_sel:[0,1,0]
	v_pk_mul_f32 v[112:113], v[66:67], v[180:181] op_sel_hi:[1,0]
	v_pk_mul_f32 v[150:151], v[66:67], v[212:213] op_sel_hi:[1,0]
	ds_read_b128 v[172:175], v152 offset:31488
	v_pk_fma_f32 v[112:113], v[20:21], v[180:181], v[112:113] op_sel:[0,1,0]
	v_pk_fma_f32 v[150:151], v[20:21], v[212:213], v[150:151] op_sel:[0,1,0]
	ds_read_b128 v[164:167], v152 offset:30976
	v_pk_fma_f32 v[112:113], v[68:69], v[182:183], v[112:113] op_sel_hi:[1,0,1]
	v_pk_fma_f32 v[150:151], v[68:69], v[214:215], v[150:151] op_sel_hi:[1,0,1]
	ds_read2st64_b64 v[244:247], v153 offset0:62 offset1:65
	v_pk_fma_f32 v[112:113], v[70:71], v[182:183], v[112:113] op_sel:[0,1,0]
	v_pk_fma_f32 v[150:151], v[70:71], v[214:215], v[150:151] op_sel:[0,1,0]
	ds_read_b128 v[168:171], v152 offset:31232
	v_pk_fma_f32 v[142:143], v[66:67], v[204:205], v[66:67] op_sel_hi:[1,0,1] neg_lo:[1,0,0] neg_hi:[1,0,0]
	v_pk_fma_f32 v[144:145], v[20:21], v[204:205], v[20:21] op_sel:[0,1,0] neg_lo:[1,0,0] neg_hi:[1,0,0]
	v_add_f32_dpp v150, v151, v150 row_ror:8 row_mask:0xf bank_mask:0xf bound_ctrl:1
	v_pk_fma_f32 v[146:147], v[68:69], v[206:207], v[68:69] op_sel_hi:[1,0,1] neg_lo:[1,0,0] neg_hi:[1,0,0]
	v_pk_fma_f32 v[148:149], v[70:71], v[206:207], v[70:71] op_sel:[0,1,0] neg_lo:[1,0,0] neg_hi:[1,0,0]
	v_add_f32_dpp v150, v150, v150 quad_perm:[1,0,3,2] row_mask:0xf bank_mask:0xf bound_ctrl:1
	v_pk_fma_f32 v[142:143], v[240:241], v[208:209], v[142:143] op_sel_hi:[1,0,1]
	v_pk_fma_f32 v[144:145], v[240:241], v[208:209], v[144:145] op_sel:[0,1,0]
	v_add_f32_dpp v150, v150, v150 quad_perm:[2,3,0,1] row_mask:0xf bank_mask:0xf bound_ctrl:1
	v_pk_fma_f32 v[146:147], v[240:241], v[210:211], v[146:147] op_sel_hi:[1,0,1]
	v_pk_fma_f32 v[148:149], v[240:241], v[210:211], v[148:149] op_sel:[0,1,0]
	v_add_f32_dpp v150, v150, v150 row_half_mirror row_mask:0xf bank_mask:0xf bound_ctrl:1
	ds_read_b128 v[192:195], v152 offset:33024
	ds_read_b128 v[184:187], v152 offset:32512
	v_mov_b32_dpp v151, v150 row_ror:8 row_mask:0xf bank_mask:0xf bound_ctrl:1
	ds_read_b128 v[176:179], v152 offset:31744
	ds_read_b128 v[188:191], v152 offset:32768
	ds_read_b128 v[196:199], v152 offset:33280
	ds_read_b128 v[160:163], v152 offset:30720
	ds_read_b128 v[180:183], v152 offset:32256
	v_pk_fma_f32 v[66:67], v[150:151], v[216:217], v[142:143] op_sel_hi:[1,0,1]
	v_pk_fma_f32 v[20:21], v[150:151], v[216:217], v[144:145] op_sel:[0,1,0]
	v_pk_fma_f32 v[68:69], v[150:151], v[218:219], v[146:147] op_sel_hi:[1,0,1]
	v_pk_fma_f32 v[70:71], v[150:151], v[218:219], v[148:149] op_sel:[0,1,0]
	v_pk_mul_f32 v[114:115], v[66:67], v[200:201] op_sel_hi:[1,0]
	v_pk_mul_f32 v[150:151], v[66:67], v[232:233] op_sel_hi:[1,0]
	v_pk_fma_f32 v[114:115], v[20:21], v[200:201], v[114:115] op_sel:[0,1,0]
	v_pk_fma_f32 v[150:151], v[20:21], v[232:233], v[150:151] op_sel:[0,1,0]
	v_pk_fma_f32 v[114:115], v[68:69], v[202:203], v[114:115] op_sel_hi:[1,0,1]
	v_pk_fma_f32 v[150:151], v[68:69], v[234:235], v[150:151] op_sel_hi:[1,0,1]
	v_pk_fma_f32 v[114:115], v[70:71], v[202:203], v[114:115] op_sel:[0,1,0]
	v_pk_fma_f32 v[150:151], v[70:71], v[234:235], v[150:151] op_sel:[0,1,0]
	v_pk_fma_f32 v[142:143], v[66:67], v[224:225], v[66:67] op_sel_hi:[1,0,1] neg_lo:[1,0,0] neg_hi:[1,0,0]
	v_pk_fma_f32 v[144:145], v[20:21], v[224:225], v[20:21] op_sel:[0,1,0] neg_lo:[1,0,0] neg_hi:[1,0,0]
	v_add_f32_dpp v150, v151, v150 row_ror:8 row_mask:0xf bank_mask:0xf bound_ctrl:1
	v_pk_fma_f32 v[146:147], v[68:69], v[226:227], v[68:69] op_sel_hi:[1,0,1] neg_lo:[1,0,0] neg_hi:[1,0,0]
	v_pk_fma_f32 v[148:149], v[70:71], v[226:227], v[70:71] op_sel:[0,1,0] neg_lo:[1,0,0] neg_hi:[1,0,0]
	v_add_f32_dpp v150, v150, v150 quad_perm:[1,0,3,2] row_mask:0xf bank_mask:0xf bound_ctrl:1
	v_pk_fma_f32 v[142:143], v[242:243], v[228:229], v[142:143] op_sel_hi:[1,0,1]
	v_pk_fma_f32 v[144:145], v[242:243], v[228:229], v[144:145] op_sel:[0,1,0]
	v_add_f32_dpp v150, v150, v150 quad_perm:[2,3,0,1] row_mask:0xf bank_mask:0xf bound_ctrl:1
	v_pk_fma_f32 v[146:147], v[242:243], v[230:231], v[146:147] op_sel_hi:[1,0,1]
	v_pk_fma_f32 v[148:149], v[242:243], v[230:231], v[148:149] op_sel:[0,1,0]
	v_add_f32_dpp v150, v150, v150 row_half_mirror row_mask:0xf bank_mask:0xf bound_ctrl:1
	s_nop 0
	s_waitcnt lgkmcnt(0)
; #define LAS __attribute__((address_space(3)))
; #define ROW16_SUM4(x, y, z, w) do { DPP4(x, y, z, w, "quad_perm:[1,0,3,2]", "s_nop 1"); DPP4(x, y, z, w, "quad_perm:[2,3,0,1]", ""); DPP4(x, y, z, w, "row_half_mirror", ""); DPP4(x, y, z, w, "row_mirror", ""); } while (0)
; template <bool SAMPLE>
; __device__ __forceinline__ void rwkv_unit(PR P, LAS float* lds, const int b, const int h, const int half, const int wv) {
;     ...
;                 for (int tt = 0; tt < GS; ++tt) {
;                     const LAS float* qn = q0 + (tt + 1 < GS ? tt + 1 : tt) * 384;
;                     const f32x4 nr4 = *(const LAS f32x4*)(qn + j0), no4 = *(const LAS f32x4*)(qn + 64 + j0), nk4 = *(const LAS f32x4*)(qn + 128 + j0), na4 = *(const LAS f32x4*)(qn + 192 + j0), nb4 = *(const LAS f32x4*)(qn + 256 + j0);
;                     const f32x2 nv2 = *(const LAS f32x2*)(qn + 320 + row0);
;                     f32x2 sa = (S[0] * a4[0] + S[1] * a4[1]) + (S[2] * a4[2] + S[3] * a4[3]);
;                     float sx = sa.x, sy = sa.y; ROW16_SUM4(sx, sy, py0, py1); sa = (f32x2){sx, sy};
;                     if (tt > 0) { yk0 = cgl == tt - 1 ? py0 : yk0; yk1 = cgl == tt - 1 ? py1 : yk1; }
; #pragma unroll
;                     for (int c = 0; c < 4; ++c) { f32x2 t = S[c] - S[c] * o4[c]; t = t + sa * b4[c]; S[c] = t + v2 * k4[c]; }
;                     const f32x2 y = (S[0] * r4[0] + S[1] * r4[1]) + (S[2] * r4[2] + S[3] * r4[3]);
;                     py0 = y.x; py1 = y.y;
;                     r4 = nr4; o4 = no4; k4 = nk4; a4 = na4; b4 = nb4; v2 = nv2;
	v_mov_b32_dpp v151, v150 row_ror:8 row_mask:0xf bank_mask:0xf bound_ctrl:1
	v_pk_fma_f32 v[66:67], v[150:151], v[236:237], v[142:143] op_sel_hi:[1,0,1]
	v_pk_fma_f32 v[20:21], v[150:151], v[236:237], v[144:145] op_sel:[0,1,0]
	v_pk_fma_f32 v[68:69], v[150:151], v[238:239], v[146:147] op_sel_hi:[1,0,1]
	v_pk_fma_f32 v[70:71], v[150:151], v[238:239], v[148:149] op_sel:[0,1,0]
	v_pk_mul_f32 v[116:117], v[66:67], v[220:221] op_sel_hi:[1,0]
	v_pk_mul_f32 v[150:151], v[66:67], v[172:173] op_sel_hi:[1,0]
	ds_read_b128 v[212:215], v152 offset:34560
	v_pk_fma_f32 v[116:117], v[20:21], v[220:221], v[116:117] op_sel:[0,1,0]
	v_pk_fma_f32 v[150:151], v[20:21], v[172:173], v[150:151] op_sel:[0,1,0]
	ds_read_b128 v[204:207], v152 offset:34048
	v_pk_fma_f32 v[116:117], v[68:69], v[222:223], v[116:117] op_sel_hi:[1,0,1]
	v_pk_fma_f32 v[150:151], v[68:69], v[174:175], v[150:151] op_sel_hi:[1,0,1]
	ds_read2st64_b64 v[248:251], v153 offset0:68 offset1:71
	v_pk_fma_f32 v[116:117], v[70:71], v[222:223], v[116:117] op_sel:[0,1,0]
	v_pk_fma_f32 v[150:151], v[70:71], v[174:175], v[150:151] op_sel:[0,1,0]
	ds_read_b128 v[208:211], v152 offset:34304
	v_pk_fma_f32 v[142:143], v[66:67], v[164:165], v[66:67] op_sel_hi:[1,0,1] neg_lo:[1,0,0] neg_hi:[1,0,0]
	v_pk_fma_f32 v[144:145], v[20:21], v[164:165], v[20:21] op_sel:[0,1,0] neg_lo:[1,0,0] neg_hi:[1,0,0]
	v_add_f32_dpp v150, v151, v150 row_ror:8 row_mask:0xf bank_mask:0xf bound_ctrl:1
	v_pk_fma_f32 v[146:147], v[68:69], v[166:167], v[68:69] op_sel_hi:[1,0,1] neg_lo:[1,0,0] neg_hi:[1,0,0]
	v_pk_fma_f32 v[148:149], v[70:71], v[166:167], v[70:71] op_sel:[0,1,0] neg_lo:[1,0,0] neg_hi:[1,0,0]
	v_add_f32_dpp v150, v150, v150 quad_perm:[1,0,3,2] row_mask:0xf bank_mask:0xf bound_ctrl:1
	v_pk_fma_f32 v[142:143], v[244:245], v[168:169], v[142:143] op_sel_hi:[1,0,1]
	v_pk_fma_f32 v[144:145], v[244:245], v[168:169], v[144:145] op_sel:[0,1,0]
	v_add_f32_dpp v150, v150, v150 quad_perm:[2,3,0,1] row_mask:0xf bank_mask:0xf bound_ctrl:1
	v_pk_fma_f32 v[146:147], v[244:245], v[170:171], v[146:147] op_sel_hi:[1,0,1]
	v_pk_fma_f32 v[148:149], v[244:245], v[170:171], v[148:149] op_sel:[0,1,0]
	v_add_f32_dpp v150, v150, v150 row_half_mirror row_mask:0xf bank_mask:0xf bound_ctrl:1
	ds_read_b128 v[232:235], v152 offset:36096
	ds_read_b128 v[224:227], v152 offset:35584
	v_mov_b32_dpp v151, v150 row_ror:8 row_mask:0xf bank_mask:0xf bound_ctrl:1
	ds_read_b128 v[216:219], v152 offset:34816
	ds_read_b128 v[228:231], v152 offset:35840
	ds_read_b128 v[236:239], v152 offset:36352
	ds_read_b128 v[200:203], v152 offset:33792
	ds_read_b128 v[220:223], v152 offset:35328
	v_pk_fma_f32 v[66:67], v[150:151], v[176:177], v[142:143] op_sel_hi:[1,0,1]
	v_pk_fma_f32 v[20:21], v[150:151], v[176:177], v[144:145] op_sel:[0,1,0]
	v_pk_fma_f32 v[68:69], v[150:151], v[178:179], v[146:147] op_sel_hi:[1,0,1]
	v_pk_fma_f32 v[70:71], v[150:151], v[178:179], v[148:149] op_sel:[0,1,0]
	v_pk_mul_f32 v[118:119], v[66:67], v[160:161] op_sel_hi:[1,0]
	v_pk_mul_f32 v[150:151], v[66:67], v[192:193] op_sel_hi:[1,0]
	v_pk_fma_f32 v[118:119], v[20:21], v[160:161], v[118:119] op_sel:[0,1,0]
	v_pk_fma_f32 v[150:151], v[20:21], v[192:193], v[150:151] op_sel:[0,1,0]
	v_pk_fma_f32 v[118:119], v[68:69], v[162:163], v[118:119] op_sel_hi:[1,0,1]
	v_pk_fma_f32 v[150:151], v[68:69], v[194:195], v[150:151] op_sel_hi:[1,0,1]
	v_pk_fma_f32 v[118:119], v[70:71], v[162:163], v[118:119] op_sel:[0,1,0]
	v_pk_fma_f32 v[150:151], v[70:71], v[194:195], v[150:151] op_sel:[0,1,0]
	v_pk_fma_f32 v[142:143], v[66:67], v[184:185], v[66:67] op_sel_hi:[1,0,1] neg_lo:[1,0,0] neg_hi:[1,0,0]
	v_pk_fma_f32 v[144:145], v[20:21], v[184:185], v[20:21] op_sel:[0,1,0] neg_lo:[1,0,0] neg_hi:[1,0,0]
	v_add_f32_dpp v150, v151, v150 row_ror:8 row_mask:0xf bank_mask:0xf bound_ctrl:1
	v_pk_fma_f32 v[146:147], v[68:69], v[186:187], v[68:69] op_sel_hi:[1,0,1] neg_lo:[1,0,0] neg_hi:[1,0,0]
	v_pk_fma_f32 v[148:149], v[70:71], v[186:187], v[70:71] op_sel:[0,1,0] neg_lo:[1,0,0] neg_hi:[1,0,0]
	v_add_f32_dpp v150, v150, v150 quad_perm:[1,0,3,2] row_mask:0xf bank_mask:0xf bound_ctrl:1
	v_pk_fma_f32 v[142:143], v[246:247], v[188:189], v[142:143] op_sel_hi:[1,0,1]
	v_pk_fma_f32 v[144:145], v[246:247], v[188:189], v[144:145] op_sel:[0,1,0]
	v_add_f32_dpp v150, v150, v150 quad_perm:[2,3,0,1] row_mask:0xf bank_mask:0xf bound_ctrl:1
	v_pk_fma_f32 v[146:147], v[246:247], v[190:191], v[146:147] op_sel_hi:[1,0,1]
	v_pk_fma_f32 v[148:149], v[246:247], v[190:191], v[148:149] op_sel:[0,1,0]
	v_add_f32_dpp v150, v150, v150 row_half_mirror row_mask:0xf bank_mask:0xf bound_ctrl:1
	s_nop 0
	s_waitcnt lgkmcnt(0)
; #define LAS __attribute__((address_space(3)))
; #define ROW16_SUM4(x, y, z, w) do { DPP4(x, y, z, w, "quad_perm:[1,0,3,2]", "s_nop 1"); DPP4(x, y, z, w, "quad_perm:[2,3,0,1]", ""); DPP4(x, y, z, w, "row_half_mirror", ""); DPP4(x, y, z, w, "row_mirror", ""); } while (0)
; template <bool SAMPLE>
; __device__ __forceinline__ void rwkv_unit(PR P, LAS float* lds, const int b, const int h, const int half, const int wv) {
;     ...
;                 for (int tt = 0; tt < GS; ++tt) {
;                     const LAS float* qn = q0 + (tt + 1 < GS ? tt + 1 : tt) * 384;
;                     const f32x4 nr4 = *(const LAS f32x4*)(qn + j0), no4 = *(const LAS f32x4*)(qn + 64 + j0), nk4 = *(const LAS f32x4*)(qn + 128 + j0), na4 = *(const LAS f32x4*)(qn + 192 + j0), nb4 = *(const LAS f32x4*)(qn + 256 + j0);
;                     const f32x2 nv2 = *(const LAS f32x2*)(qn + 320 + row0);
;                     f32x2 sa = (S[0] * a4[0] + S[1] * a4[1]) + (S[2] * a4[2] + S[3] * a4[3]);
;                     float sx = sa.x, sy = sa.y; ROW16_SUM4(sx, sy, py0, py1); sa = (f32x2){sx, sy};
;                     if (tt > 0) { yk0 = cgl == tt - 1 ? py0 : yk0; yk1 = cgl == tt - 1 ? py1 : yk1; }
; #pragma unroll
;                     for (int c = 0; c < 4; ++c) { f32x2 t = S[c] - S[c] * o4[c]; t = t + sa * b4[c]; S[c] = t + v2 * k4[c]; }
;                     const f32x2 y = (S[0] * r4[0] + S[1] * r4[1]) + (S[2] * r4[2] + S[3] * r4[3]);
;                     py0 = y.x; py1 = y.y;
;                     r4 = nr4; o4 = no4; k4 = nk4; a4 = na4; b4 = nb4; v2 = nv2;
	v_mov_b32_dpp v151, v150 row_ror:8 row_mask:0xf bank_mask:0xf bound_ctrl:1
	v_pk_fma_f32 v[66:67], v[150:151], v[196:197], v[142:143] op_sel_hi:[1,0,1]
	v_pk_fma_f32 v[20:21], v[150:151], v[196:197], v[144:145] op_sel:[0,1,0]
	v_pk_fma_f32 v[68:69], v[150:151], v[198:199], v[146:147] op_sel_hi:[1,0,1]
	v_pk_fma_f32 v[70:71], v[150:151], v[198:199], v[148:149] op_sel:[0,1,0]
	v_pk_mul_f32 v[120:121], v[66:67], v[180:181] op_sel_hi:[1,0]
	v_pk_mul_f32 v[150:151], v[66:67], v[212:213] op_sel_hi:[1,0]
	ds_read_b128 v[172:175], v152 offset:37632
	v_pk_fma_f32 v[120:121], v[20:21], v[180:181], v[120:121] op_sel:[0,1,0]
	v_pk_fma_f32 v[150:151], v[20:21], v[212:213], v[150:151] op_sel:[0,1,0]
	ds_read_b128 v[164:167], v152 offset:37120
	v_pk_fma_f32 v[120:121], v[68:69], v[182:183], v[120:121] op_sel_hi:[1,0,1]
	v_pk_fma_f32 v[150:151], v[68:69], v[214:215], v[150:151] op_sel_hi:[1,0,1]
	ds_read2st64_b64 v[240:243], v153 offset0:74 offset1:77
	v_pk_fma_f32 v[120:121], v[70:71], v[182:183], v[120:121] op_sel:[0,1,0]
	v_pk_fma_f32 v[150:151], v[70:71], v[214:215], v[150:151] op_sel:[0,1,0]
	ds_read_b128 v[168:171], v152 offset:37376
	v_pk_fma_f32 v[142:143], v[66:67], v[204:205], v[66:67] op_sel_hi:[1,0,1] neg_lo:[1,0,0] neg_hi:[1,0,0]
	v_pk_fma_f32 v[144:145], v[20:21], v[204:205], v[20:21] op_sel:[0,1,0] neg_lo:[1,0,0] neg_hi:[1,0,0]
	v_add_f32_dpp v150, v151, v150 row_ror:8 row_mask:0xf bank_mask:0xf bound_ctrl:1
	v_pk_fma_f32 v[146:147], v[68:69], v[206:207], v[68:69] op_sel_hi:[1,0,1] neg_lo:[1,0,0] neg_hi:[1,0,0]
	v_pk_fma_f32 v[148:149], v[70:71], v[206:207], v[70:71] op_sel:[0,1,0] neg_lo:[1,0,0] neg_hi:[1,0,0]
	v_add_f32_dpp v150, v150, v150 quad_perm:[1,0,3,2] row_mask:0xf bank_mask:0xf bound_ctrl:1
	v_pk_fma_f32 v[142:143], v[248:249], v[208:209], v[142:143] op_sel_hi:[1,0,1]
	v_pk_fma_f32 v[144:145], v[248:249], v[208:209], v[144:145] op_sel:[0,1,0]
	v_add_f32_dpp v150, v150, v150 quad_perm:[2,3,0,1] row_mask:0xf bank_mask:0xf bound_ctrl:1
	v_pk_fma_f32 v[146:147], v[248:249], v[210:211], v[146:147] op_sel_hi:[1,0,1]
	v_pk_fma_f32 v[148:149], v[248:249], v[210:211], v[148:149] op_sel:[0,1,0]
	v_add_f32_dpp v150, v150, v150 row_half_mirror row_mask:0xf bank_mask:0xf bound_ctrl:1
	ds_read_b128 v[192:195], v152 offset:39168
	ds_read_b128 v[184:187], v152 offset:38656
	v_mov_b32_dpp v151, v150 row_ror:8 row_mask:0xf bank_mask:0xf bound_ctrl:1
	ds_read_b128 v[176:179], v152 offset:37888
	ds_read_b128 v[188:191], v152 offset:38912
	ds_read_b128 v[196:199], v152 offset:39424
	ds_read_b128 v[160:163], v152 offset:36864
	ds_read_b128 v[180:183], v152 offset:38400
	v_pk_fma_f32 v[66:67], v[150:151], v[216:217], v[142:143] op_sel_hi:[1,0,1]
	v_pk_fma_f32 v[20:21], v[150:151], v[216:217], v[144:145] op_sel:[0,1,0]
	v_pk_fma_f32 v[68:69], v[150:151], v[218:219], v[146:147] op_sel_hi:[1,0,1]
	v_pk_fma_f32 v[70:71], v[150:151], v[218:219], v[148:149] op_sel:[0,1,0]
	v_pk_mul_f32 v[122:123], v[66:67], v[200:201] op_sel_hi:[1,0]
	v_pk_mul_f32 v[150:151], v[66:67], v[232:233] op_sel_hi:[1,0]
	v_pk_fma_f32 v[122:123], v[20:21], v[200:201], v[122:123] op_sel:[0,1,0]
	v_pk_fma_f32 v[150:151], v[20:21], v[232:233], v[150:151] op_sel:[0,1,0]
	v_pk_fma_f32 v[122:123], v[68:69], v[202:203], v[122:123] op_sel_hi:[1,0,1]
	v_pk_fma_f32 v[150:151], v[68:69], v[234:235], v[150:151] op_sel_hi:[1,0,1]
	v_pk_fma_f32 v[122:123], v[70:71], v[202:203], v[122:123] op_sel:[0,1,0]
	v_pk_fma_f32 v[150:151], v[70:71], v[234:235], v[150:151] op_sel:[0,1,0]
	v_pk_fma_f32 v[142:143], v[66:67], v[224:225], v[66:67] op_sel_hi:[1,0,1] neg_lo:[1,0,0] neg_hi:[1,0,0]
	v_pk_fma_f32 v[144:145], v[20:21], v[224:225], v[20:21] op_sel:[0,1,0] neg_lo:[1,0,0] neg_hi:[1,0,0]
	v_add_f32_dpp v150, v151, v150 row_ror:8 row_mask:0xf bank_mask:0xf bound_ctrl:1
	v_pk_fma_f32 v[146:147], v[68:69], v[226:227], v[68:69] op_sel_hi:[1,0,1] neg_lo:[1,0,0] neg_hi:[1,0,0]
	v_pk_fma_f32 v[148:149], v[70:71], v[226:227], v[70:71] op_sel:[0,1,0] neg_lo:[1,0,0] neg_hi:[1,0,0]
	v_add_f32_dpp v150, v150, v150 quad_perm:[1,0,3,2] row_mask:0xf bank_mask:0xf bound_ctrl:1
	v_pk_fma_f32 v[142:143], v[250:251], v[228:229], v[142:143] op_sel_hi:[1,0,1]
	v_pk_fma_f32 v[144:145], v[250:251], v[228:229], v[144:145] op_sel:[0,1,0]
	v_add_f32_dpp v150, v150, v150 quad_perm:[2,3,0,1] row_mask:0xf bank_mask:0xf bound_ctrl:1
	v_pk_fma_f32 v[146:147], v[250:251], v[230:231], v[146:147] op_sel_hi:[1,0,1]
	v_pk_fma_f32 v[148:149], v[250:251], v[230:231], v[148:149] op_sel:[0,1,0]
	v_add_f32_dpp v150, v150, v150 row_half_mirror row_mask:0xf bank_mask:0xf bound_ctrl:1
	s_nop 0
	s_waitcnt lgkmcnt(0)
; #define LAS __attribute__((address_space(3)))
; #define ROW16_SUM4(x, y, z, w) do { DPP4(x, y, z, w, "quad_perm:[1,0,3,2]", "s_nop 1"); DPP4(x, y, z, w, "quad_perm:[2,3,0,1]", ""); DPP4(x, y, z, w, "row_half_mirror", ""); DPP4(x, y, z, w, "row_mirror", ""); } while (0)
; template <bool SAMPLE>
; __device__ __forceinline__ void rwkv_unit(PR P, LAS float* lds, const int b, const int h, const int half, const int wv) {
;     ...
;                 for (int tt = 0; tt < GS; ++tt) {
;                     const LAS float* qn = q0 + (tt + 1 < GS ? tt + 1 : tt) * 384;
;                     const f32x4 nr4 = *(const LAS f32x4*)(qn + j0), no4 = *(const LAS f32x4*)(qn + 64 + j0), nk4 = *(const LAS f32x4*)(qn + 128 + j0), na4 = *(const LAS f32x4*)(qn + 192 + j0), nb4 = *(const LAS f32x4*)(qn + 256 + j0);
;                     const f32x2 nv2 = *(const LAS f32x2*)(qn + 320 + row0);
;                     f32x2 sa = (S[0] * a4[0] + S[1] * a4[1]) + (S[2] * a4[2] + S[3] * a4[3]);
;                     float sx = sa.x, sy = sa.y; ROW16_SUM4(sx, sy, py0, py1); sa = (f32x2){sx, sy};
;                     if (tt > 0) { yk0 = cgl == tt - 1 ? py0 : yk0; yk1 = cgl == tt - 1 ? py1 : yk1; }
; #pragma unroll
;                     for (int c = 0; c < 4; ++c) { f32x2 t = S[c] - S[c] * o4[c]; t = t + sa * b4[c]; S[c] = t + v2 * k4[c]; }
;                     const f32x2 y = (S[0] * r4[0] + S[1] * r4[1]) + (S[2] * r4[2] + S[3] * r4[3]);
;                     py0 = y.x; py1 = y.y;
;                     r4 = nr4; o4 = no4; k4 = nk4; a4 = na4; b4 = nb4; v2 = nv2;
	v_mov_b32_dpp v151, v150 row_ror:8 row_mask:0xf bank_mask:0xf bound_ctrl:1
	v_pk_fma_f32 v[66:67], v[150:151], v[236:237], v[142:143] op_sel_hi:[1,0,1]
	v_pk_fma_f32 v[20:21], v[150:151], v[236:237], v[144:145] op_sel:[0,1,0]
	v_pk_fma_f32 v[68:69], v[150:151], v[238:239], v[146:147] op_sel_hi:[1,0,1]
	v_pk_fma_f32 v[70:71], v[150:151], v[238:239], v[148:149] op_sel:[0,1,0]
	v_pk_mul_f32 v[124:125], v[66:67], v[220:221] op_sel_hi:[1,0]
	v_pk_mul_f32 v[150:151], v[66:67], v[172:173] op_sel_hi:[1,0]
	ds_read_b128 v[212:215], v152 offset:40704
	v_pk_fma_f32 v[124:125], v[20:21], v[220:221], v[124:125] op_sel:[0,1,0]
	v_pk_fma_f32 v[150:151], v[20:21], v[172:173], v[150:151] op_sel:[0,1,0]
	ds_read_b128 v[204:207], v152 offset:40192
	v_pk_fma_f32 v[124:125], v[68:69], v[222:223], v[124:125] op_sel_hi:[1,0,1]
	v_pk_fma_f32 v[150:151], v[68:69], v[174:175], v[150:151] op_sel_hi:[1,0,1]
	ds_read2st64_b64 v[244:247], v153 offset0:80 offset1:83
	v_pk_fma_f32 v[124:125], v[70:71], v[222:223], v[124:125] op_sel:[0,1,0]
	v_pk_fma_f32 v[150:151], v[70:71], v[174:175], v[150:151] op_sel:[0,1,0]
	ds_read_b128 v[208:211], v152 offset:40448
	v_pk_fma_f32 v[142:143], v[66:67], v[164:165], v[66:67] op_sel_hi:[1,0,1] neg_lo:[1,0,0] neg_hi:[1,0,0]
	v_pk_fma_f32 v[144:145], v[20:21], v[164:165], v[20:21] op_sel:[0,1,0] neg_lo:[1,0,0] neg_hi:[1,0,0]
	v_add_f32_dpp v150, v151, v150 row_ror:8 row_mask:0xf bank_mask:0xf bound_ctrl:1
	v_pk_fma_f32 v[146:147], v[68:69], v[166:167], v[68:69] op_sel_hi:[1,0,1] neg_lo:[1,0,0] neg_hi:[1,0,0]
	v_pk_fma_f32 v[148:149], v[70:71], v[166:167], v[70:71] op_sel:[0,1,0] neg_lo:[1,0,0] neg_hi:[1,0,0]
	v_add_f32_dpp v150, v150, v150 quad_perm:[1,0,3,2] row_mask:0xf bank_mask:0xf bound_ctrl:1
	v_pk_fma_f32 v[142:143], v[240:241], v[168:169], v[142:143] op_sel_hi:[1,0,1]
	v_pk_fma_f32 v[144:145], v[240:241], v[168:169], v[144:145] op_sel:[0,1,0]
	v_add_f32_dpp v150, v150, v150 quad_perm:[2,3,0,1] row_mask:0xf bank_mask:0xf bound_ctrl:1
	v_pk_fma_f32 v[146:147], v[240:241], v[170:171], v[146:147] op_sel_hi:[1,0,1]
	v_pk_fma_f32 v[148:149], v[240:241], v[170:171], v[148:149] op_sel:[0,1,0]
	v_add_f32_dpp v150, v150, v150 row_half_mirror row_mask:0xf bank_mask:0xf bound_ctrl:1
	ds_read_b128 v[232:235], v152 offset:42240
	ds_read_b128 v[224:227], v152 offset:41728
	v_mov_b32_dpp v151, v150 row_ror:8 row_mask:0xf bank_mask:0xf bound_ctrl:1
	ds_read_b128 v[216:219], v152 offset:40960
	ds_read_b128 v[228:231], v152 offset:41984
	ds_read_b128 v[236:239], v152 offset:42496
	ds_read_b128 v[200:203], v152 offset:39936
	ds_read_b128 v[220:223], v152 offset:41472
	v_pk_fma_f32 v[66:67], v[150:151], v[176:177], v[142:143] op_sel_hi:[1,0,1]
	v_pk_fma_f32 v[20:21], v[150:151], v[176:177], v[144:145] op_sel:[0,1,0]
	v_pk_fma_f32 v[68:69], v[150:151], v[178:179], v[146:147] op_sel_hi:[1,0,1]
	v_pk_fma_f32 v[70:71], v[150:151], v[178:179], v[148:149] op_sel:[0,1,0]
	v_pk_mul_f32 v[126:127], v[66:67], v[160:161] op_sel_hi:[1,0]
	v_pk_mul_f32 v[150:151], v[66:67], v[192:193] op_sel_hi:[1,0]
	v_pk_fma_f32 v[126:127], v[20:21], v[160:161], v[126:127] op_sel:[0,1,0]
	v_pk_fma_f32 v[150:151], v[20:21], v[192:193], v[150:151] op_sel:[0,1,0]
	v_pk_fma_f32 v[126:127], v[68:69], v[162:163], v[126:127] op_sel_hi:[1,0,1]
	v_pk_fma_f32 v[150:151], v[68:69], v[194:195], v[150:151] op_sel_hi:[1,0,1]
	v_pk_fma_f32 v[126:127], v[70:71], v[162:163], v[126:127] op_sel:[0,1,0]
	v_pk_fma_f32 v[150:151], v[70:71], v[194:195], v[150:151] op_sel:[0,1,0]
	v_pk_fma_f32 v[142:143], v[66:67], v[184:185], v[66:67] op_sel_hi:[1,0,1] neg_lo:[1,0,0] neg_hi:[1,0,0]
	v_pk_fma_f32 v[144:145], v[20:21], v[184:185], v[20:21] op_sel:[0,1,0] neg_lo:[1,0,0] neg_hi:[1,0,0]
	v_add_f32_dpp v150, v151, v150 row_ror:8 row_mask:0xf bank_mask:0xf bound_ctrl:1
	v_pk_fma_f32 v[146:147], v[68:69], v[186:187], v[68:69] op_sel_hi:[1,0,1] neg_lo:[1,0,0] neg_hi:[1,0,0]
	v_pk_fma_f32 v[148:149], v[70:71], v[186:187], v[70:71] op_sel:[0,1,0] neg_lo:[1,0,0] neg_hi:[1,0,0]
	v_add_f32_dpp v150, v150, v150 quad_perm:[1,0,3,2] row_mask:0xf bank_mask:0xf bound_ctrl:1
	v_pk_fma_f32 v[142:143], v[242:243], v[188:189], v[142:143] op_sel_hi:[1,0,1]
	v_pk_fma_f32 v[144:145], v[242:243], v[188:189], v[144:145] op_sel:[0,1,0]
	v_add_f32_dpp v150, v150, v150 quad_perm:[2,3,0,1] row_mask:0xf bank_mask:0xf bound_ctrl:1
	v_pk_fma_f32 v[146:147], v[242:243], v[190:191], v[146:147] op_sel_hi:[1,0,1]
	v_pk_fma_f32 v[148:149], v[242:243], v[190:191], v[148:149] op_sel:[0,1,0]
	v_add_f32_dpp v150, v150, v150 row_half_mirror row_mask:0xf bank_mask:0xf bound_ctrl:1
	s_nop 0
	s_waitcnt lgkmcnt(0)
; #define LAS __attribute__((address_space(3)))
; #define ROW16_SUM4(x, y, z, w) do { DPP4(x, y, z, w, "quad_perm:[1,0,3,2]", "s_nop 1"); DPP4(x, y, z, w, "quad_perm:[2,3,0,1]", ""); DPP4(x, y, z, w, "row_half_mirror", ""); DPP4(x, y, z, w, "row_mirror", ""); } while (0)
; template <bool SAMPLE>
; __device__ __forceinline__ void rwkv_unit(PR P, LAS float* lds, const int b, const int h, const int half, const int wv) {
;     ...
;                 for (int tt = 0; tt < GS; ++tt) {
;                     const LAS float* qn = q0 + (tt + 1 < GS ? tt + 1 : tt) * 384;
;                     const f32x4 nr4 = *(const LAS f32x4*)(qn + j0), no4 = *(const LAS f32x4*)(qn + 64 + j0), nk4 = *(const LAS f32x4*)(qn + 128 + j0), na4 = *(const LAS f32x4*)(qn + 192 + j0), nb4 = *(const LAS f32x4*)(qn + 256 + j0);
;                     const f32x2 nv2 = *(const LAS f32x2*)(qn + 320 + row0);
;                     f32x2 sa = (S[0] * a4[0] + S[1] * a4[1]) + (S[2] * a4[2] + S[3] * a4[3]);
;                     float sx = sa.x, sy = sa.y; ROW16_SUM4(sx, sy, py0, py1); sa = (f32x2){sx, sy};
;                     if (tt > 0) { yk0 = cgl == tt - 1 ? py0 : yk0; yk1 = cgl == tt - 1 ? py1 : yk1; }
; #pragma unroll
;                     for (int c = 0; c < 4; ++c) { f32x2 t = S[c] - S[c] * o4[c]; t = t + sa * b4[c]; S[c] = t + v2 * k4[c]; }
;                     const f32x2 y = (S[0] * r4[0] + S[1] * r4[1]) + (S[2] * r4[2] + S[3] * r4[3]);
;                     py0 = y.x; py1 = y.y;
;                     r4 = nr4; o4 = no4; k4 = nk4; a4 = na4; b4 = nb4; v2 = nv2;
	v_mov_b32_dpp v151, v150 row_ror:8 row_mask:0xf bank_mask:0xf bound_ctrl:1
	v_pk_fma_f32 v[66:67], v[150:151], v[196:197], v[142:143] op_sel_hi:[1,0,1]
	v_pk_fma_f32 v[20:21], v[150:151], v[196:197], v[144:145] op_sel:[0,1,0]
	v_pk_fma_f32 v[68:69], v[150:151], v[198:199], v[146:147] op_sel_hi:[1,0,1]
	v_pk_fma_f32 v[70:71], v[150:151], v[198:199], v[148:149] op_sel:[0,1,0]
	v_pk_mul_f32 v[128:129], v[66:67], v[180:181] op_sel_hi:[1,0]
	v_pk_mul_f32 v[150:151], v[66:67], v[212:213] op_sel_hi:[1,0]
	ds_read_b128 v[172:175], v152 offset:43776
	v_pk_fma_f32 v[128:129], v[20:21], v[180:181], v[128:129] op_sel:[0,1,0]
	v_pk_fma_f32 v[150:151], v[20:21], v[212:213], v[150:151] op_sel:[0,1,0]
	ds_read_b128 v[164:167], v152 offset:43264
	v_pk_fma_f32 v[128:129], v[68:69], v[182:183], v[128:129] op_sel_hi:[1,0,1]
	v_pk_fma_f32 v[150:151], v[68:69], v[214:215], v[150:151] op_sel_hi:[1,0,1]
	ds_read2st64_b64 v[248:251], v153 offset0:86 offset1:89
	v_pk_fma_f32 v[128:129], v[70:71], v[182:183], v[128:129] op_sel:[0,1,0]
	v_pk_fma_f32 v[150:151], v[70:71], v[214:215], v[150:151] op_sel:[0,1,0]
	ds_read_b128 v[168:171], v152 offset:43520
	v_pk_fma_f32 v[142:143], v[66:67], v[204:205], v[66:67] op_sel_hi:[1,0,1] neg_lo:[1,0,0] neg_hi:[1,0,0]
	v_pk_fma_f32 v[144:145], v[20:21], v[204:205], v[20:21] op_sel:[0,1,0] neg_lo:[1,0,0] neg_hi:[1,0,0]
	v_add_f32_dpp v150, v151, v150 row_ror:8 row_mask:0xf bank_mask:0xf bound_ctrl:1
	v_pk_fma_f32 v[146:147], v[68:69], v[206:207], v[68:69] op_sel_hi:[1,0,1] neg_lo:[1,0,0] neg_hi:[1,0,0]
	v_pk_fma_f32 v[148:149], v[70:71], v[206:207], v[70:71] op_sel:[0,1,0] neg_lo:[1,0,0] neg_hi:[1,0,0]
	v_add_f32_dpp v150, v150, v150 quad_perm:[1,0,3,2] row_mask:0xf bank_mask:0xf bound_ctrl:1
	v_pk_fma_f32 v[142:143], v[244:245], v[208:209], v[142:143] op_sel_hi:[1,0,1]
	v_pk_fma_f32 v[144:145], v[244:245], v[208:209], v[144:145] op_sel:[0,1,0]
	v_add_f32_dpp v150, v150, v150 quad_perm:[2,3,0,1] row_mask:0xf bank_mask:0xf bound_ctrl:1
	v_pk_fma_f32 v[146:147], v[244:245], v[210:211], v[146:147] op_sel_hi:[1,0,1]
	v_pk_fma_f32 v[148:149], v[244:245], v[210:211], v[148:149] op_sel:[0,1,0]
	v_add_f32_dpp v150, v150, v150 row_half_mirror row_mask:0xf bank_mask:0xf bound_ctrl:1
	ds_read_b128 v[192:195], v152 offset:45312
	ds_read_b128 v[184:187], v152 offset:44800
	v_mov_b32_dpp v151, v150 row_ror:8 row_mask:0xf bank_mask:0xf bound_ctrl:1
	ds_read_b128 v[176:179], v152 offset:44032
	ds_read_b128 v[188:191], v152 offset:45056
	ds_read_b128 v[196:199], v152 offset:45568
	ds_read_b128 v[160:163], v152 offset:43008
	ds_read_b128 v[180:183], v152 offset:44544
	v_pk_fma_f32 v[66:67], v[150:151], v[216:217], v[142:143] op_sel_hi:[1,0,1]
	v_pk_fma_f32 v[20:21], v[150:151], v[216:217], v[144:145] op_sel:[0,1,0]
	v_pk_fma_f32 v[68:69], v[150:151], v[218:219], v[146:147] op_sel_hi:[1,0,1]
	v_pk_fma_f32 v[70:71], v[150:151], v[218:219], v[148:149] op_sel:[0,1,0]
	v_pk_mul_f32 v[130:131], v[66:67], v[200:201] op_sel_hi:[1,0]
	v_pk_mul_f32 v[150:151], v[66:67], v[232:233] op_sel_hi:[1,0]
	v_pk_fma_f32 v[130:131], v[20:21], v[200:201], v[130:131] op_sel:[0,1,0]
	v_pk_fma_f32 v[150:151], v[20:21], v[232:233], v[150:151] op_sel:[0,1,0]
	v_pk_fma_f32 v[130:131], v[68:69], v[202:203], v[130:131] op_sel_hi:[1,0,1]
	v_pk_fma_f32 v[150:151], v[68:69], v[234:235], v[150:151] op_sel_hi:[1,0,1]
	v_pk_fma_f32 v[130:131], v[70:71], v[202:203], v[130:131] op_sel:[0,1,0]
	v_pk_fma_f32 v[150:151], v[70:71], v[234:235], v[150:151] op_sel:[0,1,0]
	v_pk_fma_f32 v[142:143], v[66:67], v[224:225], v[66:67] op_sel_hi:[1,0,1] neg_lo:[1,0,0] neg_hi:[1,0,0]
	v_pk_fma_f32 v[144:145], v[20:21], v[224:225], v[20:21] op_sel:[0,1,0] neg_lo:[1,0,0] neg_hi:[1,0,0]
	v_add_f32_dpp v150, v151, v150 row_ror:8 row_mask:0xf bank_mask:0xf bound_ctrl:1
	v_pk_fma_f32 v[146:147], v[68:69], v[226:227], v[68:69] op_sel_hi:[1,0,1] neg_lo:[1,0,0] neg_hi:[1,0,0]
	v_pk_fma_f32 v[148:149], v[70:71], v[226:227], v[70:71] op_sel:[0,1,0] neg_lo:[1,0,0] neg_hi:[1,0,0]
	v_add_f32_dpp v150, v150, v150 quad_perm:[1,0,3,2] row_mask:0xf bank_mask:0xf bound_ctrl:1
	v_pk_fma_f32 v[142:143], v[246:247], v[228:229], v[142:143] op_sel_hi:[1,0,1]
	v_pk_fma_f32 v[144:145], v[246:247], v[228:229], v[144:145] op_sel:[0,1,0]
	v_add_f32_dpp v150, v150, v150 quad_perm:[2,3,0,1] row_mask:0xf bank_mask:0xf bound_ctrl:1
	v_pk_fma_f32 v[146:147], v[246:247], v[230:231], v[146:147] op_sel_hi:[1,0,1]
	v_pk_fma_f32 v[148:149], v[246:247], v[230:231], v[148:149] op_sel:[0,1,0]
	v_add_f32_dpp v150, v150, v150 row_half_mirror row_mask:0xf bank_mask:0xf bound_ctrl:1
	s_nop 0
	s_waitcnt lgkmcnt(0)
; #define LAS __attribute__((address_space(3)))
; #define ROW16_SUM4(x, y, z, w) do { DPP4(x, y, z, w, "quad_perm:[1,0,3,2]", "s_nop 1"); DPP4(x, y, z, w, "quad_perm:[2,3,0,1]", ""); DPP4(x, y, z, w, "row_half_mirror", ""); DPP4(x, y, z, w, "row_mirror", ""); } while (0)
; template <bool SAMPLE>
; __device__ __forceinline__ void rwkv_unit(PR P, LAS float* lds, const int b, const int h, const int half, const int wv) {
;     ...
;                 for (int tt = 0; tt < GS; ++tt) {
;                     const LAS float* qn = q0 + (tt + 1 < GS ? tt + 1 : tt) * 384;
;                     const f32x4 nr4 = *(const LAS f32x4*)(qn + j0), no4 = *(const LAS f32x4*)(qn + 64 + j0), nk4 = *(const LAS f32x4*)(qn + 128 + j0), na4 = *(const LAS f32x4*)(qn + 192 + j0), nb4 = *(const LAS f32x4*)(qn + 256 + j0);
;                     const f32x2 nv2 = *(const LAS f32x2*)(qn + 320 + row0);
;                     f32x2 sa = (S[0] * a4[0] + S[1] * a4[1]) + (S[2] * a4[2] + S[3] * a4[3]);
;                     float sx = sa.x, sy = sa.y; ROW16_SUM4(sx, sy, py0, py1); sa = (f32x2){sx, sy};
;                     if (tt > 0) { yk0 = cgl == tt - 1 ? py0 : yk0; yk1 = cgl == tt - 1 ? py1 : yk1; }
; #pragma unroll
;                     for (int c = 0; c < 4; ++c) { f32x2 t = S[c] - S[c] * o4[c]; t = t + sa * b4[c]; S[c] = t + v2 * k4[c]; }
;                     const f32x2 y = (S[0] * r4[0] + S[1] * r4[1]) + (S[2] * r4[2] + S[3] * r4[3]);
;                     py0 = y.x; py1 = y.y;
;                     r4 = nr4; o4 = no4; k4 = nk4; a4 = na4; b4 = nb4; v2 = nv2;
	v_mov_b32_dpp v151, v150 row_ror:8 row_mask:0xf bank_mask:0xf bound_ctrl:1
	v_pk_fma_f32 v[66:67], v[150:151], v[236:237], v[142:143] op_sel_hi:[1,0,1]
	v_pk_fma_f32 v[20:21], v[150:151], v[236:237], v[144:145] op_sel:[0,1,0]
	v_pk_fma_f32 v[68:69], v[150:151], v[238:239], v[146:147] op_sel_hi:[1,0,1]
	v_pk_fma_f32 v[70:71], v[150:151], v[238:239], v[148:149] op_sel:[0,1,0]
	v_pk_mul_f32 v[132:133], v[66:67], v[220:221] op_sel_hi:[1,0]
	v_pk_mul_f32 v[150:151], v[66:67], v[172:173] op_sel_hi:[1,0]
	ds_read_b128 v[212:215], v152 offset:46848
	v_pk_fma_f32 v[132:133], v[20:21], v[220:221], v[132:133] op_sel:[0,1,0]
	v_pk_fma_f32 v[150:151], v[20:21], v[172:173], v[150:151] op_sel:[0,1,0]
	ds_read_b128 v[204:207], v152 offset:46336
	v_pk_fma_f32 v[132:133], v[68:69], v[222:223], v[132:133] op_sel_hi:[1,0,1]
	v_pk_fma_f32 v[150:151], v[68:69], v[174:175], v[150:151] op_sel_hi:[1,0,1]
	ds_read2st64_b64 v[240:243], v153 offset0:92 offset1:95
	v_pk_fma_f32 v[132:133], v[70:71], v[222:223], v[132:133] op_sel:[0,1,0]
	v_pk_fma_f32 v[150:151], v[70:71], v[174:175], v[150:151] op_sel:[0,1,0]
	ds_read_b128 v[208:211], v152 offset:46592
	v_pk_fma_f32 v[142:143], v[66:67], v[164:165], v[66:67] op_sel_hi:[1,0,1] neg_lo:[1,0,0] neg_hi:[1,0,0]
	v_pk_fma_f32 v[144:145], v[20:21], v[164:165], v[20:21] op_sel:[0,1,0] neg_lo:[1,0,0] neg_hi:[1,0,0]
	v_add_f32_dpp v150, v151, v150 row_ror:8 row_mask:0xf bank_mask:0xf bound_ctrl:1
	v_pk_fma_f32 v[146:147], v[68:69], v[166:167], v[68:69] op_sel_hi:[1,0,1] neg_lo:[1,0,0] neg_hi:[1,0,0]
	v_pk_fma_f32 v[148:149], v[70:71], v[166:167], v[70:71] op_sel:[0,1,0] neg_lo:[1,0,0] neg_hi:[1,0,0]
	v_add_f32_dpp v150, v150, v150 quad_perm:[1,0,3,2] row_mask:0xf bank_mask:0xf bound_ctrl:1
	v_pk_fma_f32 v[142:143], v[248:249], v[168:169], v[142:143] op_sel_hi:[1,0,1]
	v_pk_fma_f32 v[144:145], v[248:249], v[168:169], v[144:145] op_sel:[0,1,0]
	v_add_f32_dpp v150, v150, v150 quad_perm:[2,3,0,1] row_mask:0xf bank_mask:0xf bound_ctrl:1
	v_pk_fma_f32 v[146:147], v[248:249], v[170:171], v[146:147] op_sel_hi:[1,0,1]
	v_pk_fma_f32 v[148:149], v[248:249], v[170:171], v[148:149] op_sel:[0,1,0]
	v_add_f32_dpp v150, v150, v150 row_half_mirror row_mask:0xf bank_mask:0xf bound_ctrl:1
	ds_read_b128 v[232:235], v152 offset:48384
	ds_read_b128 v[224:227], v152 offset:47872
	v_mov_b32_dpp v151, v150 row_ror:8 row_mask:0xf bank_mask:0xf bound_ctrl:1
	ds_read_b128 v[216:219], v152 offset:47104
	ds_read_b128 v[228:231], v152 offset:48128
	ds_read_b128 v[236:239], v152 offset:48640
	ds_read_b128 v[200:203], v152 offset:46080
	ds_read_b128 v[220:223], v152 offset:47616
	v_pk_fma_f32 v[66:67], v[150:151], v[176:177], v[142:143] op_sel_hi:[1,0,1]
	v_pk_fma_f32 v[20:21], v[150:151], v[176:177], v[144:145] op_sel:[0,1,0]
	v_pk_fma_f32 v[68:69], v[150:151], v[178:179], v[146:147] op_sel_hi:[1,0,1]
	v_pk_fma_f32 v[70:71], v[150:151], v[178:179], v[148:149] op_sel:[0,1,0]
	v_pk_mul_f32 v[134:135], v[66:67], v[160:161] op_sel_hi:[1,0]
	v_pk_mul_f32 v[150:151], v[66:67], v[192:193] op_sel_hi:[1,0]
	v_pk_fma_f32 v[134:135], v[20:21], v[160:161], v[134:135] op_sel:[0,1,0]
	v_pk_fma_f32 v[150:151], v[20:21], v[192:193], v[150:151] op_sel:[0,1,0]
	v_pk_fma_f32 v[134:135], v[68:69], v[162:163], v[134:135] op_sel_hi:[1,0,1]
	v_pk_fma_f32 v[150:151], v[68:69], v[194:195], v[150:151] op_sel_hi:[1,0,1]
	v_pk_fma_f32 v[134:135], v[70:71], v[162:163], v[134:135] op_sel:[0,1,0]
	v_pk_fma_f32 v[150:151], v[70:71], v[194:195], v[150:151] op_sel:[0,1,0]
	v_pk_fma_f32 v[142:143], v[66:67], v[184:185], v[66:67] op_sel_hi:[1,0,1] neg_lo:[1,0,0] neg_hi:[1,0,0]
	v_pk_fma_f32 v[144:145], v[20:21], v[184:185], v[20:21] op_sel:[0,1,0] neg_lo:[1,0,0] neg_hi:[1,0,0]
	v_add_f32_dpp v150, v151, v150 row_ror:8 row_mask:0xf bank_mask:0xf bound_ctrl:1
	v_pk_fma_f32 v[146:147], v[68:69], v[186:187], v[68:69] op_sel_hi:[1,0,1] neg_lo:[1,0,0] neg_hi:[1,0,0]
	v_pk_fma_f32 v[148:149], v[70:71], v[186:187], v[70:71] op_sel:[0,1,0] neg_lo:[1,0,0] neg_hi:[1,0,0]
	v_add_f32_dpp v150, v150, v150 quad_perm:[1,0,3,2] row_mask:0xf bank_mask:0xf bound_ctrl:1
	v_pk_fma_f32 v[142:143], v[250:251], v[188:189], v[142:143] op_sel_hi:[1,0,1]
	v_pk_fma_f32 v[144:145], v[250:251], v[188:189], v[144:145] op_sel:[0,1,0]
	v_add_f32_dpp v150, v150, v150 quad_perm:[2,3,0,1] row_mask:0xf bank_mask:0xf bound_ctrl:1
	v_pk_fma_f32 v[146:147], v[250:251], v[190:191], v[146:147] op_sel_hi:[1,0,1]
	v_pk_fma_f32 v[148:149], v[250:251], v[190:191], v[148:149] op_sel:[0,1,0]
	v_add_f32_dpp v150, v150, v150 row_half_mirror row_mask:0xf bank_mask:0xf bound_ctrl:1
	s_nop 0
	s_waitcnt lgkmcnt(0)
; #define LAS __attribute__((address_space(3)))
; #define ROW16_SUM4(x, y, z, w) do { DPP4(x, y, z, w, "quad_perm:[1,0,3,2]", "s_nop 1"); DPP4(x, y, z, w, "quad_perm:[2,3,0,1]", ""); DPP4(x, y, z, w, "row_half_mirror", ""); DPP4(x, y, z, w, "row_mirror", ""); } while (0)
; template <bool SAMPLE>
; __device__ __forceinline__ void rwkv_unit(PR P, LAS float* lds, const int b, const int h, const int half, const int wv) {
;     ...
;                 for (int tt = 0; tt < GS; ++tt) {
;                     const LAS float* qn = q0 + (tt + 1 < GS ? tt + 1 : tt) * 384;
;                     const f32x4 nr4 = *(const LAS f32x4*)(qn + j0), no4 = *(const LAS f32x4*)(qn + 64 + j0), nk4 = *(const LAS f32x4*)(qn + 128 + j0), na4 = *(const LAS f32x4*)(qn + 192 + j0), nb4 = *(const LAS f32x4*)(qn + 256 + j0);
;                     const f32x2 nv2 = *(const LAS f32x2*)(qn + 320 + row0);
;                     f32x2 sa = (S[0] * a4[0] + S[1] * a4[1]) + (S[2] * a4[2] + S[3] * a4[3]);
;                     float sx = sa.x, sy = sa.y; ROW16_SUM4(sx, sy, py0, py1); sa = (f32x2){sx, sy};
;                     if (tt > 0) { yk0 = cgl == tt - 1 ? py0 : yk0; yk1 = cgl == tt - 1 ? py1 : yk1; }
; #pragma unroll
;                     for (int c = 0; c < 4; ++c) { f32x2 t = S[c] - S[c] * o4[c]; t = t + sa * b4[c]; S[c] = t + v2 * k4[c]; }
;                     const f32x2 y = (S[0] * r4[0] + S[1] * r4[1]) + (S[2] * r4[2] + S[3] * r4[3]);
;                     py0 = y.x; py1 = y.y;
;                     r4 = nr4; o4 = no4; k4 = nk4; a4 = na4; b4 = nb4; v2 = nv2;
;                 }
	v_mov_b32_dpp v151, v150 row_ror:8 row_mask:0xf bank_mask:0xf bound_ctrl:1
	v_pk_fma_f32 v[66:67], v[150:151], v[196:197], v[142:143] op_sel_hi:[1,0,1]
	v_pk_fma_f32 v[20:21], v[150:151], v[196:197], v[144:145] op_sel:[0,1,0]
	v_pk_fma_f32 v[68:69], v[150:151], v[198:199], v[146:147] op_sel_hi:[1,0,1]
	v_pk_fma_f32 v[70:71], v[150:151], v[198:199], v[148:149] op_sel:[0,1,0]
	v_pk_mul_f32 v[136:137], v[66:67], v[180:181] op_sel_hi:[1,0]
	v_pk_mul_f32 v[150:151], v[66:67], v[212:213] op_sel_hi:[1,0]
	v_pk_fma_f32 v[136:137], v[20:21], v[180:181], v[136:137] op_sel:[0,1,0]
	v_pk_fma_f32 v[150:151], v[20:21], v[212:213], v[150:151] op_sel:[0,1,0]
	v_pk_fma_f32 v[136:137], v[68:69], v[182:183], v[136:137] op_sel_hi:[1,0,1]
	v_pk_fma_f32 v[150:151], v[68:69], v[214:215], v[150:151] op_sel_hi:[1,0,1]
	v_pk_fma_f32 v[136:137], v[70:71], v[182:183], v[136:137] op_sel:[0,1,0]
	v_pk_fma_f32 v[150:151], v[70:71], v[214:215], v[150:151] op_sel:[0,1,0]
	v_pk_fma_f32 v[142:143], v[66:67], v[204:205], v[66:67] op_sel_hi:[1,0,1] neg_lo:[1,0,0] neg_hi:[1,0,0]
	v_pk_fma_f32 v[144:145], v[20:21], v[204:205], v[20:21] op_sel:[0,1,0] neg_lo:[1,0,0] neg_hi:[1,0,0]
	v_add_f32_dpp v150, v151, v150 row_ror:8 row_mask:0xf bank_mask:0xf bound_ctrl:1
	v_pk_fma_f32 v[146:147], v[68:69], v[206:207], v[68:69] op_sel_hi:[1,0,1] neg_lo:[1,0,0] neg_hi:[1,0,0]
	v_pk_fma_f32 v[148:149], v[70:71], v[206:207], v[70:71] op_sel:[0,1,0] neg_lo:[1,0,0] neg_hi:[1,0,0]
	v_add_f32_dpp v150, v150, v150 quad_perm:[1,0,3,2] row_mask:0xf bank_mask:0xf bound_ctrl:1
	v_pk_fma_f32 v[142:143], v[240:241], v[208:209], v[142:143] op_sel_hi:[1,0,1]
	v_pk_fma_f32 v[144:145], v[240:241], v[208:209], v[144:145] op_sel:[0,1,0]
	v_add_f32_dpp v150, v150, v150 quad_perm:[2,3,0,1] row_mask:0xf bank_mask:0xf bound_ctrl:1
	v_pk_fma_f32 v[146:147], v[240:241], v[210:211], v[146:147] op_sel_hi:[1,0,1]
	v_pk_fma_f32 v[148:149], v[240:241], v[210:211], v[148:149] op_sel:[0,1,0]
	v_add_f32_dpp v150, v150, v150 row_half_mirror row_mask:0xf bank_mask:0xf bound_ctrl:1
	s_nop 0
	s_nop 0
	v_mov_b32_dpp v151, v150 row_ror:8 row_mask:0xf bank_mask:0xf bound_ctrl:1
	v_pk_fma_f32 v[66:67], v[150:151], v[216:217], v[142:143] op_sel_hi:[1,0,1]
	v_pk_fma_f32 v[20:21], v[150:151], v[216:217], v[144:145] op_sel:[0,1,0]
	v_pk_fma_f32 v[68:69], v[150:151], v[218:219], v[146:147] op_sel_hi:[1,0,1]
	v_pk_fma_f32 v[70:71], v[150:151], v[218:219], v[148:149] op_sel:[0,1,0]
	v_pk_mul_f32 v[138:139], v[66:67], v[200:201] op_sel_hi:[1,0]
	v_pk_mul_f32 v[150:151], v[66:67], v[232:233] op_sel_hi:[1,0]
	v_pk_fma_f32 v[138:139], v[20:21], v[200:201], v[138:139] op_sel:[0,1,0]
	v_pk_fma_f32 v[150:151], v[20:21], v[232:233], v[150:151] op_sel:[0,1,0]
	v_pk_fma_f32 v[138:139], v[68:69], v[202:203], v[138:139] op_sel_hi:[1,0,1]
	v_pk_fma_f32 v[150:151], v[68:69], v[234:235], v[150:151] op_sel_hi:[1,0,1]
	v_pk_fma_f32 v[138:139], v[70:71], v[202:203], v[138:139] op_sel:[0,1,0]
	v_pk_fma_f32 v[150:151], v[70:71], v[234:235], v[150:151] op_sel:[0,1,0]
	v_pk_fma_f32 v[142:143], v[66:67], v[224:225], v[66:67] op_sel_hi:[1,0,1] neg_lo:[1,0,0] neg_hi:[1,0,0]
	v_pk_fma_f32 v[144:145], v[20:21], v[224:225], v[20:21] op_sel:[0,1,0] neg_lo:[1,0,0] neg_hi:[1,0,0]
	v_add_f32_dpp v150, v151, v150 row_ror:8 row_mask:0xf bank_mask:0xf bound_ctrl:1
	v_pk_fma_f32 v[146:147], v[68:69], v[226:227], v[68:69] op_sel_hi:[1,0,1] neg_lo:[1,0,0] neg_hi:[1,0,0]
	v_pk_fma_f32 v[148:149], v[70:71], v[226:227], v[70:71] op_sel:[0,1,0] neg_lo:[1,0,0] neg_hi:[1,0,0]
	v_add_f32_dpp v150, v150, v150 quad_perm:[1,0,3,2] row_mask:0xf bank_mask:0xf bound_ctrl:1
	v_pk_fma_f32 v[142:143], v[242:243], v[228:229], v[142:143] op_sel_hi:[1,0,1]
	v_pk_fma_f32 v[144:145], v[242:243], v[228:229], v[144:145] op_sel:[0,1,0]
	v_add_f32_dpp v150, v150, v150 quad_perm:[2,3,0,1] row_mask:0xf bank_mask:0xf bound_ctrl:1
	v_pk_fma_f32 v[146:147], v[242:243], v[230:231], v[146:147] op_sel_hi:[1,0,1]
	v_pk_fma_f32 v[148:149], v[242:243], v[230:231], v[148:149] op_sel:[0,1,0]
	v_add_f32_dpp v150, v150, v150 row_half_mirror row_mask:0xf bank_mask:0xf bound_ctrl:1
	s_nop 0
	s_nop 0
	v_mov_b32_dpp v151, v150 row_ror:8 row_mask:0xf bank_mask:0xf bound_ctrl:1
	v_pk_fma_f32 v[66:67], v[150:151], v[236:237], v[142:143] op_sel_hi:[1,0,1]
	v_pk_fma_f32 v[20:21], v[150:151], v[236:237], v[144:145] op_sel:[0,1,0]
	v_pk_fma_f32 v[68:69], v[150:151], v[238:239], v[146:147] op_sel_hi:[1,0,1]
	v_pk_fma_f32 v[70:71], v[150:151], v[238:239], v[148:149] op_sel:[0,1,0]
	v_pk_mul_f32 v[140:141], v[66:67], v[220:221] op_sel_hi:[1,0]
	v_pk_fma_f32 v[140:141], v[20:21], v[220:221], v[140:141] op_sel:[0,1,0]
	v_pk_fma_f32 v[140:141], v[68:69], v[222:223], v[140:141] op_sel_hi:[1,0,1]
	v_pk_fma_f32 v[140:141], v[70:71], v[222:223], v[140:141] op_sel:[0,1,0]
	s_branch .LBB0_704
; __device__ __forceinline__ unsigned cvt_pk_bf16(float lo, float hi) { const f32x2_t v = {lo, hi}; const bf16x2_t b = __builtin_convertvector(v, bf16x2_t); return __builtin_bit_cast(unsigned, b); }
; #define ROW16_SUM2(x, y) do { DPP2(x, y, "quad_perm:[1,0,3,2]", "s_nop 1"); DPP2(x, y, "quad_perm:[2,3,0,1]", "s_nop 0"); DPP2(x, y, "row_half_mirror", "s_nop 0"); DPP2(x, y, "row_mirror", "s_nop 0"); } while (0)
; template <bool SAMPLE>
; __device__ __forceinline__ void rwkv_unit(PR P, LAS float* lds, const int b, const int h, const int half, const int wv) {
;     ...
;                 ROW16_SUM2(py0, py1); yk0 = cgl == GS - 1 ? py0 : yk0; yk1 = cgl == GS - 1 ? py1 : yk1;
;                 if (cgl < GS) *(unsigned*)(YS + (size_t)(row_base + c * TC + g * GS + cgl) * 512 + h * 64 + row0) = pg8::cvt_pk_bf16(yk0, yk1);
;     ...
;     if (wid < 4) { *(float4*)sout = make_float4(S[0].x, S[1].x, S[2].x, S[3].x); *(float4*)(sout + 64) = make_float4(S[0].y, S[1].y, S[2].y, S[3].y); }
.LBB0_723:
	s_and_saveexec_b64 s[10:11], s[8:9]
	s_cbranch_execz .LBB0_725
	v_add_f32_dpp v110, v111, v110 row_ror:8 row_mask:0xf bank_mask:0x3 bound_ctrl:1
	v_add_f32_dpp v112, v113, v112 row_ror:8 row_mask:0xf bank_mask:0x3 bound_ctrl:1
	v_add_f32_dpp v114, v115, v114 row_ror:8 row_mask:0xf bank_mask:0x3 bound_ctrl:1
	v_add_f32_dpp v116, v117, v116 row_ror:8 row_mask:0xf bank_mask:0x3 bound_ctrl:1
	v_add_f32_dpp v118, v119, v118 row_ror:8 row_mask:0xf bank_mask:0x3 bound_ctrl:1
	v_add_f32_dpp v120, v121, v120 row_ror:8 row_mask:0xf bank_mask:0x3 bound_ctrl:1
	v_add_f32_dpp v122, v123, v122 row_ror:8 row_mask:0xf bank_mask:0x3 bound_ctrl:1
	v_add_f32_dpp v124, v125, v124 row_ror:8 row_mask:0xf bank_mask:0x3 bound_ctrl:1
	v_add_f32_dpp v111, v110, v111 row_ror:8 row_mask:0xf bank_mask:0x3 bound_ctrl:1
	v_add_f32_dpp v113, v112, v113 row_ror:8 row_mask:0xf bank_mask:0x3 bound_ctrl:1
	v_add_f32_dpp v115, v114, v115 row_ror:8 row_mask:0xf bank_mask:0x3 bound_ctrl:1
	v_add_f32_dpp v117, v116, v117 row_ror:8 row_mask:0xf bank_mask:0x3 bound_ctrl:1
	v_add_f32_dpp v119, v118, v119 row_ror:8 row_mask:0xf bank_mask:0x3 bound_ctrl:1
	v_add_f32_dpp v121, v120, v121 row_ror:8 row_mask:0xf bank_mask:0x3 bound_ctrl:1
	v_add_f32_dpp v123, v122, v123 row_ror:8 row_mask:0xf bank_mask:0x3 bound_ctrl:1
	v_add_f32_dpp v125, v124, v125 row_ror:8 row_mask:0xf bank_mask:0x3 bound_ctrl:1
	v_add_f32_dpp v110, v127, v126 row_ror:8 row_mask:0xf bank_mask:0xc bound_ctrl:1
	v_add_f32_dpp v112, v129, v128 row_ror:8 row_mask:0xf bank_mask:0xc bound_ctrl:1
	v_add_f32_dpp v114, v131, v130 row_ror:8 row_mask:0xf bank_mask:0xc bound_ctrl:1
	v_add_f32_dpp v116, v133, v132 row_ror:8 row_mask:0xf bank_mask:0xc bound_ctrl:1
	v_add_f32_dpp v118, v135, v134 row_ror:8 row_mask:0xf bank_mask:0xc bound_ctrl:1
	v_add_f32_dpp v120, v137, v136 row_ror:8 row_mask:0xf bank_mask:0xc bound_ctrl:1
	v_add_f32_dpp v122, v139, v138 row_ror:8 row_mask:0xf bank_mask:0xc bound_ctrl:1
	v_add_f32_dpp v124, v141, v140 row_ror:8 row_mask:0xf bank_mask:0xc bound_ctrl:1
	v_add_f32_dpp v111, v126, v127 row_ror:8 row_mask:0xf bank_mask:0xc bound_ctrl:1
	v_add_f32_dpp v113, v128, v129 row_ror:8 row_mask:0xf bank_mask:0xc bound_ctrl:1
	v_add_f32_dpp v115, v130, v131 row_ror:8 row_mask:0xf bank_mask:0xc bound_ctrl:1
	v_add_f32_dpp v117, v132, v133 row_ror:8 row_mask:0xf bank_mask:0xc bound_ctrl:1
	v_add_f32_dpp v119, v134, v135 row_ror:8 row_mask:0xf bank_mask:0xc bound_ctrl:1
	v_add_f32_dpp v121, v136, v137 row_ror:8 row_mask:0xf bank_mask:0xc bound_ctrl:1
	v_add_f32_dpp v123, v138, v139 row_ror:8 row_mask:0xf bank_mask:0xc bound_ctrl:1
	v_add_f32_dpp v125, v140, v141 row_ror:8 row_mask:0xf bank_mask:0xc bound_ctrl:1
	v_add_f32_dpp v110, v110, v110 row_shl:4 row_mask:0xf bank_mask:0x5 bound_ctrl:1
	v_add_f32_dpp v110, v118, v118 row_shr:4 row_mask:0xf bank_mask:0xa bound_ctrl:1
	v_add_f32_dpp v112, v112, v112 row_shl:4 row_mask:0xf bank_mask:0x5 bound_ctrl:1
	v_add_f32_dpp v112, v120, v120 row_shr:4 row_mask:0xf bank_mask:0xa bound_ctrl:1
	v_add_f32_dpp v114, v114, v114 row_shl:4 row_mask:0xf bank_mask:0x5 bound_ctrl:1
	v_add_f32_dpp v114, v122, v122 row_shr:4 row_mask:0xf bank_mask:0xa bound_ctrl:1
	v_add_f32_dpp v116, v116, v116 row_shl:4 row_mask:0xf bank_mask:0x5 bound_ctrl:1
	v_add_f32_dpp v116, v124, v124 row_shr:4 row_mask:0xf bank_mask:0xa bound_ctrl:1
	v_add_f32_dpp v111, v111, v111 row_shl:4 row_mask:0xf bank_mask:0x5 bound_ctrl:1
	v_add_f32_dpp v111, v119, v119 row_shr:4 row_mask:0xf bank_mask:0xa bound_ctrl:1
	v_add_f32_dpp v113, v113, v113 row_shl:4 row_mask:0xf bank_mask:0x5 bound_ctrl:1
	v_add_f32_dpp v113, v121, v121 row_shr:4 row_mask:0xf bank_mask:0xa bound_ctrl:1
	v_add_f32_dpp v115, v115, v115 row_shl:4 row_mask:0xf bank_mask:0x5 bound_ctrl:1
	v_add_f32_dpp v115, v123, v123 row_shr:4 row_mask:0xf bank_mask:0xa bound_ctrl:1
	v_add_f32_dpp v117, v117, v117 row_shl:4 row_mask:0xf bank_mask:0x5 bound_ctrl:1
	v_add_f32_dpp v117, v125, v125 row_shr:4 row_mask:0xf bank_mask:0xa bound_ctrl:1
	v_add_f32_dpp v110, v110, v110 quad_perm:[1,0,3,2] row_mask:0xf bank_mask:0xf bound_ctrl:1
	v_add_f32_dpp v112, v112, v112 quad_perm:[1,0,3,2] row_mask:0xf bank_mask:0xf bound_ctrl:1
	v_add_f32_dpp v114, v114, v114 quad_perm:[1,0,3,2] row_mask:0xf bank_mask:0xf bound_ctrl:1
	v_add_f32_dpp v116, v116, v116 quad_perm:[1,0,3,2] row_mask:0xf bank_mask:0xf bound_ctrl:1
	v_add_f32_dpp v111, v111, v111 quad_perm:[1,0,3,2] row_mask:0xf bank_mask:0xf bound_ctrl:1
	v_add_f32_dpp v113, v113, v113 quad_perm:[1,0,3,2] row_mask:0xf bank_mask:0xf bound_ctrl:1
	v_add_f32_dpp v115, v115, v115 quad_perm:[1,0,3,2] row_mask:0xf bank_mask:0xf bound_ctrl:1
	v_add_f32_dpp v117, v117, v117 quad_perm:[1,0,3,2] row_mask:0xf bank_mask:0xf bound_ctrl:1
	v_add_f32_dpp v110, v110, v110 quad_perm:[2,3,0,1] row_mask:0xf bank_mask:0xf bound_ctrl:1
	v_add_f32_dpp v112, v112, v112 quad_perm:[2,3,0,1] row_mask:0xf bank_mask:0xf bound_ctrl:1
	v_add_f32_dpp v114, v114, v114 quad_perm:[2,3,0,1] row_mask:0xf bank_mask:0xf bound_ctrl:1
	v_add_f32_dpp v116, v116, v116 quad_perm:[2,3,0,1] row_mask:0xf bank_mask:0xf bound_ctrl:1
	v_add_f32_dpp v111, v111, v111 quad_perm:[2,3,0,1] row_mask:0xf bank_mask:0xf bound_ctrl:1
	v_add_f32_dpp v113, v113, v113 quad_perm:[2,3,0,1] row_mask:0xf bank_mask:0xf bound_ctrl:1
	v_add_f32_dpp v115, v115, v115 quad_perm:[2,3,0,1] row_mask:0xf bank_mask:0xf bound_ctrl:1
	v_add_f32_dpp v117, v117, v117 quad_perm:[2,3,0,1] row_mask:0xf bank_mask:0xf bound_ctrl:1
	v_add_u32_e32 v72, 16, v57
	v_ashrrev_i32_e32 v73, 31, v72
	v_lshlrev_b64 v[72:73], 10, v[72:73]
	v_lshl_add_u64 v[72:73], v[64:65], 0, v[72:73]
	v_cndmask_b32_e64 v154, v116, v114, s[16:17]
	v_cndmask_b32_e64 v155, v117, v115, s[16:17]
	v_cndmask_b32_e64 v154, v154, v112, s[14:15]
	v_cndmask_b32_e64 v155, v155, v113, s[14:15]
	v_cndmask_b32_e64 v154, v154, v110, s[12:13]
	v_cndmask_b32_e64 v155, v155, v111, s[12:13]
	v_cvt_pk_bf16_f32 v157, v155, v154
	v_cvt_pk_bf16_f32 v154, v154, v155
	v_cndmask_b32_e64 v154, v154, v157, s[98:99]
	global_store_dword v[72:73], v154, off
	s_lshl_b32 s5, s5, 3
	s_or_b32 s4, s5, s4
	s_ashr_i32 s5, s4, 31
	s_lshl_b64 s[4:5], s[4:5], 14
	s_add_u32 s4, s44, s4
	s_addc_u32 s5, s45, s5
	s_waitcnt vmcnt(4)
	v_lshlrev_b32_e32 v0, 8, v54
	v_mov_b32_e32 v1, 0
	v_lshl_add_u64 v[2:3], s[4:5], 0, v[0:1]
	v_lshlrev_b32_e32 v0, 2, v76
	s_waitcnt vmcnt(3)
	v_lshl_add_u64 v[4:5], v[2:3], 0, v[0:1]
	s_mov_b64 s[4:5], 0x4208000
	v_lshl_add_u64 v[6:7], v[4:5], 0, s[4:5]
	v_add_co_u32_e32 v4, vcc, 0x4208000, v4
	v_mov_b32_e32 v0, v66
	v_mov_b32_e32 v1, v20
	v_mov_b32_e32 v2, v68
	v_mov_b32_e32 v3, v70
	v_addc_co_u32_e32 v5, vcc, 0, v5, vcc
	v_mov_b32_e32 v20, v67
	v_mov_b32_e32 v22, v69
	v_mov_b32_e32 v23, v71
	v_mov_b32_e32 v8, 0x100
	v_mov_b32_e32 v11, 0
	v_cndmask_b32_e64 v10, 0, v8, s[98:99]
	v_lshl_add_u64 v[4:5], v[4:5], 0, v[10:11]
	v_sub_co_u32_e32 v6, vcc, v6, v10
	s_nop 1
	v_subbrev_co_u32_e32 v7, vcc, 0, v7, vcc
	global_store_dwordx4 v[4:5], v[0:3], off
	global_store_dwordx4 v[6:7], v[20:23], off offset:256
